# stack: up tile remap + q64 V-fragment direct reads + res X-line L2 touch in last K-step + NA rpb gathers batched + NA item rotation
# speedup vs baseline: 1.0191x; 1.0074x over previous
; template <int DV, int MODE>
; DI void attn_item(const AttnArgs& a, char* smem) {
;     ...
;   for (int ks = 0; ks < 4; ++ks) qf[ks] = *(const bf8*)(qp + qcoff + ks * 16 + h * 8);
;   const u16* Ks = (MODE == 1 && (w >> 2)) ? Ks2 : Ks1;
;   int rq = 0, qc = 0, cs = 0, rsw = 0;
;   if (MODE == 2) {
;     __syncthreads();
;     for (int e = t; e < 15 * 32; e += NTHR) {
;       const int dr = e >> 5, dc = e & 31;
;       rpbS[e] = (dc < 31) ? a.rpb[dr * 31 + dc] * LOG2E : 0.f;
;     }
;     rq = a.rq0 + (w >> 1);
;     qc = (w & 1) * 32 + r;
;     cs = qc - 8; cs = cs < 0 ? 0 : (cs > 48 ? 48 : cs);
; DI void phase_attn(const Params& p, int l, char* smem) {
;     ...
;         const int id2 = id - 1024;
;         const int x = id2 & 7, q = id2 >> 3, pr = q & 7, g = (q >> 3) * 8 + x;
;         const int b = g >> 3, hd = g & 7;
;         const int r0 = 4 * pr;
;         int rs0 = r0 - 4; rs0 = rs0 < 0 ? 0 : (rs0 > 24 ? 24 : rs0);
;         int rs3 = r0 - 1; rs3 = rs3 < 0 ? 0 : (rs3 > 24 ? 24 : rs3);
;         a.qo = QO + (size_t)(b * 2048 + r0 * 64) * 1024 + hd * 64;
;         a.k1 = Kb + ((size_t)b * 16 + hd) * T * 64;
;         a.vt = VT + ((size_t)b * 1024 + hd * 64) * T;
;         a.s0 = rs0 * 64; a.n0 = rs3 + 8 - rs0; a.n1 = 4;
;         a.rpb = p.na_rpb + ((size_t)li * 8 + hd) * 15 * 31;
;         a.rq0 = r0; a.us = rs0;
;         attn_item<64, 2>(a, smem);
.LBB0_457:
	s_andn2_b64 vcc, exec, s[2:3]
	s_cbranch_vccnz .LBB0_550
	s_add_i32 s0, s39, 0xfffffc00
	s_lshr_b32 s2, s0, 6
	s_and_b32 s80, s8, 28
	s_lshr_b32 s0, s39, 5
	s_and_b32 s0, s0, 24
	s_add_i32 s80, s80, s0
	s_and_b32 s80, s80, 28
	s_lshl_b32 s0, s2, 11
	s_lshl_b32 s3, s80, 6
	s_or_b32 s0, s0, s3
	s_and_b32 s18, s39, 7
	s_lshl_b64 s[8:9], s[0:1], 11
	s_add_u32 s0, s20, s8
	s_addc_u32 s3, s21, s9
	s_lshl_b32 s8, s18, 7
	s_add_u32 s8, s0, s8
	v_mov_b32 v4, v163
	s_addc_u32 s9, s3, 0
	v_readfirstlane_b32 s16, v4
	s_ashr_i32 s17, s16, 1
	v_mov_b32_e32 v0, s17
	s_movk_i32 s0, 0xffe0
	v_bfi_b32 v2, s0, v0, v4
	v_ashrrev_i32_e32 v3, 31, v2
	v_bfe_u32 v6, v4, 5, 1
	v_lshlrev_b64 v[2:3], 11, v[2:3]
	v_lshl_add_u64 v[90:91], s[8:9], 0, v[2:3]
	v_lshlrev_b32_e32 v0, 4, v6
	v_lshl_add_u64 v[2:3], v[90:91], 0, v[0:1]
	global_load_dwordx4 v[66:69], v[2:3], off
	global_load_dwordx4 v[70:73], v[2:3], off offset:32
	global_load_dwordx4 v[74:77], v[2:3], off offset:64
	global_load_dwordx4 v[78:81], v[2:3], off offset:96
	v_med3_u32 v3, s80, 1, 25
	s_movk_i32 s0, 0x1e0
	v_readfirstlane_b32 s19, v3
	v_and_b32_e32 v2, 31, v4
	v_cmp_gt_i32_e32 vcc, s0, v4
	s_barrier
	s_and_saveexec_b64 s[8:9], vcc
	s_cbranch_execz .LBB0_463
	v_readlane_b32 s10, v234, 47
	v_readlane_b32 s11, v234, 48
	s_or_b32 s0, s10, s18
	s_mul_i32 s3, s11, 0x744
	s_mul_hi_u32 s10, s0, 0x744
	v_readlane_b32 s40, v236, 8
	s_add_i32 s3, s10, s3
	s_mulk_i32 s0, 0x744
	v_readlane_b32 s44, v236, 12
	v_readlane_b32 s45, v236, 13
	s_add_u32 s10, s44, s0
	s_addc_u32 s11, s45, s3
	v_cmp_ne_u32_e32 vcc, 31, v2
	v_lshl_add_u32 v5, v4, 2, v207
	s_mov_b64 s[12:13], 0
	v_mov_b32_e32 v7, v4
	v_readlane_b32 s41, v236, 9
	v_readlane_b32 s42, v236, 10
	v_readlane_b32 s43, v236, 11
	v_readlane_b32 s46, v236, 14
	v_readlane_b32 s47, v236, 15
	v_readlane_b32 s48, v236, 16
	v_readlane_b32 s49, v236, 17
	v_readlane_b32 s50, v236, 18
	v_readlane_b32 s51, v236, 19
	v_readlane_b32 s52, v236, 20
	v_readlane_b32 s53, v236, 21
	v_readlane_b32 s54, v236, 22
	v_readlane_b32 s55, v236, 23
	s_branch .LBB0_461

; DI f32x16 mfma32(bf8 a, bf8 b, f32x16 c) { return __builtin_amdgcn_mfma_f32_32x32x16_bf16(a, b, c, 0, 0, 0); }
; template <int DV, int MODE>
; DI void attn_item(const AttnArgs& a, char* smem) {
;     ...
;     bool active = true;
;     int kr = 0;
;     const bool local = (MODE == 2) && (tt < a.n0);
;     if (local) { kr = a.us + tt; active = (kr >= rsw) && (kr < rsw + 8); }
;     if (active) {
;       f32x16 s[2];
; #pragma unroll
;       for (int kb = 0; kb < 2; ++kb) {
; #pragma unroll
;         for (int i = 0; i < 16; ++i) s[kb][i] = 0.f;
; #pragma unroll
;         for (int ks = 0; ks < 4; ++ks) {
;           const bf8 kf = *(const bf8*)(Ks + (kb * 32 + r) * 72 + ks * 16 + h * 8);
;           s[kb] = mfma32(kf, qf[ks], s[kb]);
;         }
;       }
.LBB0_473:
	s_cmp_lt_i32 s72, s76
	s_cselect_b64 s[82:83], -1, 0
	s_cmp_ge_i32 s72, s76
	s_cselect_b64 s[10:11], -1, 0
	s_add_i32 s72, s0, s72
	v_cmp_ge_i32_e32 vcc, s72, v135
	v_cmp_lt_i32_e64 s[72:73], s72, v93
	s_and_b64 s[72:73], vcc, s[72:73]
	s_or_b64 s[10:11], s[10:11], s[72:73]
	s_andn2_b64 vcc, exec, s[10:11]
	s_cbranch_vccnz .LBB0_545
	v_add_u32_e32 v110, v0, v136
	ds_read_b128 v[34:37], v110
	ds_read_b128 v[98:101], v110 offset:32
	ds_read_b128 v[50:53], v110 offset:4608
	ds_read_b128 v[102:105], v110 offset:4640
	s_mov_b64 s[10:11], -1
	s_and_b64 vcc, exec, s[82:83]
	s_waitcnt lgkmcnt(1)
	v_mfma_f32_32x32x16_bf16 v[50:65], v[50:53], v[66:69], 0
	s_waitcnt lgkmcnt(0)
	v_mfma_f32_32x32x16_bf16 v[50:65], v[102:105], v[70:73], v[50:65]
	ds_read_b128 v[102:105], v110 offset:4672
	ds_read_b128 v[106:109], v110 offset:4704
	v_mfma_f32_32x32x16_bf16 v[34:49], v[34:37], v[66:69], 0
	s_waitcnt lgkmcnt(1)
	v_mfma_f32_32x32x16_bf16 v[50:65], v[102:105], v[74:77], v[50:65]
	v_mfma_f32_32x32x16_bf16 v[34:49], v[98:101], v[70:73], v[34:49]
	s_waitcnt lgkmcnt(0)
	v_mfma_f32_32x32x16_bf16 v[50:65], v[106:109], v[78:81], v[50:65]
	ds_read_b128 v[102:105], v110 offset:64
	ds_read_b128 v[106:109], v110 offset:96
	s_waitcnt lgkmcnt(1)
	v_mfma_f32_32x32x16_bf16 v[34:49], v[102:105], v[74:77], v[34:49]
	s_nop 7
	v_mov_b32_e32 v129, v65
	v_mov_b32_e32 v128, v64
	v_mov_b32_e32 v127, v63
	v_mov_b32_e32 v126, v62
	v_mov_b32_e32 v125, v61
	v_mov_b32_e32 v124, v60
	v_mov_b32_e32 v123, v59
	s_waitcnt lgkmcnt(0)
	v_mfma_f32_32x32x16_bf16 v[34:49], v[106:109], v[78:81], v[34:49]
	v_mov_b32_e32 v122, v58
	v_mov_b32_e32 v121, v57
	v_mov_b32_e32 v120, v56
	v_mov_b32_e32 v119, v55
	v_mov_b32_e32 v118, v54
	v_mov_b32_e32 v117, v53
	v_mov_b32_e32 v116, v52
	v_mov_b32_e32 v115, v51
	v_mov_b32_e32 v114, v50
	s_nop 2
	v_mov_b32_e32 v113, v49
	v_mov_b32_e32 v112, v48
	v_mov_b32_e32 v111, v47
	v_mov_b32_e32 v110, v46
	v_mov_b32_e32 v109, v45
	v_mov_b32_e32 v108, v44
	v_mov_b32_e32 v107, v43
	v_mov_b32_e32 v106, v42
	v_mov_b32_e32 v105, v41
	v_mov_b32_e32 v104, v40
	v_mov_b32_e32 v103, v39
	v_mov_b32_e32 v102, v38
	v_mov_b32_e32 v101, v37
	v_mov_b32_e32 v100, v36
	v_mov_b32_e32 v99, v35
	v_mov_b32_e32 v98, v34
	s_cbranch_vccz .LBB0_540
; DI int crow(int i, int h) { return (i & 3) + 8 * (i >> 2) + 4 * h; }
; template <int DV, int MODE>
; DI void attn_item(const AttnArgs& a, char* smem) {
;     ...
;       if (local) {
; #pragma unroll
;         for (int kb = 0; kb < 2; ++kb)
; #pragma unroll
;           for (int i = 0; i < 16; ++i) {
;             const int kc = kb * 32 + crow(i, h);
;             const bool ok = (kc >= cs) && (kc < cs + 16);
;             const int dc = kc - qc + 15;
;             const int dr = kr - rq + 7;
;             const float bias = rpbS[dr * 32 + (ok ? dc : 0)];
;             const float v = ok ? (s[kb][i] + bias * (1.f / SC)) : -INFINITY;
;             s[kb][i] = v;
;             mx = fmaxf(mx, v);
;           }
	v_mov_b32_e32 v253, 0xff800000
	ds_read_b32 v237, v138
	ds_read_b32 v238, v138 offset:4
	ds_read_b32 v239, v138 offset:8
	ds_read_b32 v240, v138 offset:12
	ds_read_b32 v241, v138 offset:32
	ds_read_b32 v242, v138 offset:36
	ds_read_b32 v243, v138 offset:40
	ds_read_b32 v244, v138 offset:44
	ds_read_b32 v245, v138 offset:64
	ds_read_b32 v246, v138 offset:68
	ds_read_b32 v247, v138 offset:72
	ds_read_b32 v248, v138 offset:76
	ds_read_b32 v249, v138 offset:96
	ds_read_b32 v250, v138 offset:100
	ds_read_b32 v251, v138 offset:104
	ds_read_b32 v252, v138 offset:108
	s_waitcnt lgkmcnt(15)
	v_fmamk_f32 v237, v237, 0x40b17218, v34
	v_cndmask_b32_e64 v98, v253, v237, s[36:37]
	s_waitcnt lgkmcnt(14)
	v_fmamk_f32 v238, v238, 0x40b17218, v35
	v_cndmask_b32_e64 v99, v253, v238, s[40:41]
	s_waitcnt lgkmcnt(13)
	v_fmamk_f32 v239, v239, 0x40b17218, v36
	v_cndmask_b32_e64 v100, v253, v239, s[42:43]
	s_waitcnt lgkmcnt(12)
	v_fmamk_f32 v240, v240, 0x40b17218, v37
	v_cndmask_b32_e64 v101, v253, v240, s[44:45]
	s_waitcnt lgkmcnt(11)
	v_fmamk_f32 v241, v241, 0x40b17218, v38
	v_cndmask_b32_e64 v102, v253, v241, s[46:47]
	s_waitcnt lgkmcnt(10)
	v_fmamk_f32 v242, v242, 0x40b17218, v39
	v_cndmask_b32_e64 v103, v253, v242, s[48:49]
	s_waitcnt lgkmcnt(9)
	v_fmamk_f32 v243, v243, 0x40b17218, v40
	v_cndmask_b32_e64 v104, v253, v243, s[50:51]
	s_waitcnt lgkmcnt(8)
	v_fmamk_f32 v244, v244, 0x40b17218, v41
	v_cndmask_b32_e64 v105, v253, v244, s[52:53]
	s_waitcnt lgkmcnt(7)
	v_fmamk_f32 v245, v245, 0x40b17218, v42
	v_cndmask_b32_e64 v106, v253, v245, s[12:13]
	s_waitcnt lgkmcnt(6)
	v_fmamk_f32 v246, v246, 0x40b17218, v43
	v_cndmask_b32_e64 v107, v253, v246, s[16:17]
	s_waitcnt lgkmcnt(5)
	v_fmamk_f32 v247, v247, 0x40b17218, v44
	v_cndmask_b32_e64 v108, v253, v247, s[18:19]
	s_waitcnt lgkmcnt(4)
	v_fmamk_f32 v248, v248, 0x40b17218, v45
	v_cndmask_b32_e64 v109, v253, v248, s[86:87]
	s_waitcnt lgkmcnt(3)
	v_fmamk_f32 v249, v249, 0x40b17218, v46
	v_cndmask_b32_e64 v110, v253, v249, s[78:79]
	s_waitcnt lgkmcnt(2)
	v_fmamk_f32 v250, v250, 0x40b17218, v47
	v_cndmask_b32_e64 v111, v253, v250, s[96:97]
	s_waitcnt lgkmcnt(1)
	v_fmamk_f32 v251, v251, 0x40b17218, v48
	v_cndmask_b32_e64 v112, v253, v251, s[92:93]
	s_waitcnt lgkmcnt(0)
	v_fmamk_f32 v252, v252, 0x40b17218, v49
	v_cndmask_b32_e64 v113, v253, v252, s[94:95]
	ds_read_b32 v237, v138 offset:128
	ds_read_b32 v238, v138 offset:132
	ds_read_b32 v239, v138 offset:136
	ds_read_b32 v240, v138 offset:140
	ds_read_b32 v241, v138 offset:160
	ds_read_b32 v242, v138 offset:164
	ds_read_b32 v243, v138 offset:168
	ds_read_b32 v244, v138 offset:172
	ds_read_b32 v245, v138 offset:192
	ds_read_b32 v246, v138 offset:196
	ds_read_b32 v247, v138 offset:200
	ds_read_b32 v248, v138 offset:204
	ds_read_b32 v249, v138 offset:224
	ds_read_b32 v250, v138 offset:228
	ds_read_b32 v251, v138 offset:232
	ds_read_b32 v252, v138 offset:236
	s_waitcnt lgkmcnt(15)
	v_fmamk_f32 v237, v237, 0x40b17218, v50
	v_cndmask_b32_e64 v114, v253, v237, s[22:23]
	s_waitcnt lgkmcnt(14)
	v_fmamk_f32 v238, v238, 0x40b17218, v51
	v_cndmask_b32_e64 v115, v253, v238, s[26:27]
	s_waitcnt lgkmcnt(13)
	v_fmamk_f32 v239, v239, 0x40b17218, v52
	v_cndmask_b32_e64 v116, v253, v239, s[2:3]
	s_waitcnt lgkmcnt(12)
	v_fmamk_f32 v240, v240, 0x40b17218, v53
	v_cndmask_b32_e64 v117, v253, v240, s[28:29]
	s_waitcnt lgkmcnt(11)
	v_fmamk_f32 v241, v241, 0x40b17218, v54
	v_cndmask_b32_e64 v118, v253, v241, s[74:75]
	s_waitcnt lgkmcnt(10)
	v_fmamk_f32 v242, v242, 0x40b17218, v55
	v_cndmask_b32_e64 v119, v253, v242, s[14:15]
	s_waitcnt lgkmcnt(9)
	v_fmamk_f32 v243, v243, 0x40b17218, v56
	v_cndmask_b32_e64 v120, v253, v243, s[70:71]
	s_waitcnt lgkmcnt(8)
	v_fmamk_f32 v244, v244, 0x40b17218, v57
	v_cndmask_b32_e64 v121, v253, v244, s[8:9]
	s_waitcnt lgkmcnt(7)
	v_fmamk_f32 v245, v245, 0x40b17218, v58
	v_cndmask_b32_e64 v122, v253, v245, s[54:55]
	s_waitcnt lgkmcnt(6)
	v_fmamk_f32 v246, v246, 0x40b17218, v59
	v_cndmask_b32_e64 v123, v253, v246, s[56:57]
	s_waitcnt lgkmcnt(5)
	v_fmamk_f32 v247, v247, 0x40b17218, v60
	v_cndmask_b32_e64 v124, v253, v247, s[58:59]
	s_waitcnt lgkmcnt(4)
	v_fmamk_f32 v248, v248, 0x40b17218, v61
	v_cndmask_b32_e64 v125, v253, v248, s[60:61]
	s_waitcnt lgkmcnt(3)
	v_fmamk_f32 v249, v249, 0x40b17218, v62
	v_cndmask_b32_e64 v126, v253, v249, s[62:63]
	s_waitcnt lgkmcnt(2)
	v_fmamk_f32 v250, v250, 0x40b17218, v63
	v_cndmask_b32_e64 v127, v253, v250, s[64:65]
	s_waitcnt lgkmcnt(1)
	v_fmamk_f32 v251, v251, 0x40b17218, v64
	v_cndmask_b32_e64 v128, v253, v251, s[66:67]
	s_waitcnt lgkmcnt(0)
	v_fmamk_f32 v252, v252, 0x40b17218, v65
	v_cndmask_b32_e64 v129, v253, v252, s[68:69]
	v_max3_f32 v141, v98, s33, v99
	v_max3_f32 v141, v141, v100, v101
	v_max3_f32 v141, v141, v102, v103
	v_max3_f32 v141, v141, v104, v105
	v_max3_f32 v141, v141, v106, v107
	v_max3_f32 v141, v141, v108, v109
	v_max3_f32 v141, v141, v110, v111
	v_max3_f32 v141, v141, v112, v113
	v_max3_f32 v141, v141, v114, v115
	v_max3_f32 v141, v141, v116, v117
	v_max3_f32 v141, v141, v118, v119
	v_max3_f32 v141, v141, v120, v121
	v_max3_f32 v141, v141, v122, v123
	v_max3_f32 v141, v141, v124, v125
	v_max3_f32 v141, v141, v126, v127
	v_max3_f32 v141, v141, v128, v129
	s_mov_b64 s[10:11], 0

; template <int MB, class Epi>
; DI void gemm_tile(const u16* __restrict__ A, int lda, int row0, int Mrows, const u16* __restrict__ Bt, int ldb, int K, char* smem, Epi& epi, int rot) {
;     ...
;   for (int kt = 0; kt < KT; ++kt) {
;     const bool more = (kt + 1 < KT);
;     const bool more2 = (kt + 2 < KT);
;     const int nstg = (kt + 1) & 1;
;     const char* as = As + (kt & 1) * 32768 + wm * (32 * MB) * 128;
;     const char* bs = Bs + (kt & 1) * 32768 + wn * 64 * 128;
;     int k1_ = kbase + kt + 1; if (k1_ >= KT) k1_ -= KT;
;     int k2_ = kbase + kt + 2; if (k2_ >= KT) k2_ -= KT; if (k2_ >= KT) k2_ -= KT;
; #pragma unroll
;     for (int ks = 0; ks < 3; ++ks) {
; #pragma unroll
;       for (int idx = 0; idx < 2 * MB; ++idx) {
;         const int nb = idx / MB, mb = idx % MB;
;         acc[nb][mb] = mfma32(bfr[ks & 1][nb], af[ks & 1][mb], acc[nb][mb]);
;         if (idx < MB) af[(ks + 1) & 1][idx] = *(const bf8*)(as + idx * 32 * 128 + foff[ks + 1]);
;         else if (idx < MB + 2) bfr[(ks + 1) & 1][idx - MB] = *(const bf8*)(bs + (idx - MB) * 32 * 128 + foff[ks + 1]);
;         if (more && ks < 2 && idx < 3) {
;           const int ko_ = k1_ * 64;
;           GEMM_PIECE(nstg, 3 + ks * 3 + idx)
;         }
;         __builtin_amdgcn_sched_barrier(0);
;       }
;     }
;     if (more) {
;       asm volatile("s_waitcnt vmcnt(0)" ::: "memory");
;       __syncthreads();
;       if (more2) {
;         const int ko_ = k2_ * 64;
; #pragma unroll
;         for (int pc = 0; pc < 3; ++pc) GEMM_PIECE(kt & 1, pc)
;       }
;       __builtin_amdgcn_sched_barrier(0);
;       const char* asn = As + nstg * 32768 + wm * (32 * MB) * 128;
;       const char* bsn = Bs + nstg * 32768 + wn * 64 * 128;
; #pragma unroll
;       for (int mb = 0; mb < MB; ++mb) af[0][mb] = *(const bf8*)(asn + mb * 32 * 128 + foff[0]);
; #pragma unroll
;       for (int nb = 0; nb < 2; ++nb) bfr[0][nb] = *(const bf8*)(bsn + nb * 32 * 128 + foff[0]);
;     }
; #pragma unroll
;     for (int nb = 0; nb < 2; ++nb)
; #pragma unroll
;       for (int mb = 0; mb < MB; ++mb) acc[nb][mb] = mfma32(bfr[1][nb], af[1][mb], acc[nb][mb]);
; #pragma unroll
;     for (int gk = 0; gk < 2 * MB; ++gk) {
;       __builtin_amdgcn_sched_group_barrier(0x008, 1, 0);
;       __builtin_amdgcn_sched_group_barrier(0x100, 1, 0);
;     }
;     __builtin_amdgcn_sched_barrier(0);
;   }
.LBB0_649:
	s_and_b32 s23, s15, 0x8000
	s_add_i32 s19, s22, 1
	s_add_i32 s28, s13, s23
	s_add_i32 s25, s12, s23
	s_add_i32 s22, s16, s22
	s_cmp_lt_i32 s22, 15
	s_cselect_b32 s18, 0, -16
	s_waitcnt lgkmcnt(1)
	v_mfma_f32_32x32x16_bf16 v[66:81], v[114:117], v[110:113], v[66:81]
	s_add_i32 s18, s22, s18
	s_lshl_b32 s18, s18, 6
	s_add_i32 s26, s18, 64
	s_add_i32 s15, s15, 0x8000
	v_add_u32_e32 v144, s28, v129
	s_ashr_i32 s27, s26, 31
	s_and_b32 s18, s15, 0x8000
	ds_read_b128 v[132:135], v144
	v_lshl_add_u64 v[140:141], s[26:27], 1, v[120:121]
	s_add_i32 s26, s18, s17
	s_mov_b32 m0, s26
	s_nop 0
	global_load_lds_dwordx4 v[140:141], off
	v_mfma_f32_32x32x16_bf16 v[34:49], v[114:117], v[106:109], v[34:49]
	ds_read_b128 v[136:139], v144 offset:4096
	v_lshl_add_u64 v[142:143], v[140:141], 0, s[4:5]
	s_add_i32 s27, s26, 0x2000
	s_mov_b32 m0, s27
	s_nop 0
	global_load_lds_dwordx4 v[142:143], off
	v_mfma_f32_32x32x16_bf16 v[2:17], v[114:117], v[98:101], v[2:17]
	ds_read_b128 v[114:117], v144 offset:8192
	v_lshl_add_u64 v[142:143], v[140:141], 0, s[6:7]
	s_add_i32 s27, s26, 0x4000
	s_mov_b32 m0, s27
	s_nop 0
	global_load_lds_dwordx4 v[142:143], off
	s_waitcnt lgkmcnt(3)
	v_mfma_f32_32x32x16_bf16 v[82:97], v[102:105], v[110:113], v[82:97]
	v_add_u32_e32 v142, s25, v129
	ds_read_b128 v[110:113], v142
	v_mfma_f32_32x32x16_bf16 v[50:65], v[102:105], v[106:109], v[50:65]
	ds_read_b128 v[106:109], v142 offset:4096
	v_mfma_f32_32x32x16_bf16 v[18:33], v[102:105], v[98:101], v[18:33]
	s_waitcnt lgkmcnt(1)
	v_mfma_f32_32x32x16_bf16 v[66:81], v[110:113], v[132:135], v[66:81]
	v_add_u32_e32 v142, s28, v128
	ds_read_b128 v[98:101], v142
	v_lshl_add_u64 v[102:103], v[140:141], 0, s[34:35]
	s_addk_i32 s26, 0x6000
	s_mov_b32 m0, s26
	s_nop 0
	global_load_lds_dwordx4 v[102:103], off
	v_mfma_f32_32x32x16_bf16 v[34:49], v[110:113], v[136:139], v[34:49]
	ds_read_b128 v[102:105], v142 offset:4096
	v_mfma_f32_32x32x16_bf16 v[2:17], v[110:113], v[114:117], v[2:17]
	ds_read_b128 v[110:113], v142 offset:8192
	s_waitcnt lgkmcnt(3)
	v_mfma_f32_32x32x16_bf16 v[82:97], v[106:109], v[132:135], v[82:97]
	v_add_u32_e32 v140, s25, v128
	ds_read_b128 v[132:135], v140
	v_mfma_f32_32x32x16_bf16 v[50:65], v[106:109], v[136:139], v[50:65]
	ds_read_b128 v[136:139], v140 offset:4096
	v_mfma_f32_32x32x16_bf16 v[18:33], v[106:109], v[114:117], v[18:33]
	s_waitcnt lgkmcnt(1)
	v_mfma_f32_32x32x16_bf16 v[66:81], v[132:135], v[98:101], v[66:81]
	v_add_u32_e32 v106, s28, v127
	ds_read_b128 v[114:117], v106
	v_mfma_f32_32x32x16_bf16 v[34:49], v[132:135], v[102:105], v[34:49]
	ds_read_b128 v[140:143], v106 offset:4096
	v_mfma_f32_32x32x16_bf16 v[2:17], v[132:135], v[110:113], v[2:17]
	ds_read_b128 v[132:135], v106 offset:8192
	s_waitcnt lgkmcnt(3)
	v_mfma_f32_32x32x16_bf16 v[82:97], v[136:139], v[98:101], v[82:97]
	v_add_u32_e32 v106, s25, v127
	ds_read_b128 v[98:101], v106
	v_mfma_f32_32x32x16_bf16 v[50:65], v[136:139], v[102:105], v[50:65]
	ds_read_b128 v[144:147], v106 offset:4096
	v_mfma_f32_32x32x16_bf16 v[18:33], v[136:139], v[110:113], v[18:33]
	s_cmp_lt_i32 s22, 14
	s_cselect_b32 s25, 0, -16
	s_add_i32 s26, s22, s25
	s_add_i32 s26, s26, 2
	s_cmp_lt_i32 s26, 16
	s_cselect_b32 s26, 0, -16
	s_add_i32 s25, s25, s26
	s_add_i32 s22, s22, s25
	s_lshl_b32 s22, s22, 6
	s_add_i32 s26, s22, 0x80
	s_ashr_i32 s27, s26, 31
	s_lshl_b64 s[26:27], s[26:27], 1
	s_add_u32 s26, s20, s26
	s_addc_u32 s27, s21, s27
	s_waitcnt vmcnt(0)
	s_waitcnt lgkmcnt(0)
	s_barrier
	s_add_i32 s22, s23, s14
	v_lshl_add_u64 v[102:103], s[26:27], 0, v[0:1]
	s_mov_b32 m0, s22
	s_nop 0
	global_load_lds_dwordx4 v[102:103], off
	v_lshl_add_u64 v[102:103], v[118:119], 1, s[26:27]
	s_add_i32 s23, s22, 0x2000
	s_mov_b32 m0, s23
	s_nop 0
	global_load_lds_dwordx4 v[102:103], off
	v_lshl_add_u64 v[102:103], v[122:123], 1, s[26:27]
	s_addk_i32 s22, 0x4000
	s_mov_b32 m0, s22
	s_nop 0
	global_load_lds_dwordx4 v[102:103], off
	v_add_u32_e32 v102, s18, v131
	v_mfma_f32_32x32x16_bf16 v[66:81], v[98:101], v[114:117], v[66:81]
	ds_read_b128 v[110:113], v102
	v_mfma_f32_32x32x16_bf16 v[34:49], v[98:101], v[140:143], v[34:49]
	ds_read_b128 v[106:109], v102 offset:4096
	v_mfma_f32_32x32x16_bf16 v[2:17], v[98:101], v[132:135], v[2:17]
	ds_read_b128 v[98:101], v102 offset:8192
	v_add_u32_e32 v102, s18, v130
	v_mfma_f32_32x32x16_bf16 v[82:97], v[144:147], v[114:117], v[82:97]
	ds_read_b128 v[114:117], v102
	v_mfma_f32_32x32x16_bf16 v[50:65], v[144:147], v[140:143], v[50:65]
	ds_read_b128 v[102:105], v102 offset:4096
	v_mfma_f32_32x32x16_bf16 v[18:33], v[144:147], v[132:135], v[18:33]
	s_cmp_eq_u32 s19, 14
	s_mov_b32 s22, s19
	s_cbranch_scc0 .LBB0_649
; DI f32x16 mfma32(bf8 a, bf8 b, f32x16 c) { return __builtin_amdgcn_mfma_f32_32x32x16_bf16(a, b, c, 0, 0, 0); }
; template <int MB, class Epi>
; DI void gemm_tile(const u16* __restrict__ A, int lda, int row0, int Mrows, const u16* __restrict__ Bt, int ldb, int K, char* smem, Epi& epi, int rot) {
;     ...
;   for (int kt = 0; kt < KT; ++kt) {
;     const bool more = (kt + 1 < KT);
;     const bool more2 = (kt + 2 < KT);
;     const int nstg = (kt + 1) & 1;
;     const char* as = As + (kt & 1) * 32768 + wm * (32 * MB) * 128;
;     const char* bs = Bs + (kt & 1) * 32768 + wn * 64 * 128;
;     int k1_ = kbase + kt + 1; if (k1_ >= KT) k1_ -= KT;
;     int k2_ = kbase + kt + 2; if (k2_ >= KT) k2_ -= KT; if (k2_ >= KT) k2_ -= KT;
; #pragma unroll
;     for (int ks = 0; ks < 3; ++ks) {
; #pragma unroll
;       for (int idx = 0; idx < 2 * MB; ++idx) {
;         const int nb = idx / MB, mb = idx % MB;
;         acc[nb][mb] = mfma32(bfr[ks & 1][nb], af[ks & 1][mb], acc[nb][mb]);
;         if (idx < MB) af[(ks + 1) & 1][idx] = *(const bf8*)(as + idx * 32 * 128 + foff[ks + 1]);
;         else if (idx < MB + 2) bfr[(ks + 1) & 1][idx - MB] = *(const bf8*)(bs + (idx - MB) * 32 * 128 + foff[ks + 1]);
;         if (more && ks < 2 && idx < 3) {
;           const int ko_ = k1_ * 64;
;           GEMM_PIECE(nstg, 3 + ks * 3 + idx)
;         }
;         __builtin_amdgcn_sched_barrier(0);
;       }
;     }
;     if (more) {
;       asm volatile("s_waitcnt vmcnt(0)" ::: "memory");
;       __syncthreads();
;       if (more2) {
;         const int ko_ = k2_ * 64;
; #pragma unroll
;         for (int pc = 0; pc < 3; ++pc) GEMM_PIECE(kt & 1, pc)
;       }
;       __builtin_amdgcn_sched_barrier(0);
;       const char* asn = As + nstg * 32768 + wm * (32 * MB) * 128;
;       const char* bsn = Bs + nstg * 32768 + wn * 64 * 128;
; #pragma unroll
;       for (int mb = 0; mb < MB; ++mb) af[0][mb] = *(const bf8*)(asn + mb * 32 * 128 + foff[0]);
; #pragma unroll
;       for (int nb = 0; nb < 2; ++nb) bfr[0][nb] = *(const bf8*)(bsn + nb * 32 * 128 + foff[0]);
;     }
; #pragma unroll
;     for (int nb = 0; nb < 2; ++nb)
; #pragma unroll
;       for (int mb = 0; mb < MB; ++mb) acc[nb][mb] = mfma32(bfr[1][nb], af[1][mb], acc[nb][mb]);
	s_add_i32 s15, s13, s18
	s_add_i32 s18, s12, s18
	s_add_i32 s16, s16, 14
	s_cmp_lt_i32 s16, 15
	s_cselect_b32 s17, 0, -16
	s_add_i32 s16, s16, s17
	s_lshl_b32 s16, s16, 6
	s_add_i32 s16, s16, 64
	s_ashr_i32 s17, s16, 31
	v_add_u32_e32 v0, s15, v129
	v_lshl_add_u64 v[122:123], s[16:17], 1, v[120:121]
	ds_read_b128 v[118:121], v0
	s_add_i32 s16, s14, 0x18000
	s_mov_b32 m0, s16
	s_nop 0
	global_load_lds_dwordx4 v[122:123], off
	s_waitcnt lgkmcnt(2)
	v_mfma_f32_32x32x16_bf16 v[66:81], v[114:117], v[110:113], v[66:81]
	ds_read_b128 v[132:135], v0 offset:4096
	v_lshl_add_u64 v[136:137], v[122:123], 0, s[4:5]
	s_add_i32 s16, s14, 0x1a000
	s_mov_b32 m0, s16
	s_nop 0
	global_load_lds_dwordx4 v[136:137], off
	v_mfma_f32_32x32x16_bf16 v[34:49], v[114:117], v[106:109], v[34:49]
	v_mfma_f32_32x32x16_bf16 v[2:17], v[114:117], v[98:101], v[2:17]
	ds_read_b128 v[114:117], v0 offset:8192
	v_lshl_add_u64 v[136:137], v[122:123], 0, s[6:7]
	s_add_i32 s16, s14, 0x1c000
	s_mov_b32 m0, s16
	s_nop 0
	global_load_lds_dwordx4 v[136:137], off
	v_add_u32_e32 v0, s18, v129
	s_waitcnt lgkmcnt(3)
	v_mfma_f32_32x32x16_bf16 v[82:97], v[102:105], v[110:113], v[82:97]
	ds_read_b128 v[110:113], v0
	v_mfma_f32_32x32x16_bf16 v[50:65], v[102:105], v[106:109], v[50:65]
	ds_read_b128 v[106:109], v0 offset:4096
	v_mfma_f32_32x32x16_bf16 v[18:33], v[102:105], v[98:101], v[18:33]
	v_add_u32_e32 v0, s15, v128
	ds_read_b128 v[98:101], v0
	v_lshl_add_u64 v[102:103], v[122:123], 0, s[34:35]
	s_add_i32 s14, s14, 0x1e000
	s_mov_b32 m0, s14
	s_nop 0
	global_load_lds_dwordx4 v[102:103], off
	s_waitcnt lgkmcnt(2)
	v_mfma_f32_32x32x16_bf16 v[66:81], v[110:113], v[118:121], v[66:81]
	ds_read_b128 v[102:105], v0 offset:4096
	v_mfma_f32_32x32x16_bf16 v[34:49], v[110:113], v[132:135], v[34:49]
	v_mfma_f32_32x32x16_bf16 v[2:17], v[110:113], v[114:117], v[2:17]
	ds_read_b128 v[110:113], v0 offset:8192
	v_add_u32_e32 v0, s18, v128
	s_waitcnt lgkmcnt(3)
	v_mfma_f32_32x32x16_bf16 v[82:97], v[106:109], v[118:121], v[82:97]
	ds_read_b128 v[118:121], v0
	v_mfma_f32_32x32x16_bf16 v[50:65], v[106:109], v[132:135], v[50:65]
	ds_read_b128 v[132:135], v0 offset:4096
	v_mfma_f32_32x32x16_bf16 v[18:33], v[106:109], v[114:117], v[18:33]
	v_add_u32_e32 v0, s15, v127
	ds_read_b128 v[106:109], v0
	s_waitcnt lgkmcnt(2)
	v_mfma_f32_32x32x16_bf16 v[66:81], v[118:121], v[98:101], v[66:81]
	ds_read_b128 v[114:117], v0 offset:4096
	v_mfma_f32_32x32x16_bf16 v[34:49], v[118:121], v[102:105], v[34:49]
	v_mfma_f32_32x32x16_bf16 v[2:17], v[118:121], v[110:113], v[2:17]
	ds_read_b128 v[118:121], v0 offset:8192
	v_add_u32_e32 v0, s18, v127
	s_waitcnt lgkmcnt(3)
	v_mfma_f32_32x32x16_bf16 v[82:97], v[132:135], v[98:101], v[82:97]
	ds_read_b128 v[98:101], v0
	v_mfma_f32_32x32x16_bf16 v[50:65], v[132:135], v[102:105], v[50:65]
	ds_read_b128 v[102:105], v0 offset:4096
	v_mfma_f32_32x32x16_bf16 v[18:33], v[132:135], v[110:113], v[18:33]
	s_waitcnt vmcnt(0)
	s_waitcnt lgkmcnt(0)
	s_barrier
	s_lshr_b32 s100, s0, 5
	s_lshl_b32 s100, s100, 3
	s_and_b32 s101, s0, 7
	s_or_b32 s100, s100, s101
	s_mul_i32 s100, s100, 0xc0
	s_lshr_b32 s101, s0, 3
	s_and_b32 s101, s101, 3
	s_lshl_b32 s101, s101, 9
	v_lshrrev_b32_e32 v237, 2, v163
	v_and_b32_e32 v238, 3, v163
	v_add_u32_e32 v237, s100, v237
	v_lshlrev_b32_e32 v237, 11, v237
	v_lshl_add_u32 v237, v238, 7, v237
	v_add_u32_e32 v237, s101, v237
	global_load_dword v239, v237, s[46:47]
	v_add_u32_e32 v237, 0x40000, v237
	global_load_dword v239, v237, s[46:47]
	v_mfma_f32_32x32x16_bf16 v[66:81], v[98:101], v[106:109], v[66:81]
	ds_read_b128 v[110:113], v131 offset:32768
	v_mfma_f32_32x32x16_bf16 v[34:49], v[98:101], v[114:117], v[34:49]
	ds_read_b128 v[132:135], v131 offset:36864
	v_mfma_f32_32x32x16_bf16 v[2:17], v[98:101], v[118:121], v[2:17]
	ds_read_b128 v[98:101], v131 offset:40960
	v_mfma_f32_32x32x16_bf16 v[82:97], v[102:105], v[106:109], v[82:97]
	ds_read_b128 v[106:109], v130 offset:32768
	v_mfma_f32_32x32x16_bf16 v[50:65], v[102:105], v[114:117], v[50:65]
	ds_read_b128 v[114:117], v130 offset:36864
	v_mfma_f32_32x32x16_bf16 v[18:33], v[102:105], v[118:121], v[18:33]
	v_add_u32_e32 v0, s13, v129
	ds_read_b128 v[102:105], v0 offset:32768
	s_lshl_b32 s14, s2, 8
	s_waitcnt lgkmcnt(2)
	v_mfma_f32_32x32x16_bf16 v[66:81], v[106:109], v[110:113], v[66:81]
	ds_read_b128 v[118:121], v0 offset:36864
	v_mfma_f32_32x32x16_bf16 v[34:49], v[106:109], v[132:135], v[34:49]
	v_mfma_f32_32x32x16_bf16 v[2:17], v[106:109], v[98:101], v[2:17]
	ds_read_b128 v[106:109], v0 offset:40960
	v_add_u32_e32 v0, s12, v129
	s_waitcnt lgkmcnt(3)
	v_mfma_f32_32x32x16_bf16 v[82:97], v[114:117], v[110:113], v[82:97]
	ds_read_b128 v[110:113], v0 offset:32768
	v_mfma_f32_32x32x16_bf16 v[50:65], v[114:117], v[132:135], v[50:65]
	ds_read_b128 v[130:133], v0 offset:36864
	v_mfma_f32_32x32x16_bf16 v[18:33], v[114:117], v[98:101], v[18:33]
	v_add_u32_e32 v0, s13, v128
	ds_read_b128 v[98:101], v0 offset:32768
	s_waitcnt lgkmcnt(2)
	v_mfma_f32_32x32x16_bf16 v[66:81], v[110:113], v[102:105], v[66:81]
	ds_read_b128 v[114:117], v0 offset:36864
	v_mfma_f32_32x32x16_bf16 v[34:49], v[110:113], v[118:121], v[34:49]
	v_mfma_f32_32x32x16_bf16 v[2:17], v[110:113], v[106:109], v[2:17]
	ds_read_b128 v[110:113], v0 offset:40960
	v_add_u32_e32 v0, s12, v128
	s_waitcnt lgkmcnt(3)
	v_mfma_f32_32x32x16_bf16 v[82:97], v[130:133], v[102:105], v[82:97]
	ds_read_b128 v[102:105], v0 offset:32768
	v_mfma_f32_32x32x16_bf16 v[50:65], v[130:133], v[118:121], v[50:65]
	ds_read_b128 v[118:121], v0 offset:36864
	v_mfma_f32_32x32x16_bf16 v[18:33], v[130:133], v[106:109], v[18:33]
	v_add_u32_e32 v0, s13, v127
	ds_read_b128 v[106:109], v0 offset:32768
	s_waitcnt lgkmcnt(2)
; DI f32x16 mfma32(bf8 a, bf8 b, f32x16 c) { return __builtin_amdgcn_mfma_f32_32x32x16_bf16(a, b, c, 0, 0, 0); }
; template <int MB, class Epi>
; DI void gemm_tile(const u16* __restrict__ A, int lda, int row0, int Mrows, const u16* __restrict__ Bt, int ldb, int K, char* smem, Epi& epi, int rot) {
;     ...
; #pragma unroll
;     for (int nb = 0; nb < 2; ++nb)
; #pragma unroll
;       for (int mb = 0; mb < MB; ++mb) acc[nb][mb] = mfma32(bfr[1][nb], af[1][mb], acc[nb][mb]);
; #pragma unroll
;     for (int gk = 0; gk < 2 * MB; ++gk) {
;       __builtin_amdgcn_sched_group_barrier(0x008, 1, 0);
;       __builtin_amdgcn_sched_group_barrier(0x100, 1, 0);
;     }
;     __builtin_amdgcn_sched_barrier(0);
;   }
;   __syncthreads();
;   epi(acc, wm, wn, r, h);
; }
;   DI void operator()(f32x16 (&acc)[2][MB], int wm, int wn, int r, int h) {
;     u16* slab = ostage + (wm * 4 + wn) * (64 * 72);
;     const int lane = h * 32 + r;
; #pragma unroll
;     for (int mb = 0; mb < MB; ++mb) {
;       const int tokl = (mb & 1) * 32 + r;
; #pragma unroll
;       for (int nb = 0; nb < 2; ++nb)
; #pragma unroll
;         for (int ig = 0; ig < 4; ++ig) {
;           u32x2 o;
;           o.x = pack2(acc[nb][mb][ig * 4 + 0], acc[nb][mb][ig * 4 + 1]);
;           o.y = pack2(acc[nb][mb][ig * 4 + 2], acc[nb][mb][ig * 4 + 3]);
;           *(u32x2*)(slab + tokl * 72 + nb * 32 + ig * 8 + h * 4) = o;
;         }
;       if ((mb & 1) || mb == MB - 1) {
;         asm volatile("s_waitcnt lgkmcnt(0)" ::: "memory");
;         const int ntok = (mb & 1) ? 64 : 32;
;         const int R0 = row0 + wm * (32 * MB) + (mb >> 1) * 64;
; #pragma unroll
;         for (int j = 0; j < 8; ++j) {
;           const int rowl = (lane >> 3) + 8 * j, ch = lane & 7;
;           if (rowl < ntok) {
;             const u32x4 yv = *(const u32x4*)(slab + rowl * 72 + ch * 8);
;             const int R = R0 + rowl;
;             const int mi = (R < NLAT) ? (R >> 11) : 16;
;             const int col = n0 + wn * 64 + ch * 8;
;             const float* g = gate + (size_t)mi * 6144 + col;
;             const f32x4n g0 = *(const f32x4n*)(g), g1 = *(const f32x4n*)(g + 4);
;             _Float16* xp = X + (size_t)R * 1024 + col;
;             const h8 xv = *(const h8*)xp;
;             const float y[8] = {__uint_as_float(yv.x << 16), __uint_as_float(yv.x & 0xffff0000u), __uint_as_float(yv.y << 16), __uint_as_float(yv.y & 0xffff0000u),
	v_mfma_f32_32x32x16_bf16 v[66:81], v[102:105], v[98:101], v[66:81]
	ds_read_b128 v[128:131], v0 offset:36864
	v_mfma_f32_32x32x16_bf16 v[34:49], v[102:105], v[114:117], v[34:49]
	v_mfma_f32_32x32x16_bf16 v[2:17], v[102:105], v[110:113], v[2:17]
	ds_read_b128 v[102:105], v0 offset:40960
	v_add_u32_e32 v0, s12, v127
	s_waitcnt lgkmcnt(3)
	v_mfma_f32_32x32x16_bf16 v[82:97], v[118:121], v[98:101], v[82:97]
	ds_read_b128 v[98:101], v0 offset:32768
	v_mfma_f32_32x32x16_bf16 v[50:65], v[118:121], v[114:117], v[50:65]
	ds_read_b128 v[114:117], v0 offset:36864
	v_mfma_f32_32x32x16_bf16 v[18:33], v[118:121], v[110:113], v[18:33]
	s_waitcnt lgkmcnt(1)
	v_mfma_f32_32x32x16_bf16 v[66:81], v[98:101], v[106:109], v[66:81]
	v_mfma_f32_32x32x16_bf16 v[34:49], v[98:101], v[128:131], v[34:49]
	v_mfma_f32_32x32x16_bf16 v[2:17], v[98:101], v[102:105], v[2:17]
	s_waitcnt lgkmcnt(0)
	v_mfma_f32_32x32x16_bf16 v[82:97], v[114:117], v[106:109], v[82:97]
	v_mfma_f32_32x32x16_bf16 v[50:65], v[114:117], v[128:131], v[50:65]
	v_mfma_f32_32x32x16_bf16 v[18:33], v[114:117], v[102:105], v[18:33]
	s_lshl_b32 s2, s11, 2
	s_or_b32 s2, s2, s3
	s_mul_i32 s12, s2, 0x2400
	v_lshl_or_b32 v0, v126, 3, s12
	v_lshlrev_b32_e32 v98, 3, v125
	v_and_b32_e32 v100, 56, v98
	v_mad_u32_u24 v98, v125, s78, v0
	v_cvt_pk_bf16_f32 v34, v34, v35
	v_cvt_pk_bf16_f32 v35, v36, v37
	v_cvt_pk_bf16_f32 v36, v38, v39
	v_cvt_pk_bf16_f32 v37, v40, v41
	v_add_u32_e32 v0, 0x1000, v98
	s_barrier
	ds_write2_b64 v0, v[34:35], v[36:37] offset0:64 offset1:66
	v_cvt_pk_bf16_f32 v34, v42, v43
	v_cvt_pk_bf16_f32 v35, v44, v45
	v_cvt_pk_bf16_f32 v36, v46, v47
	v_cvt_pk_bf16_f32 v37, v48, v49
	s_mul_i32 s2, s11, 0x60
	ds_write2_b64 v0, v[34:35], v[36:37] offset0:68 offset1:70
	v_cvt_pk_bf16_f32 v34, v50, v51
	v_cvt_pk_bf16_f32 v35, v52, v53
	v_cvt_pk_bf16_f32 v36, v54, v55
	v_cvt_pk_bf16_f32 v37, v56, v57
	v_bfe_u32 v99, v124, 3, 3
	s_lshl_b32 s3, s3, 6
	v_cvt_pk_bf16_f32 v66, v66, v67
	v_cvt_pk_bf16_f32 v67, v68, v69
	v_cvt_pk_bf16_f32 v68, v70, v71
	v_cvt_pk_bf16_f32 v69, v72, v73
	ds_write2_b64 v0, v[34:35], v[36:37] offset0:72 offset1:74
	v_cvt_pk_bf16_f32 v34, v58, v59
	v_cvt_pk_bf16_f32 v35, v60, v61
	v_cvt_pk_bf16_f32 v36, v62, v63
	v_cvt_pk_bf16_f32 v37, v64, v65
	s_add_i32 s2, s2, s10
	ds_write2_b64 v98, v[66:67], v[68:69] offset1:2
	v_cvt_pk_bf16_f32 v66, v74, v75
	v_cvt_pk_bf16_f32 v67, v76, v77
	v_cvt_pk_bf16_f32 v68, v78, v79
	v_cvt_pk_bf16_f32 v69, v80, v81
	ds_write2_b64 v0, v[34:35], v[36:37] offset0:76 offset1:78
	v_or_b32_e32 v34, s2, v99
	s_or_b32 s3, s3, s14
	ds_write2_b64 v98, v[66:67], v[68:69] offset0:4 offset1:6
	v_cvt_pk_bf16_f32 v66, v82, v83
	v_cvt_pk_bf16_f32 v67, v84, v85
	v_cvt_pk_bf16_f32 v68, v86, v87
	v_cvt_pk_bf16_f32 v69, v88, v89
	v_or_b32_e32 v36, s3, v100
	v_ashrrev_i32_e32 v35, 31, v34
	ds_write2_b64 v98, v[66:67], v[68:69] offset0:8 offset1:10
	v_cvt_pk_bf16_f32 v66, v90, v91
	v_cvt_pk_bf16_f32 v67, v92, v93
	v_cvt_pk_bf16_f32 v68, v94, v95
	v_cvt_pk_bf16_f32 v69, v96, v97
	v_min_i32_e32 v0, 0x8000, v34
	v_ashrrev_i32_e32 v37, 31, v36
	v_lshlrev_b64 v[34:35], 11, v[34:35]
	ds_write2_b64 v98, v[66:67], v[68:69] offset0:12 offset1:14
	v_lshl_add_u64 v[38:39], s[46:47], 0, v[34:35]
	v_lshlrev_b64 v[34:35], 1, v[36:37]
	s_waitcnt lgkmcnt(0)
	v_lshl_add_u64 v[64:65], v[38:39], 0, v[34:35]
	global_load_dwordx4 v[40:43], v[64:65], off
	v_ashrrev_i32_e32 v0, 11, v0
	v_mul_hi_i32_i24_e32 v39, 0x6000, v0
	v_mul_i32_i24_e32 v38, 0x6000, v0
	v_lshl_add_u64 v[38:39], s[36:37], 0, v[38:39]
	v_lshlrev_b64 v[36:37], 2, v[36:37]
	v_lshl_add_u64 v[38:39], v[38:39], 0, v[36:37]
	global_load_dwordx4 v[44:47], v[38:39], off
	global_load_dwordx4 v[48:51], v[38:39], off offset:16
	v_lshl_or_b32 v0, v100, 1, s12
	v_mad_u32_u24 v0, v99, s78, v0
	ds_read_b128 v[52:55], v0
	v_or_b32_e32 v38, 8, v99
	v_or_b32_e32 v66, s2, v38
	v_ashrrev_i32_e32 v67, 31, v66
	v_lshlrev_b64 v[56:57], 11, v[66:67]
	s_waitcnt lgkmcnt(0)
	v_lshlrev_b32_e32 v70, 16, v52
	v_and_b32_e32 v71, 0xffff0000, v52
	v_lshl_add_u64 v[56:57], s[46:47], 0, v[56:57]
	v_lshl_add_u64 v[68:69], v[56:57], 0, v[34:35]
	global_load_dwordx4 v[60:63], v[68:69], off
	v_min_i32_e32 v39, 0x8000, v66
	v_ashrrev_i32_e32 v39, 11, v39
	ds_read_b128 v[56:59], v0 offset:1152
	v_cvt_pk_bf16_f32 v2, v2, v3
	v_cvt_pk_bf16_f32 v3, v4, v5
	v_cvt_pk_bf16_f32 v4, v6, v7
	v_cvt_pk_bf16_f32 v5, v8, v9
	v_cvt_pk_bf16_f32 v6, v10, v11
	v_cvt_pk_bf16_f32 v7, v12, v13
	v_cvt_pk_bf16_f32 v8, v14, v15
	v_cvt_pk_bf16_f32 v9, v16, v17
	v_cvt_pk_bf16_f32 v10, v18, v19
	v_cvt_pk_bf16_f32 v11, v20, v21
	v_cvt_pk_bf16_f32 v12, v22, v23
	v_cvt_pk_bf16_f32 v13, v24, v25
	v_cvt_pk_bf16_f32 v14, v26, v27
	v_cvt_pk_bf16_f32 v15, v28, v29
	v_cvt_pk_bf16_f32 v16, v30, v31
	v_cvt_pk_bf16_f32 v17, v32, v33
	s_waitcnt vmcnt(3)
	v_cvt_f32_f16_e32 v72, v40
	v_cvt_f32_f16_sdwa v73, v40 dst_sel:DWORD dst_unused:UNUSED_PAD src0_sel:WORD_1
	v_cvt_f32_f16_e32 v74, v41
	v_cvt_f32_f16_sdwa v75, v41 dst_sel:DWORD dst_unused:UNUSED_PAD src0_sel:WORD_1
	v_pk_mul_f32 v[40:41], v[72:73], s[30:31] op_sel_hi:[1,0]
	s_waitcnt vmcnt(2)
	v_pk_fma_f32 v[40:41], v[44:45], v[70:71], v[40:41]
	v_lshlrev_b32_e32 v44, 16, v53
	v_and_b32_e32 v45, 0xffff0000, v53
	v_pk_mul_f32 v[52:53], v[74:75], s[30:31] op_sel_hi:[1,0]
	v_cvt_pk_f16_f32 v40, v40, v41
	v_pk_fma_f32 v[44:45], v[46:47], v[44:45], v[52:53]
	v_cvt_f32_f16_e32 v46, v42
	v_cvt_f32_f16_sdwa v47, v42 dst_sel:DWORD dst_unused:UNUSED_PAD src0_sel:WORD_1
	v_cvt_pk_f16_f32 v41, v44, v45
	v_lshlrev_b32_e32 v44, 16, v54
	v_and_b32_e32 v45, 0xffff0000, v54
	v_pk_mul_f32 v[46:47], v[46:47], s[30:31] op_sel_hi:[1,0]
	s_waitcnt lgkmcnt(0)
;   DI void operator()(f32x16 (&acc)[2][MB], int wm, int wn, int r, int h) {
;     ...
;       if ((mb & 1) || mb == MB - 1) {
;         asm volatile("s_waitcnt lgkmcnt(0)" ::: "memory");
;         const int ntok = (mb & 1) ? 64 : 32;
;         const int R0 = row0 + wm * (32 * MB) + (mb >> 1) * 64;
; #pragma unroll
;         for (int j = 0; j < 8; ++j) {
;           const int rowl = (lane >> 3) + 8 * j, ch = lane & 7;
;           if (rowl < ntok) {
;             const u32x4 yv = *(const u32x4*)(slab + rowl * 72 + ch * 8);
;             const int R = R0 + rowl;
;             const int mi = (R < NLAT) ? (R >> 11) : 16;
;             const int col = n0 + wn * 64 + ch * 8;
;             const float* g = gate + (size_t)mi * 6144 + col;
;             const f32x4n g0 = *(const f32x4n*)(g), g1 = *(const f32x4n*)(g + 4);
;             _Float16* xp = X + (size_t)R * 1024 + col;
;             const h8 xv = *(const h8*)xp;
;             const float y[8] = {__uint_as_float(yv.x << 16), __uint_as_float(yv.x & 0xffff0000u), __uint_as_float(yv.y << 16), __uint_as_float(yv.y & 0xffff0000u),
;                                 __uint_as_float(yv.z << 16), __uint_as_float(yv.z & 0xffff0000u), __uint_as_float(yv.w << 16), __uint_as_float(yv.w & 0xffff0000u)};
;             const float gg[8] = {g0.x, g0.y, g0.z, g0.w, g1.x, g1.y, g1.z, g1.w};
;             h8 o;
; #pragma unroll
;             for (int q = 0; q < 8; ++q) o[q] = (_Float16)(ALPHA * (float)xv[q] + gg[q] * y[q]);
;             *(h8*)xp = o;
;           }
;         }
	v_lshlrev_b32_e32 v54, 16, v56
	s_waitcnt vmcnt(1)
	v_pk_fma_f32 v[44:45], v[48:49], v[44:45], v[46:47]
	v_cvt_f32_f16_e32 v46, v43
	v_cvt_f32_f16_sdwa v47, v43 dst_sel:DWORD dst_unused:UNUSED_PAD src0_sel:WORD_1
	v_cvt_pk_f16_f32 v42, v44, v45
	v_lshlrev_b32_e32 v44, 16, v55
	v_and_b32_e32 v45, 0xffff0000, v55
	v_pk_mul_f32 v[46:47], v[46:47], s[30:31] op_sel_hi:[1,0]
	s_waitcnt vmcnt(0)
	v_cvt_f32_f16_e32 v66, v60
	v_pk_fma_f32 v[44:45], v[50:51], v[44:45], v[46:47]
	v_cvt_f32_f16_sdwa v67, v60 dst_sel:DWORD dst_unused:UNUSED_PAD src0_sel:WORD_1
	v_cvt_pk_f16_f32 v43, v44, v45
	global_store_dwordx4 v[64:65], v[40:43], off
	v_cvt_f32_f16_e32 v60, v61
	v_cvt_f32_f16_sdwa v61, v61 dst_sel:DWORD dst_unused:UNUSED_PAD src0_sel:WORD_1
	v_mul_hi_i32_i24_e32 v41, 0x6000, v39
	v_mul_i32_i24_e32 v40, 0x6000, v39
	v_lshl_add_u64 v[40:41], s[36:37], 0, v[40:41]
	v_lshl_add_u64 v[44:45], v[40:41], 0, v[36:37]
	global_load_dwordx4 v[40:43], v[44:45], off
	v_or_b32_e32 v39, 16, v99
	global_load_dwordx4 v[44:47], v[44:45], off offset:16
	v_or_b32_e32 v48, s2, v39
	v_min_i32_e32 v50, 0x8000, v48
	v_ashrrev_i32_e32 v49, 31, v48
	v_ashrrev_i32_e32 v50, 11, v50
	v_lshlrev_b64 v[48:49], 11, v[48:49]
	v_cvt_f32_f16_e32 v72, v62
	v_cvt_f32_f16_sdwa v73, v62 dst_sel:DWORD dst_unused:UNUSED_PAD src0_sel:WORD_1
	v_cvt_f32_f16_e32 v62, v63
	v_cvt_f32_f16_sdwa v63, v63 dst_sel:DWORD dst_unused:UNUSED_PAD src0_sel:WORD_1
	v_mul_hi_i32_i24_e32 v51, 0x6000, v50
	v_mul_i32_i24_e32 v50, 0x6000, v50
	v_lshl_add_u64 v[48:49], s[46:47], 0, v[48:49]
	v_lshl_add_u64 v[50:51], s[36:37], 0, v[50:51]
	v_lshl_add_u64 v[70:71], v[48:49], 0, v[34:35]
	v_lshl_add_u64 v[52:53], v[50:51], 0, v[36:37]
	global_load_dwordx4 v[48:51], v[70:71], off
	v_and_b32_e32 v55, 0xffff0000, v56
	v_lshlrev_b32_e32 v56, 16, v57
	v_and_b32_e32 v57, 0xffff0000, v57
	v_lshlrev_b32_e32 v64, 16, v58
	v_and_b32_e32 v65, 0xffff0000, v58
	v_lshlrev_b32_e32 v58, 16, v59
	v_and_b32_e32 v59, 0xffff0000, v59
	v_pk_mul_f32 v[66:67], v[66:67], s[30:31] op_sel_hi:[1,0]
	v_pk_mul_f32 v[60:61], v[60:61], s[30:31] op_sel_hi:[1,0]
	v_pk_mul_f32 v[72:73], v[72:73], s[30:31] op_sel_hi:[1,0]
	v_pk_mul_f32 v[62:63], v[62:63], s[30:31] op_sel_hi:[1,0]
	s_waitcnt vmcnt(2)
	v_pk_fma_f32 v[40:41], v[40:41], v[54:55], v[66:67]
	v_pk_fma_f32 v[42:43], v[42:43], v[56:57], v[60:61]
	s_waitcnt vmcnt(1)
	v_pk_fma_f32 v[44:45], v[44:45], v[64:65], v[72:73]
	v_pk_fma_f32 v[46:47], v[46:47], v[58:59], v[62:63]
	v_cvt_pk_f16_f32 v40, v40, v41
	v_cvt_pk_f16_f32 v41, v42, v43
	v_cvt_pk_f16_f32 v42, v44, v45
	v_cvt_pk_f16_f32 v43, v46, v47
	global_store_dwordx4 v[68:69], v[40:43], off
	global_load_dwordx4 v[42:45], v[52:53], off
	s_waitcnt vmcnt(2)
	v_cvt_f32_f16_e32 v76, v48
	global_load_dwordx4 v[52:55], v[52:53], off offset:16
	v_or_b32_e32 v40, 24, v99
	v_or_b32_e32 v46, s2, v40
	v_min_i32_e32 v41, 0x8000, v46
	v_ashrrev_i32_e32 v41, 11, v41
	v_ashrrev_i32_e32 v47, 31, v46
	v_mul_hi_i32_i24_e32 v57, 0x6000, v41
	v_mul_i32_i24_e32 v56, 0x6000, v41
	v_lshlrev_b64 v[46:47], 11, v[46:47]
	v_lshl_add_u64 v[60:61], s[36:37], 0, v[56:57]
	ds_read_b128 v[56:59], v0 offset:2304
	v_lshl_add_u64 v[46:47], s[46:47], 0, v[46:47]
	v_cvt_f32_f16_sdwa v77, v48 dst_sel:DWORD dst_unused:UNUSED_PAD src0_sel:WORD_1
	v_cvt_f32_f16_e32 v48, v49
	v_cvt_f32_f16_sdwa v49, v49 dst_sel:DWORD dst_unused:UNUSED_PAD src0_sel:WORD_1
	v_cvt_f32_f16_e32 v78, v50
	v_cvt_f32_f16_sdwa v79, v50 dst_sel:DWORD dst_unused:UNUSED_PAD src0_sel:WORD_1
	v_cvt_f32_f16_e32 v50, v51
	v_cvt_f32_f16_sdwa v51, v51 dst_sel:DWORD dst_unused:UNUSED_PAD src0_sel:WORD_1
	v_lshl_add_u64 v[68:69], v[46:47], 0, v[34:35]
	global_load_dwordx4 v[64:67], v[68:69], off
	s_waitcnt lgkmcnt(0)
	v_lshlrev_b32_e32 v72, 16, v56
	v_and_b32_e32 v73, 0xffff0000, v56
	v_lshlrev_b32_e32 v56, 16, v57
	v_and_b32_e32 v57, 0xffff0000, v57
	v_lshlrev_b32_e32 v74, 16, v58
	v_and_b32_e32 v75, 0xffff0000, v58
	v_lshlrev_b32_e32 v58, 16, v59
	v_and_b32_e32 v59, 0xffff0000, v59
	v_pk_mul_f32 v[76:77], v[76:77], s[30:31] op_sel_hi:[1,0]
	v_pk_mul_f32 v[48:49], v[48:49], s[30:31] op_sel_hi:[1,0]
	v_pk_mul_f32 v[78:79], v[78:79], s[30:31] op_sel_hi:[1,0]
	v_pk_mul_f32 v[50:51], v[50:51], s[30:31] op_sel_hi:[1,0]
	v_lshl_add_u64 v[46:47], v[60:61], 0, v[36:37]
	v_add_u32_e32 v41, s2, v99
	ds_read_b128 v[60:63], v0 offset:3456
	s_add_i32 s2, s2, 64
	v_or_b32_e32 v18, s2, v99
	v_ashrrev_i32_e32 v19, 31, v18
	v_lshlrev_b64 v[20:21], 11, v[18:19]
	v_lshl_add_u64 v[20:21], s[46:47], 0, v[20:21]
	v_lshl_add_u64 v[26:27], v[20:21], 0, v[34:35]
	s_waitcnt vmcnt(2)
	v_pk_fma_f32 v[42:43], v[42:43], v[72:73], v[76:77]
	v_pk_fma_f32 v[44:45], v[44:45], v[56:57], v[48:49]
	v_cvt_pk_f16_f32 v42, v42, v43
	v_cvt_pk_f16_f32 v43, v44, v45
	s_waitcnt lgkmcnt(0)
	v_lshlrev_b32_e32 v56, 16, v60
	v_and_b32_e32 v57, 0xffff0000, v60
	v_lshlrev_b32_e32 v60, 16, v62
	s_waitcnt vmcnt(1)
	v_pk_fma_f32 v[48:49], v[52:53], v[74:75], v[78:79]
	v_pk_fma_f32 v[50:51], v[54:55], v[58:59], v[50:51]
	v_cvt_pk_f16_f32 v44, v48, v49
	v_cvt_pk_f16_f32 v45, v50, v51
	global_store_dwordx4 v[70:71], v[42:45], off
	global_load_dwordx4 v[42:45], v[46:47], off
	v_add_u32_e32 v50, 32, v41
	global_load_dwordx4 v[46:49], v[46:47], off offset:16
	v_min_i32_e32 v52, 0x8000, v50
	v_ashrrev_i32_e32 v51, 31, v50
	v_ashrrev_i32_e32 v52, 11, v52
	v_lshlrev_b64 v[50:51], 11, v[50:51]
	v_mul_hi_i32_i24_e32 v53, 0x6000, v52
	v_mul_i32_i24_e32 v52, 0x6000, v52
	v_lshl_add_u64 v[50:51], s[46:47], 0, v[50:51]
	v_lshl_add_u64 v[52:53], s[36:37], 0, v[52:53]
	v_lshl_add_u64 v[70:71], v[50:51], 0, v[34:35]
	v_lshl_add_u64 v[54:55], v[52:53], 0, v[36:37]
	v_lshlrev_b32_e32 v58, 16, v61
	v_and_b32_e32 v59, 0xffff0000, v61
	s_waitcnt vmcnt(3)
;   DI void operator()(f32x16 (&acc)[2][MB], int wm, int wn, int r, int h) {
;     ...
;       if ((mb & 1) || mb == MB - 1) {
;         asm volatile("s_waitcnt lgkmcnt(0)" ::: "memory");
;         const int ntok = (mb & 1) ? 64 : 32;
;         const int R0 = row0 + wm * (32 * MB) + (mb >> 1) * 64;
; #pragma unroll
;         for (int j = 0; j < 8; ++j) {
;           const int rowl = (lane >> 3) + 8 * j, ch = lane & 7;
;           if (rowl < ntok) {
;             const u32x4 yv = *(const u32x4*)(slab + rowl * 72 + ch * 8);
;             const int R = R0 + rowl;
;             const int mi = (R < NLAT) ? (R >> 11) : 16;
;             const int col = n0 + wn * 64 + ch * 8;
;             const float* g = gate + (size_t)mi * 6144 + col;
;             const f32x4n g0 = *(const f32x4n*)(g), g1 = *(const f32x4n*)(g + 4);
;             _Float16* xp = X + (size_t)R * 1024 + col;
;             const h8 xv = *(const h8*)xp;
;             const float y[8] = {__uint_as_float(yv.x << 16), __uint_as_float(yv.x & 0xffff0000u), __uint_as_float(yv.y << 16), __uint_as_float(yv.y & 0xffff0000u),
;                                 __uint_as_float(yv.z << 16), __uint_as_float(yv.z & 0xffff0000u), __uint_as_float(yv.w << 16), __uint_as_float(yv.w & 0xffff0000u)};
;             const float gg[8] = {g0.x, g0.y, g0.z, g0.w, g1.x, g1.y, g1.z, g1.w};
;             h8 o;
; #pragma unroll
;             for (int q = 0; q < 8; ++q) o[q] = (_Float16)(ALPHA * (float)xv[q] + gg[q] * y[q]);
;             *(h8*)xp = o;
;           }
;         }
	v_cvt_f32_f16_e32 v50, v64
	v_cvt_f32_f16_sdwa v51, v64 dst_sel:DWORD dst_unused:UNUSED_PAD src0_sel:WORD_1
	v_cvt_f32_f16_e32 v52, v65
	v_cvt_f32_f16_sdwa v53, v65 dst_sel:DWORD dst_unused:UNUSED_PAD src0_sel:WORD_1
	v_cvt_f32_f16_e32 v64, v66
	v_cvt_f32_f16_sdwa v65, v66 dst_sel:DWORD dst_unused:UNUSED_PAD src0_sel:WORD_1
	v_cvt_f32_f16_e32 v66, v67
	v_cvt_f32_f16_sdwa v67, v67 dst_sel:DWORD dst_unused:UNUSED_PAD src0_sel:WORD_1
	v_pk_mul_f32 v[72:73], v[50:51], s[30:31] op_sel_hi:[1,0]
	v_pk_mul_f32 v[74:75], v[52:53], s[30:31] op_sel_hi:[1,0]
	global_load_dwordx4 v[50:53], v[70:71], off
	v_and_b32_e32 v61, 0xffff0000, v62
	v_lshlrev_b32_e32 v62, 16, v63
	v_and_b32_e32 v63, 0xffff0000, v63
	v_pk_mul_f32 v[64:65], v[64:65], s[30:31] op_sel_hi:[1,0]
	v_pk_mul_f32 v[66:67], v[66:67], s[30:31] op_sel_hi:[1,0]
	s_waitcnt vmcnt(2)
	v_pk_fma_f32 v[42:43], v[42:43], v[56:57], v[72:73]
	v_pk_fma_f32 v[44:45], v[44:45], v[58:59], v[74:75]
	s_waitcnt vmcnt(1)
	v_pk_fma_f32 v[46:47], v[46:47], v[60:61], v[64:65]
	v_pk_fma_f32 v[48:49], v[48:49], v[62:63], v[66:67]
	v_cvt_pk_f16_f32 v42, v42, v43
	v_cvt_pk_f16_f32 v43, v44, v45
	v_cvt_pk_f16_f32 v44, v46, v47
	v_cvt_pk_f16_f32 v45, v48, v49
	global_store_dwordx4 v[68:69], v[42:45], off
	global_load_dwordx4 v[42:45], v[54:55], off
	s_waitcnt vmcnt(2)
	v_cvt_f32_f16_e32 v76, v50
	global_load_dwordx4 v[46:49], v[54:55], off offset:16
	v_add_u32_e32 v54, 40, v41
	v_min_i32_e32 v56, 0x8000, v54
	v_ashrrev_i32_e32 v55, 31, v54
	v_ashrrev_i32_e32 v56, 11, v56
	v_lshlrev_b64 v[54:55], 11, v[54:55]
	v_mul_hi_i32_i24_e32 v59, 0x6000, v56
	v_mul_i32_i24_e32 v58, 0x6000, v56
	v_lshl_add_u64 v[60:61], s[46:47], 0, v[54:55]
	ds_read_b128 v[54:57], v0 offset:4608
	v_cvt_f32_f16_sdwa v77, v50 dst_sel:DWORD dst_unused:UNUSED_PAD src0_sel:WORD_1
	v_cvt_f32_f16_e32 v50, v51
	v_cvt_f32_f16_sdwa v51, v51 dst_sel:DWORD dst_unused:UNUSED_PAD src0_sel:WORD_1
	v_cvt_f32_f16_e32 v78, v52
	v_cvt_f32_f16_sdwa v79, v52 dst_sel:DWORD dst_unused:UNUSED_PAD src0_sel:WORD_1
	v_cvt_f32_f16_e32 v52, v53
	v_cvt_f32_f16_sdwa v53, v53 dst_sel:DWORD dst_unused:UNUSED_PAD src0_sel:WORD_1
	v_lshl_add_u64 v[64:65], v[60:61], 0, v[34:35]
	s_waitcnt lgkmcnt(0)
	v_lshlrev_b32_e32 v66, 16, v54
	v_and_b32_e32 v67, 0xffff0000, v54
	v_lshlrev_b32_e32 v68, 16, v55
	v_and_b32_e32 v69, 0xffff0000, v55
	v_lshlrev_b32_e32 v72, 16, v56
	v_and_b32_e32 v73, 0xffff0000, v56
	v_lshlrev_b32_e32 v74, 16, v57
	v_and_b32_e32 v75, 0xffff0000, v57
	global_load_dwordx4 v[54:57], v[64:65], off
	v_pk_mul_f32 v[76:77], v[76:77], s[30:31] op_sel_hi:[1,0]
	v_pk_mul_f32 v[50:51], v[50:51], s[30:31] op_sel_hi:[1,0]
	v_pk_mul_f32 v[78:79], v[78:79], s[30:31] op_sel_hi:[1,0]
	v_pk_mul_f32 v[52:53], v[52:53], s[30:31] op_sel_hi:[1,0]
	v_lshl_add_u64 v[62:63], s[36:37], 0, v[58:59]
	v_lshl_add_u64 v[62:63], v[62:63], 0, v[36:37]
	ds_read_b128 v[58:61], v0 offset:5760
	s_waitcnt vmcnt(2)
	v_pk_fma_f32 v[42:43], v[42:43], v[66:67], v[76:77]
	v_pk_fma_f32 v[44:45], v[44:45], v[68:69], v[50:51]
	v_cvt_pk_f16_f32 v42, v42, v43
	v_cvt_pk_f16_f32 v43, v44, v45
	v_add_u32_e32 v50, 48, v41
	v_ashrrev_i32_e32 v51, 31, v50
	s_waitcnt lgkmcnt(0)
	v_lshlrev_b32_e32 v68, 16, v58
	v_and_b32_e32 v69, 0xffff0000, v58
	v_lshlrev_b32_e32 v58, 16, v59
	v_and_b32_e32 v59, 0xffff0000, v59
	s_waitcnt vmcnt(1)
	v_pk_fma_f32 v[46:47], v[46:47], v[72:73], v[78:79]
	v_pk_fma_f32 v[48:49], v[48:49], v[74:75], v[52:53]
	v_cvt_pk_f16_f32 v44, v46, v47
	v_cvt_pk_f16_f32 v45, v48, v49
	global_store_dwordx4 v[70:71], v[42:45], off
	global_load_dwordx4 v[42:45], v[62:63], off
	v_min_i32_e32 v52, 0x8000, v50
	global_load_dwordx4 v[46:49], v[62:63], off offset:16
	v_ashrrev_i32_e32 v52, 11, v52
	v_lshlrev_b64 v[50:51], 11, v[50:51]
	v_mul_hi_i32_i24_e32 v53, 0x6000, v52
	v_mul_i32_i24_e32 v52, 0x6000, v52
	v_lshl_add_u64 v[50:51], s[46:47], 0, v[50:51]
	v_lshl_add_u64 v[52:53], s[36:37], 0, v[52:53]
	v_lshl_add_u64 v[62:63], v[50:51], 0, v[34:35]
	v_lshl_add_u64 v[66:67], v[52:53], 0, v[36:37]
	global_load_dwordx4 v[50:53], v[62:63], off
	v_lshlrev_b32_e32 v70, 16, v60
	v_and_b32_e32 v71, 0xffff0000, v60
	v_lshlrev_b32_e32 v60, 16, v61
	v_and_b32_e32 v61, 0xffff0000, v61
	s_waitcnt vmcnt(4)
	v_cvt_f32_f16_e32 v72, v54
	v_cvt_f32_f16_sdwa v73, v54 dst_sel:DWORD dst_unused:UNUSED_PAD src0_sel:WORD_1
	v_cvt_f32_f16_e32 v54, v55
	v_cvt_f32_f16_sdwa v55, v55 dst_sel:DWORD dst_unused:UNUSED_PAD src0_sel:WORD_1
	v_cvt_f32_f16_e32 v74, v56
	v_cvt_f32_f16_sdwa v75, v56 dst_sel:DWORD dst_unused:UNUSED_PAD src0_sel:WORD_1
	v_cvt_f32_f16_e32 v56, v57
	v_cvt_f32_f16_sdwa v57, v57 dst_sel:DWORD dst_unused:UNUSED_PAD src0_sel:WORD_1
	v_pk_mul_f32 v[72:73], v[72:73], s[30:31] op_sel_hi:[1,0]
	v_pk_mul_f32 v[54:55], v[54:55], s[30:31] op_sel_hi:[1,0]
	v_pk_mul_f32 v[74:75], v[74:75], s[30:31] op_sel_hi:[1,0]
	v_pk_mul_f32 v[56:57], v[56:57], s[30:31] op_sel_hi:[1,0]
	s_waitcnt vmcnt(2)
	v_pk_fma_f32 v[42:43], v[42:43], v[68:69], v[72:73]
	v_pk_fma_f32 v[44:45], v[44:45], v[58:59], v[54:55]
	s_waitcnt vmcnt(1)
	v_pk_fma_f32 v[46:47], v[46:47], v[70:71], v[74:75]
	v_pk_fma_f32 v[48:49], v[48:49], v[60:61], v[56:57]
	v_cvt_pk_f16_f32 v42, v42, v43
	v_cvt_pk_f16_f32 v43, v44, v45
	v_cvt_pk_f16_f32 v44, v46, v47
	v_cvt_pk_f16_f32 v45, v48, v49
	global_store_dwordx4 v[64:65], v[42:45], off
	global_load_dwordx4 v[42:45], v[66:67], off
	v_add_u32_e32 v54, 56, v41
	global_load_dwordx4 v[46:49], v[66:67], off offset:16
	v_ashrrev_i32_e32 v55, 31, v54
	v_min_i32_e32 v41, 0x8000, v54
	v_lshlrev_b64 v[54:55], 11, v[54:55]
	v_lshl_add_u64 v[60:61], s[46:47], 0, v[54:55]
	ds_read_b128 v[54:57], v0 offset:6912
	s_waitcnt vmcnt(3)
; DI unsigned pack2(float a, float b) { f2 v = {a, b}; bf2 r = __builtin_convertvector(v, bf2); return __builtin_bit_cast(unsigned, r); }
;   DI void operator()(f32x16 (&acc)[2][MB], int wm, int wn, int r, int h) {
;     ...
;     for (int mb = 0; mb < MB; ++mb) {
;       const int tokl = (mb & 1) * 32 + r;
; #pragma unroll
;       for (int nb = 0; nb < 2; ++nb)
; #pragma unroll
;         for (int ig = 0; ig < 4; ++ig) {
;           u32x2 o;
;           o.x = pack2(acc[nb][mb][ig * 4 + 0], acc[nb][mb][ig * 4 + 1]);
;           o.y = pack2(acc[nb][mb][ig * 4 + 2], acc[nb][mb][ig * 4 + 3]);
;           *(u32x2*)(slab + tokl * 72 + nb * 32 + ig * 8 + h * 4) = o;
;         }
;       if ((mb & 1) || mb == MB - 1) {
;         asm volatile("s_waitcnt lgkmcnt(0)" ::: "memory");
;         const int ntok = (mb & 1) ? 64 : 32;
;         const int R0 = row0 + wm * (32 * MB) + (mb >> 1) * 64;
; #pragma unroll
;         for (int j = 0; j < 8; ++j) {
;           const int rowl = (lane >> 3) + 8 * j, ch = lane & 7;
;           if (rowl < ntok) {
;             const u32x4 yv = *(const u32x4*)(slab + rowl * 72 + ch * 8);
;             const int R = R0 + rowl;
;             const int mi = (R < NLAT) ? (R >> 11) : 16;
;             const int col = n0 + wn * 64 + ch * 8;
;             const float* g = gate + (size_t)mi * 6144 + col;
;             const f32x4n g0 = *(const f32x4n*)(g), g1 = *(const f32x4n*)(g + 4);
;             _Float16* xp = X + (size_t)R * 1024 + col;
;             const h8 xv = *(const h8*)xp;
;             const float y[8] = {__uint_as_float(yv.x << 16), __uint_as_float(yv.x & 0xffff0000u), __uint_as_float(yv.y << 16), __uint_as_float(yv.y & 0xffff0000u),
;                                 __uint_as_float(yv.z << 16), __uint_as_float(yv.z & 0xffff0000u), __uint_as_float(yv.w << 16), __uint_as_float(yv.w & 0xffff0000u)};
;             const float gg[8] = {g0.x, g0.y, g0.z, g0.w, g1.x, g1.y, g1.z, g1.w};
;             h8 o;
; #pragma unroll
;             for (int q = 0; q < 8; ++q) o[q] = (_Float16)(ALPHA * (float)xv[q] + gg[q] * y[q]);
;             *(h8*)xp = o;
;           }
;         }
	v_cvt_f32_f16_e32 v76, v50
	v_cvt_f32_f16_sdwa v77, v50 dst_sel:DWORD dst_unused:UNUSED_PAD src0_sel:WORD_1
	v_cvt_f32_f16_e32 v50, v51
	v_cvt_f32_f16_sdwa v51, v51 dst_sel:DWORD dst_unused:UNUSED_PAD src0_sel:WORD_1
	v_cvt_f32_f16_e32 v78, v52
	v_cvt_f32_f16_sdwa v79, v52 dst_sel:DWORD dst_unused:UNUSED_PAD src0_sel:WORD_1
	v_cvt_f32_f16_e32 v52, v53
	v_cvt_f32_f16_sdwa v53, v53 dst_sel:DWORD dst_unused:UNUSED_PAD src0_sel:WORD_1
	v_lshl_add_u64 v[66:67], v[60:61], 0, v[34:35]
	s_waitcnt lgkmcnt(0)
	v_lshlrev_b32_e32 v68, 16, v54
	v_and_b32_e32 v69, 0xffff0000, v54
	v_lshlrev_b32_e32 v70, 16, v55
	v_and_b32_e32 v71, 0xffff0000, v55
	v_lshlrev_b32_e32 v72, 16, v56
	v_and_b32_e32 v73, 0xffff0000, v56
	v_lshlrev_b32_e32 v74, 16, v57
	v_and_b32_e32 v75, 0xffff0000, v57
	global_load_dwordx4 v[54:57], v[66:67], off
	v_ashrrev_i32_e32 v41, 11, v41
	v_pk_mul_f32 v[76:77], v[76:77], s[30:31] op_sel_hi:[1,0]
	v_pk_mul_f32 v[50:51], v[50:51], s[30:31] op_sel_hi:[1,0]
	v_pk_mul_f32 v[78:79], v[78:79], s[30:31] op_sel_hi:[1,0]
	v_pk_mul_f32 v[52:53], v[52:53], s[30:31] op_sel_hi:[1,0]
	v_mul_hi_i32_i24_e32 v59, 0x6000, v41
	v_mul_i32_i24_e32 v58, 0x6000, v41
	v_lshl_add_u64 v[64:65], s[36:37], 0, v[58:59]
	v_lshl_add_u64 v[64:65], v[64:65], 0, v[36:37]
	ds_read_b128 v[58:61], v0 offset:8064
	ds_write2_b64 v98, v[10:11], v[12:13] offset0:8 offset1:10
	ds_write2_b64 v98, v[14:15], v[16:17] offset0:12 offset1:14
	ds_write2_b64 v98, v[2:3], v[4:5] offset1:2
	ds_write2_b64 v98, v[6:7], v[8:9] offset0:4 offset1:6
	s_waitcnt lgkmcnt(4)
	v_lshlrev_b32_e32 v2, 16, v58
	v_and_b32_e32 v3, 0xffff0000, v58
	v_lshlrev_b32_e32 v4, 16, v59
	v_and_b32_e32 v5, 0xffff0000, v59
	v_lshlrev_b32_e32 v6, 16, v60
	v_and_b32_e32 v7, 0xffff0000, v60
	v_lshlrev_b32_e32 v8, 16, v61
	v_and_b32_e32 v9, 0xffff0000, v61
	s_waitcnt vmcnt(2)
	v_pk_fma_f32 v[42:43], v[42:43], v[68:69], v[76:77]
	v_pk_fma_f32 v[44:45], v[44:45], v[70:71], v[50:51]
	s_waitcnt vmcnt(1)
	v_pk_fma_f32 v[46:47], v[46:47], v[72:73], v[78:79]
	v_pk_fma_f32 v[48:49], v[48:49], v[74:75], v[52:53]
	v_cvt_pk_f16_f32 v42, v42, v43
	v_cvt_pk_f16_f32 v43, v44, v45
	v_cvt_pk_f16_f32 v44, v46, v47
	v_cvt_pk_f16_f32 v45, v48, v49
	global_store_dwordx4 v[62:63], v[42:45], off
	global_load_dwordx4 v[42:45], v[64:65], off
	s_waitcnt vmcnt(2)
	v_cvt_f32_f16_e32 v10, v54
	global_load_dwordx4 v[46:49], v[64:65], off offset:16
	v_cvt_f32_f16_sdwa v11, v54 dst_sel:DWORD dst_unused:UNUSED_PAD src0_sel:WORD_1
	v_cvt_f32_f16_e32 v12, v55
	v_cvt_f32_f16_sdwa v13, v55 dst_sel:DWORD dst_unused:UNUSED_PAD src0_sel:WORD_1
	v_cvt_f32_f16_e32 v14, v56
	v_cvt_f32_f16_sdwa v15, v56 dst_sel:DWORD dst_unused:UNUSED_PAD src0_sel:WORD_1
	v_cvt_f32_f16_e32 v16, v57
	v_cvt_f32_f16_sdwa v17, v57 dst_sel:DWORD dst_unused:UNUSED_PAD src0_sel:WORD_1
	v_pk_mul_f32 v[10:11], v[10:11], s[30:31] op_sel_hi:[1,0]
	v_pk_mul_f32 v[12:13], v[12:13], s[30:31] op_sel_hi:[1,0]
	v_pk_mul_f32 v[14:15], v[14:15], s[30:31] op_sel_hi:[1,0]
	v_pk_mul_f32 v[16:17], v[16:17], s[30:31] op_sel_hi:[1,0]
	s_waitcnt vmcnt(1)
	v_pk_fma_f32 v[2:3], v[42:43], v[2:3], v[10:11]
	v_pk_fma_f32 v[4:5], v[44:45], v[4:5], v[12:13]
	v_cvt_pk_f16_f32 v2, v2, v3
	v_cvt_pk_f16_f32 v3, v4, v5
	s_waitcnt vmcnt(0)
	v_pk_fma_f32 v[6:7], v[46:47], v[6:7], v[14:15]
	v_pk_fma_f32 v[8:9], v[48:49], v[8:9], v[16:17]
	v_cvt_pk_f16_f32 v4, v6, v7
	v_cvt_pk_f16_f32 v5, v8, v9
	global_store_dwordx4 v[66:67], v[2:5], off
	s_waitcnt lgkmcnt(0)
	global_load_dwordx4 v[2:5], v[26:27], off
	v_min_i32_e32 v6, 0x8000, v18
	v_ashrrev_i32_e32 v6, 11, v6
	v_mul_hi_i32_i24_e32 v7, 0x6000, v6
	v_mul_i32_i24_e32 v6, 0x6000, v6
	v_lshl_add_u64 v[6:7], s[36:37], 0, v[6:7]
	v_lshl_add_u64 v[10:11], v[6:7], 0, v[36:37]
	global_load_dwordx4 v[6:9], v[10:11], off
	v_or_b32_e32 v14, s2, v38
	global_load_dwordx4 v[10:13], v[10:11], off offset:16
	v_min_i32_e32 v16, 0x8000, v14
	v_ashrrev_i32_e32 v15, 31, v14
	v_ashrrev_i32_e32 v16, 11, v16
	v_lshlrev_b64 v[14:15], 11, v[14:15]
	v_mul_hi_i32_i24_e32 v17, 0x6000, v16
	v_mul_i32_i24_e32 v16, 0x6000, v16
	v_lshl_add_u64 v[18:19], s[46:47], 0, v[14:15]
	v_lshl_add_u64 v[20:21], s[36:37], 0, v[16:17]
	ds_read_b128 v[14:17], v0
	v_lshl_add_u64 v[28:29], v[18:19], 0, v[34:35]
	global_load_dwordx4 v[22:25], v[28:29], off
	v_lshl_add_u64 v[30:31], v[20:21], 0, v[36:37]
	ds_read_b128 v[18:21], v0 offset:1152
	s_waitcnt lgkmcnt(1)
	v_lshlrev_b32_e32 v32, 16, v14
	v_and_b32_e32 v33, 0xffff0000, v14
	v_lshlrev_b32_e32 v14, 16, v15
	v_and_b32_e32 v15, 0xffff0000, v15
	v_lshlrev_b32_e32 v42, 16, v16
	v_and_b32_e32 v43, 0xffff0000, v16
	v_lshlrev_b32_e32 v16, 16, v17
	v_and_b32_e32 v17, 0xffff0000, v17
	s_waitcnt vmcnt(3)
	v_cvt_f32_f16_e32 v44, v2
	v_cvt_f32_f16_sdwa v45, v2 dst_sel:DWORD dst_unused:UNUSED_PAD src0_sel:WORD_1
	v_cvt_f32_f16_e32 v2, v3
	v_cvt_f32_f16_sdwa v3, v3 dst_sel:DWORD dst_unused:UNUSED_PAD src0_sel:WORD_1
	v_cvt_f32_f16_e32 v46, v4
	v_cvt_f32_f16_sdwa v47, v4 dst_sel:DWORD dst_unused:UNUSED_PAD src0_sel:WORD_1
	v_cvt_f32_f16_e32 v4, v5
	v_cvt_f32_f16_sdwa v5, v5 dst_sel:DWORD dst_unused:UNUSED_PAD src0_sel:WORD_1
	v_pk_mul_f32 v[44:45], v[44:45], s[30:31] op_sel_hi:[1,0]
	v_pk_mul_f32 v[2:3], v[2:3], s[30:31] op_sel_hi:[1,0]
	v_pk_mul_f32 v[46:47], v[46:47], s[30:31] op_sel_hi:[1,0]
	v_pk_mul_f32 v[4:5], v[4:5], s[30:31] op_sel_hi:[1,0]
	s_waitcnt vmcnt(2)
	v_pk_fma_f32 v[6:7], v[6:7], v[32:33], v[44:45]
	v_pk_fma_f32 v[8:9], v[8:9], v[14:15], v[2:3]
	s_waitcnt vmcnt(1)
;   DI void operator()(f32x16 (&acc)[2][MB], int wm, int wn, int r, int h) {
;     ...
;       if ((mb & 1) || mb == MB - 1) {
;         asm volatile("s_waitcnt lgkmcnt(0)" ::: "memory");
;         const int ntok = (mb & 1) ? 64 : 32;
;         const int R0 = row0 + wm * (32 * MB) + (mb >> 1) * 64;
; #pragma unroll
;         for (int j = 0; j < 8; ++j) {
;           const int rowl = (lane >> 3) + 8 * j, ch = lane & 7;
;           if (rowl < ntok) {
;             const u32x4 yv = *(const u32x4*)(slab + rowl * 72 + ch * 8);
;             const int R = R0 + rowl;
;             const int mi = (R < NLAT) ? (R >> 11) : 16;
;             const int col = n0 + wn * 64 + ch * 8;
;             const float* g = gate + (size_t)mi * 6144 + col;
;             const f32x4n g0 = *(const f32x4n*)(g), g1 = *(const f32x4n*)(g + 4);
;             _Float16* xp = X + (size_t)R * 1024 + col;
;             const h8 xv = *(const h8*)xp;
;             const float y[8] = {__uint_as_float(yv.x << 16), __uint_as_float(yv.x & 0xffff0000u), __uint_as_float(yv.y << 16), __uint_as_float(yv.y & 0xffff0000u),
;                                 __uint_as_float(yv.z << 16), __uint_as_float(yv.z & 0xffff0000u), __uint_as_float(yv.w << 16), __uint_as_float(yv.w & 0xffff0000u)};
;             const float gg[8] = {g0.x, g0.y, g0.z, g0.w, g1.x, g1.y, g1.z, g1.w};
;             h8 o;
; #pragma unroll
;             for (int q = 0; q < 8; ++q) o[q] = (_Float16)(ALPHA * (float)xv[q] + gg[q] * y[q]);
;             *(h8*)xp = o;
;           }
;         }
;       }
;     }
;     __syncthreads();
	v_pk_fma_f32 v[10:11], v[10:11], v[42:43], v[46:47]
	v_pk_fma_f32 v[12:13], v[12:13], v[16:17], v[4:5]
	v_cvt_pk_f16_f32 v2, v6, v7
	v_cvt_pk_f16_f32 v3, v8, v9
	v_cvt_pk_f16_f32 v4, v10, v11
	v_cvt_pk_f16_f32 v5, v12, v13
	global_store_dwordx4 v[26:27], v[2:5], off
	global_load_dwordx4 v[2:5], v[30:31], off
	v_or_b32_e32 v10, s2, v39
	global_load_dwordx4 v[6:9], v[30:31], off offset:16
	v_min_i32_e32 v12, 0x8000, v10
	v_ashrrev_i32_e32 v11, 31, v10
	v_ashrrev_i32_e32 v12, 11, v12
	v_lshlrev_b64 v[10:11], 11, v[10:11]
	s_waitcnt vmcnt(3)
	v_cvt_f32_f16_e32 v32, v22
	v_cvt_f32_f16_sdwa v33, v22 dst_sel:DWORD dst_unused:UNUSED_PAD src0_sel:WORD_1
	v_cvt_f32_f16_e32 v22, v23
	v_cvt_f32_f16_sdwa v23, v23 dst_sel:DWORD dst_unused:UNUSED_PAD src0_sel:WORD_1
	v_cvt_f32_f16_e32 v38, v24
	v_cvt_f32_f16_sdwa v39, v24 dst_sel:DWORD dst_unused:UNUSED_PAD src0_sel:WORD_1
	v_cvt_f32_f16_e32 v24, v25
	v_cvt_f32_f16_sdwa v25, v25 dst_sel:DWORD dst_unused:UNUSED_PAD src0_sel:WORD_1
	v_mul_hi_i32_i24_e32 v13, 0x6000, v12
	v_mul_i32_i24_e32 v12, 0x6000, v12
	v_lshl_add_u64 v[10:11], s[46:47], 0, v[10:11]
	v_lshl_add_u64 v[12:13], s[36:37], 0, v[12:13]
	v_lshl_add_u64 v[26:27], v[10:11], 0, v[34:35]
	v_lshl_add_u64 v[14:15], v[12:13], 0, v[36:37]
	global_load_dwordx4 v[10:13], v[26:27], off
	s_waitcnt lgkmcnt(0)
	v_lshlrev_b32_e32 v16, 16, v18
	v_and_b32_e32 v17, 0xffff0000, v18
	v_lshlrev_b32_e32 v18, 16, v19
	v_and_b32_e32 v19, 0xffff0000, v19
	v_lshlrev_b32_e32 v30, 16, v20
	v_and_b32_e32 v31, 0xffff0000, v20
	v_lshlrev_b32_e32 v20, 16, v21
	v_and_b32_e32 v21, 0xffff0000, v21
	v_pk_mul_f32 v[32:33], v[32:33], s[30:31] op_sel_hi:[1,0]
	v_pk_mul_f32 v[22:23], v[22:23], s[30:31] op_sel_hi:[1,0]
	v_pk_mul_f32 v[38:39], v[38:39], s[30:31] op_sel_hi:[1,0]
	v_pk_mul_f32 v[24:25], v[24:25], s[30:31] op_sel_hi:[1,0]
	s_waitcnt vmcnt(2)
	v_pk_fma_f32 v[2:3], v[2:3], v[16:17], v[32:33]
	v_pk_fma_f32 v[4:5], v[4:5], v[18:19], v[22:23]
	s_waitcnt vmcnt(1)
	v_pk_fma_f32 v[6:7], v[6:7], v[30:31], v[38:39]
	v_pk_fma_f32 v[8:9], v[8:9], v[20:21], v[24:25]
	v_cvt_pk_f16_f32 v2, v2, v3
	v_cvt_pk_f16_f32 v3, v4, v5
	v_cvt_pk_f16_f32 v4, v6, v7
	v_cvt_pk_f16_f32 v5, v8, v9
	global_store_dwordx4 v[28:29], v[2:5], off
	global_load_dwordx4 v[2:5], v[14:15], off
	s_waitcnt vmcnt(2)
	v_cvt_f32_f16_e32 v38, v12
	global_load_dwordx4 v[6:9], v[14:15], off offset:16
	v_or_b32_e32 v14, s2, v40
	v_min_i32_e32 v16, 0x8000, v14
	v_ashrrev_i32_e32 v15, 31, v14
	v_ashrrev_i32_e32 v16, 11, v16
	v_lshlrev_b64 v[14:15], 11, v[14:15]
	v_mul_hi_i32_i24_e32 v17, 0x6000, v16
	v_mul_i32_i24_e32 v16, 0x6000, v16
	v_lshl_add_u64 v[18:19], s[46:47], 0, v[14:15]
	v_lshl_add_u64 v[20:21], s[36:37], 0, v[16:17]
	ds_read_b128 v[14:17], v0 offset:2304
	v_lshl_add_u64 v[30:31], v[20:21], 0, v[36:37]
	v_cvt_f32_f16_e32 v36, v10
	v_cvt_f32_f16_sdwa v37, v10 dst_sel:DWORD dst_unused:UNUSED_PAD src0_sel:WORD_1
	v_cvt_f32_f16_e32 v10, v11
	v_cvt_f32_f16_sdwa v11, v11 dst_sel:DWORD dst_unused:UNUSED_PAD src0_sel:WORD_1
	v_cvt_f32_f16_sdwa v39, v12 dst_sel:DWORD dst_unused:UNUSED_PAD src0_sel:WORD_1
	v_cvt_f32_f16_e32 v12, v13
	v_cvt_f32_f16_sdwa v13, v13 dst_sel:DWORD dst_unused:UNUSED_PAD src0_sel:WORD_1
	v_lshl_add_u64 v[28:29], v[18:19], 0, v[34:35]
	global_load_dwordx4 v[22:25], v[28:29], off
	s_waitcnt lgkmcnt(0)
	v_lshlrev_b32_e32 v32, 16, v14
	v_and_b32_e32 v33, 0xffff0000, v14
	v_lshlrev_b32_e32 v14, 16, v15
	v_and_b32_e32 v15, 0xffff0000, v15
	v_lshlrev_b32_e32 v34, 16, v16
	v_and_b32_e32 v35, 0xffff0000, v16
	v_lshlrev_b32_e32 v16, 16, v17
	v_and_b32_e32 v17, 0xffff0000, v17
	v_pk_mul_f32 v[36:37], v[36:37], s[30:31] op_sel_hi:[1,0]
	v_pk_mul_f32 v[10:11], v[10:11], s[30:31] op_sel_hi:[1,0]
	v_pk_mul_f32 v[38:39], v[38:39], s[30:31] op_sel_hi:[1,0]
	v_pk_mul_f32 v[12:13], v[12:13], s[30:31] op_sel_hi:[1,0]
	ds_read_b128 v[18:21], v0 offset:3456
	s_waitcnt vmcnt(2)
	v_pk_fma_f32 v[2:3], v[2:3], v[32:33], v[36:37]
	v_pk_fma_f32 v[4:5], v[4:5], v[14:15], v[10:11]
	v_cvt_pk_f16_f32 v2, v2, v3
	v_cvt_pk_f16_f32 v3, v4, v5
	s_waitcnt lgkmcnt(0)
	v_lshlrev_b32_e32 v10, 16, v18
	v_and_b32_e32 v11, 0xffff0000, v18
	v_lshlrev_b32_e32 v14, 16, v20
	v_and_b32_e32 v15, 0xffff0000, v20
	s_waitcnt vmcnt(1)
	v_pk_fma_f32 v[6:7], v[6:7], v[34:35], v[38:39]
	v_pk_fma_f32 v[8:9], v[8:9], v[16:17], v[12:13]
	v_cvt_pk_f16_f32 v4, v6, v7
	v_cvt_pk_f16_f32 v5, v8, v9
	global_store_dwordx4 v[26:27], v[2:5], off
	global_load_dwordx4 v[2:5], v[30:31], off
	v_lshlrev_b32_e32 v12, 16, v19
	global_load_dwordx4 v[6:9], v[30:31], off offset:16
	v_and_b32_e32 v13, 0xffff0000, v19
	v_lshlrev_b32_e32 v16, 16, v21
	v_and_b32_e32 v17, 0xffff0000, v21
	s_waitcnt vmcnt(3)
	v_cvt_f32_f16_e32 v18, v22
	v_cvt_f32_f16_sdwa v19, v22 dst_sel:DWORD dst_unused:UNUSED_PAD src0_sel:WORD_1
	v_cvt_f32_f16_e32 v20, v23
	v_cvt_f32_f16_sdwa v21, v23 dst_sel:DWORD dst_unused:UNUSED_PAD src0_sel:WORD_1
	v_cvt_f32_f16_e32 v22, v24
	v_cvt_f32_f16_sdwa v23, v24 dst_sel:DWORD dst_unused:UNUSED_PAD src0_sel:WORD_1
	v_cvt_f32_f16_e32 v24, v25
	v_cvt_f32_f16_sdwa v25, v25 dst_sel:DWORD dst_unused:UNUSED_PAD src0_sel:WORD_1
	v_pk_mul_f32 v[18:19], v[18:19], s[30:31] op_sel_hi:[1,0]
	v_pk_mul_f32 v[20:21], v[20:21], s[30:31] op_sel_hi:[1,0]
	v_pk_mul_f32 v[22:23], v[22:23], s[30:31] op_sel_hi:[1,0]
	v_pk_mul_f32 v[24:25], v[24:25], s[30:31] op_sel_hi:[1,0]
	s_waitcnt vmcnt(1)
	v_pk_fma_f32 v[2:3], v[2:3], v[10:11], v[18:19]
	v_pk_fma_f32 v[4:5], v[4:5], v[12:13], v[20:21]
	s_waitcnt vmcnt(0)
	v_pk_fma_f32 v[6:7], v[6:7], v[14:15], v[22:23]
	v_pk_fma_f32 v[8:9], v[8:9], v[16:17], v[24:25]
	v_cvt_pk_f16_f32 v2, v2, v3
	v_cvt_pk_f16_f32 v3, v4, v5
	v_cvt_pk_f16_f32 v4, v6, v7
	v_cvt_pk_f16_f32 v5, v8, v9
	global_store_dwordx4 v[28:29], v[2:5], off
	s_barrier
	s_branch .LBB0_646

; template <int MB, class Epi>
; DI void gemm_tile(const u16* __restrict__ A, int lda, int row0, int Mrows, const u16* __restrict__ Bt, int ldb, int K, char* smem, Epi& epi, int rot) {
;     ...
;   for (int kt = 0; kt < KT; ++kt) {
;     const bool more = (kt + 1 < KT);
;     const bool more2 = (kt + 2 < KT);
;     const int nstg = (kt + 1) & 1;
;     const char* as = As + (kt & 1) * 32768 + wm * (32 * MB) * 128;
;     const char* bs = Bs + (kt & 1) * 32768 + wn * 64 * 128;
;     int k1_ = kbase + kt + 1; if (k1_ >= KT) k1_ -= KT;
;     int k2_ = kbase + kt + 2; if (k2_ >= KT) k2_ -= KT; if (k2_ >= KT) k2_ -= KT;
; #pragma unroll
;     for (int ks = 0; ks < 3; ++ks) {
; #pragma unroll
;       for (int idx = 0; idx < 2 * MB; ++idx) {
;         const int nb = idx / MB, mb = idx % MB;
;         acc[nb][mb] = mfma32(bfr[ks & 1][nb], af[ks & 1][mb], acc[nb][mb]);
;         if (idx < MB) af[(ks + 1) & 1][idx] = *(const bf8*)(as + idx * 32 * 128 + foff[ks + 1]);
;         else if (idx < MB + 2) bfr[(ks + 1) & 1][idx - MB] = *(const bf8*)(bs + (idx - MB) * 32 * 128 + foff[ks + 1]);
;         if (more && ks < 2 && idx < 3) {
;           const int ko_ = k1_ * 64;
;           GEMM_PIECE(nstg, 3 + ks * 3 + idx)
;         }
;         __builtin_amdgcn_sched_barrier(0);
;       }
;     }
;     if (more) {
;       asm volatile("s_waitcnt vmcnt(0)" ::: "memory");
;       __syncthreads();
;       if (more2) {
;         const int ko_ = k2_ * 64;
; #pragma unroll
;         for (int pc = 0; pc < 3; ++pc) GEMM_PIECE(kt & 1, pc)
;       }
;       __builtin_amdgcn_sched_barrier(0);
;       const char* asn = As + nstg * 32768 + wm * (32 * MB) * 128;
;       const char* bsn = Bs + nstg * 32768 + wn * 64 * 128;
; #pragma unroll
;       for (int mb = 0; mb < MB; ++mb) af[0][mb] = *(const bf8*)(asn + mb * 32 * 128 + foff[0]);
; #pragma unroll
;       for (int nb = 0; nb < 2; ++nb) bfr[0][nb] = *(const bf8*)(bsn + nb * 32 * 128 + foff[0]);
;     }
; #pragma unroll
;     for (int nb = 0; nb < 2; ++nb)
; #pragma unroll
;       for (int mb = 0; mb < MB; ++mb) acc[nb][mb] = mfma32(bfr[1][nb], af[1][mb], acc[nb][mb]);
; #pragma unroll
;     for (int gk = 0; gk < 2 * MB; ++gk) {
;       __builtin_amdgcn_sched_group_barrier(0x008, 1, 0);
;       __builtin_amdgcn_sched_group_barrier(0x100, 1, 0);
;     }
;     __builtin_amdgcn_sched_barrier(0);
;   }
.LBB0_658:
	s_and_b32 s16, s11, 0x8000
	s_add_i32 s18, s17, 1
	s_add_i32 s23, s10, s16
	s_add_i32 s22, s9, s16
	s_add_i32 s19, s13, s17
	s_cmp_lt_i32 s19, 15
	s_cselect_b32 s17, 0, -16
	s_add_i32 s17, s19, s17
	s_waitcnt lgkmcnt(1)
	v_mfma_f32_32x32x16_bf16 v[114:129], v[150:153], v[146:149], v[114:129]
	s_lshl_b32 s17, s17, 6
	s_add_i32 s26, s17, 64
	s_ashr_i32 s27, s26, 31
	s_add_i32 s11, s11, 0x8000
	v_add_u32_e32 v188, s23, v171
	s_lshl_b64 s[26:27], s[26:27], 1
	s_and_b32 s17, s11, 0x8000
	ds_read_b128 v[172:175], v188
	s_add_i32 s28, s17, s15
	v_lshl_add_u64 v[176:177], v[160:161], 0, s[26:27]
	s_mov_b32 m0, s28
	s_nop 0
	global_load_lds_dwordx4 v[176:177], off
	v_lshl_add_u64 v[184:185], v[158:159], 0, s[26:27]
	s_add_i32 s25, s17, s12
	v_mfma_f32_32x32x16_bf16 v[66:81], v[150:153], v[142:145], v[66:81]
	ds_read_b128 v[176:179], v188 offset:4096
	s_mov_b32 m0, s25
	s_nop 0
	global_load_lds_dwordx4 v[184:185], off
	v_mfma_f32_32x32x16_bf16 v[18:33], v[150:153], v[134:137], v[18:33]
	ds_read_b128 v[180:183], v188 offset:8192
	s_add_i32 s26, s25, 0x2000
	v_lshl_add_u64 v[186:187], v[184:185], 0, s[4:5]
	s_mov_b32 m0, s26
	s_nop 0
	global_load_lds_dwordx4 v[186:187], off
	v_mfma_f32_32x32x16_bf16 v[2:17], v[150:153], v[130:133], v[2:17]
	ds_read_b128 v[150:153], v188 offset:12288
	s_waitcnt lgkmcnt(4)
	v_mfma_f32_32x32x16_bf16 v[98:113], v[138:141], v[146:149], v[98:113]
	v_add_u32_e32 v186, s22, v171
	ds_read_b128 v[146:149], v186
	v_mfma_f32_32x32x16_bf16 v[82:97], v[138:141], v[142:145], v[82:97]
	ds_read_b128 v[142:145], v186 offset:4096
	v_mfma_f32_32x32x16_bf16 v[50:65], v[138:141], v[134:137], v[50:65]
	v_mfma_f32_32x32x16_bf16 v[34:49], v[138:141], v[130:133], v[34:49]
	s_waitcnt lgkmcnt(1)
	v_mfma_f32_32x32x16_bf16 v[114:129], v[146:149], v[172:175], v[114:129]
	v_add_u32_e32 v186, s23, v170
	ds_read_b128 v[130:133], v186
	s_add_i32 s26, s25, 0x4000
	v_lshl_add_u64 v[134:135], v[184:185], 0, s[6:7]
	s_mov_b32 m0, s26
	s_nop 0
	global_load_lds_dwordx4 v[134:135], off
	v_mfma_f32_32x32x16_bf16 v[66:81], v[146:149], v[176:179], v[66:81]
	ds_read_b128 v[134:137], v186 offset:4096
	s_addk_i32 s25, 0x6000
	v_lshl_add_u64 v[138:139], v[184:185], 0, s[34:35]
	s_mov_b32 m0, s25
	s_nop 0
	global_load_lds_dwordx4 v[138:139], off
	v_mfma_f32_32x32x16_bf16 v[18:33], v[146:149], v[180:183], v[18:33]
	ds_read_b128 v[138:141], v186 offset:8192
	v_mfma_f32_32x32x16_bf16 v[2:17], v[146:149], v[150:153], v[2:17]
	ds_read_b128 v[146:149], v186 offset:12288
	s_waitcnt lgkmcnt(4)
	v_mfma_f32_32x32x16_bf16 v[98:113], v[142:145], v[172:175], v[98:113]
	v_add_u32_e32 v184, s22, v170
	ds_read_b128 v[172:175], v184
	v_mfma_f32_32x32x16_bf16 v[82:97], v[142:145], v[176:179], v[82:97]
	ds_read_b128 v[176:179], v184 offset:4096
	v_mfma_f32_32x32x16_bf16 v[50:65], v[142:145], v[180:183], v[50:65]
	v_mfma_f32_32x32x16_bf16 v[34:49], v[142:145], v[150:153], v[34:49]
	s_waitcnt lgkmcnt(1)
	v_mfma_f32_32x32x16_bf16 v[114:129], v[172:175], v[130:133], v[114:129]
	v_add_u32_e32 v142, s23, v169
	ds_read_b128 v[150:153], v142
	v_mfma_f32_32x32x16_bf16 v[66:81], v[172:175], v[134:137], v[66:81]
	ds_read_b128 v[180:183], v142 offset:4096
	v_mfma_f32_32x32x16_bf16 v[18:33], v[172:175], v[138:141], v[18:33]
	ds_read_b128 v[184:187], v142 offset:8192
	v_mfma_f32_32x32x16_bf16 v[2:17], v[172:175], v[146:149], v[2:17]
	ds_read_b128 v[172:175], v142 offset:12288
	s_waitcnt lgkmcnt(4)
	v_mfma_f32_32x32x16_bf16 v[98:113], v[176:179], v[130:133], v[98:113]
	v_add_u32_e32 v142, s22, v169
	ds_read_b128 v[130:133], v142
	v_mfma_f32_32x32x16_bf16 v[82:97], v[176:179], v[134:137], v[82:97]
	ds_read_b128 v[188:191], v142 offset:4096
	v_mfma_f32_32x32x16_bf16 v[50:65], v[176:179], v[138:141], v[50:65]
	v_mfma_f32_32x32x16_bf16 v[34:49], v[176:179], v[146:149], v[34:49]
	s_cmp_lt_i32 s19, 14
	s_cselect_b32 s22, 0, -16
	s_add_i32 s23, s19, s22
	s_add_i32 s23, s23, 2
	s_cmp_lt_i32 s23, 16
	s_cselect_b32 s23, 0, -16
	s_add_i32 s22, s22, s23
	s_add_i32 s19, s19, s22
	s_lshl_b32 s19, s19, 6
	s_add_i32 s22, s19, 0x80
	s_ashr_i32 s23, s22, 31
	s_lshl_b64 s[22:23], s[22:23], 1
	s_add_u32 s22, s20, s22
	s_addc_u32 s23, s21, s23
	s_waitcnt vmcnt(0)
	s_waitcnt lgkmcnt(0)
	s_barrier
	s_add_i32 s19, s16, s14
	v_lshl_add_u64 v[134:135], s[22:23], 0, v[0:1]
	s_mov_b32 m0, s19
	s_nop 0
	global_load_lds_dwordx4 v[134:135], off
	v_lshl_add_u64 v[134:135], v[154:155], 1, s[22:23]
	s_add_i32 s25, s19, 0x2000
	s_mov_b32 m0, s25
	s_nop 0
	global_load_lds_dwordx4 v[134:135], off
	v_lshl_add_u64 v[134:135], v[156:157], 1, s[22:23]
	s_addk_i32 s19, 0x4000
	s_mov_b32 m0, s19
	s_nop 0
	global_load_lds_dwordx4 v[134:135], off
	v_add_u32_e32 v138, s17, v168
	v_mfma_f32_32x32x16_bf16 v[114:129], v[130:133], v[150:153], v[114:129]
	ds_read_b128 v[146:149], v138
	v_mfma_f32_32x32x16_bf16 v[66:81], v[130:133], v[180:183], v[66:81]
	ds_read_b128 v[142:145], v138 offset:4096
	v_mfma_f32_32x32x16_bf16 v[18:33], v[130:133], v[184:187], v[18:33]
	ds_read_b128 v[134:137], v138 offset:8192
	v_mfma_f32_32x32x16_bf16 v[2:17], v[130:133], v[172:175], v[2:17]
	ds_read_b128 v[130:133], v138 offset:12288
	v_add_u32_e32 v138, s17, v167
	v_mfma_f32_32x32x16_bf16 v[98:113], v[188:191], v[150:153], v[98:113]
	ds_read_b128 v[150:153], v138
	v_mfma_f32_32x32x16_bf16 v[82:97], v[188:191], v[180:183], v[82:97]
	ds_read_b128 v[138:141], v138 offset:4096
	v_mfma_f32_32x32x16_bf16 v[50:65], v[188:191], v[184:187], v[50:65]
	v_mfma_f32_32x32x16_bf16 v[34:49], v[188:191], v[172:175], v[34:49]
	s_cmp_lg_u32 s18, 14
	s_mov_b32 s17, s18
	s_cbranch_scc1 .LBB0_658
; DI f32x16 mfma32(bf8 a, bf8 b, f32x16 c) { return __builtin_amdgcn_mfma_f32_32x32x16_bf16(a, b, c, 0, 0, 0); }
; template <int MB, class Epi>
; DI void gemm_tile(const u16* __restrict__ A, int lda, int row0, int Mrows, const u16* __restrict__ Bt, int ldb, int K, char* smem, Epi& epi, int rot) {
;     ...
;   for (int kt = 0; kt < KT; ++kt) {
;     const bool more = (kt + 1 < KT);
;     const bool more2 = (kt + 2 < KT);
;     const int nstg = (kt + 1) & 1;
;     const char* as = As + (kt & 1) * 32768 + wm * (32 * MB) * 128;
;     const char* bs = Bs + (kt & 1) * 32768 + wn * 64 * 128;
;     int k1_ = kbase + kt + 1; if (k1_ >= KT) k1_ -= KT;
;     int k2_ = kbase + kt + 2; if (k2_ >= KT) k2_ -= KT; if (k2_ >= KT) k2_ -= KT;
; #pragma unroll
;     for (int ks = 0; ks < 3; ++ks) {
; #pragma unroll
;       for (int idx = 0; idx < 2 * MB; ++idx) {
;         const int nb = idx / MB, mb = idx % MB;
;         acc[nb][mb] = mfma32(bfr[ks & 1][nb], af[ks & 1][mb], acc[nb][mb]);
;         if (idx < MB) af[(ks + 1) & 1][idx] = *(const bf8*)(as + idx * 32 * 128 + foff[ks + 1]);
;         else if (idx < MB + 2) bfr[(ks + 1) & 1][idx - MB] = *(const bf8*)(bs + (idx - MB) * 32 * 128 + foff[ks + 1]);
;         if (more && ks < 2 && idx < 3) {
;           const int ko_ = k1_ * 64;
;           GEMM_PIECE(nstg, 3 + ks * 3 + idx)
;         }
;         __builtin_amdgcn_sched_barrier(0);
;       }
;     }
;     if (more) {
;       asm volatile("s_waitcnt vmcnt(0)" ::: "memory");
;       __syncthreads();
;       if (more2) {
;         const int ko_ = k2_ * 64;
; #pragma unroll
;         for (int pc = 0; pc < 3; ++pc) GEMM_PIECE(kt & 1, pc)
;       }
;       __builtin_amdgcn_sched_barrier(0);
;       const char* asn = As + nstg * 32768 + wm * (32 * MB) * 128;
;       const char* bsn = Bs + nstg * 32768 + wn * 64 * 128;
; #pragma unroll
;       for (int mb = 0; mb < MB; ++mb) af[0][mb] = *(const bf8*)(asn + mb * 32 * 128 + foff[0]);
; #pragma unroll
;       for (int nb = 0; nb < 2; ++nb) bfr[0][nb] = *(const bf8*)(bsn + nb * 32 * 128 + foff[0]);
;     }
; #pragma unroll
;     for (int nb = 0; nb < 2; ++nb)
; #pragma unroll
;       for (int mb = 0; mb < MB; ++mb) acc[nb][mb] = mfma32(bfr[1][nb], af[1][mb], acc[nb][mb]);
	s_add_i32 s11, s13, 14
	s_cmp_lt_i32 s11, 15
	s_cselect_b32 s13, 0, -16
	s_add_i32 s11, s11, s13
	s_lshl_b32 s11, s11, 6
	s_add_i32 s18, s11, 64
	s_ashr_i32 s19, s18, 31
	v_add_u32_e32 v0, s10, v171
	s_lshl_b64 s[18:19], s[18:19], 1
	ds_read_b128 v[154:157], v0
	v_lshl_add_u64 v[176:177], v[158:159], 0, s[18:19]
	s_add_i32 s11, s16, s12
	s_add_i32 s12, s16, s15
	v_lshl_add_u64 v[158:159], v[160:161], 0, s[18:19]
	s_mov_b32 m0, s12
	s_nop 0
	global_load_lds_dwordx4 v[158:159], off
	s_waitcnt lgkmcnt(2)
	v_mfma_f32_32x32x16_bf16 v[114:129], v[150:153], v[146:149], v[114:129]
	ds_read_b128 v[158:161], v0 offset:4096
	s_mov_b32 m0, s11
	s_nop 0
	global_load_lds_dwordx4 v[176:177], off
	v_mfma_f32_32x32x16_bf16 v[66:81], v[150:153], v[142:145], v[66:81]
	ds_read_b128 v[172:175], v0 offset:8192
	s_add_i32 s12, s11, 0x2000
	v_lshl_add_u64 v[178:179], v[176:177], 0, s[4:5]
	s_mov_b32 m0, s12
	s_nop 0
	global_load_lds_dwordx4 v[178:179], off
	v_mfma_f32_32x32x16_bf16 v[18:33], v[150:153], v[134:137], v[18:33]
	v_mfma_f32_32x32x16_bf16 v[2:17], v[150:153], v[130:133], v[2:17]
	ds_read_b128 v[150:153], v0 offset:12288
	v_add_u32_e32 v178, s9, v171
	s_waitcnt lgkmcnt(4)
	v_mfma_f32_32x32x16_bf16 v[98:113], v[138:141], v[146:149], v[98:113]
	ds_read_b128 v[146:149], v178
	v_mfma_f32_32x32x16_bf16 v[82:97], v[138:141], v[142:145], v[82:97]
	ds_read_b128 v[142:145], v178 offset:4096
	v_mfma_f32_32x32x16_bf16 v[50:65], v[138:141], v[134:137], v[50:65]
	v_mfma_f32_32x32x16_bf16 v[34:49], v[138:141], v[130:133], v[34:49]
	v_add_u32_e32 v179, s10, v170
	ds_read_b128 v[130:133], v179
	s_add_i32 s12, s11, 0x4000
	v_lshl_add_u64 v[134:135], v[176:177], 0, s[6:7]
	s_mov_b32 m0, s12
	s_nop 0
	global_load_lds_dwordx4 v[134:135], off
	s_waitcnt lgkmcnt(2)
	v_mfma_f32_32x32x16_bf16 v[114:129], v[146:149], v[154:157], v[114:129]
	ds_read_b128 v[134:137], v179 offset:4096
	s_addk_i32 s11, 0x6000
	v_lshl_add_u64 v[138:139], v[176:177], 0, s[34:35]
	s_mov_b32 m0, s11
	s_nop 0
	global_load_lds_dwordx4 v[138:139], off
	v_mfma_f32_32x32x16_bf16 v[66:81], v[146:149], v[158:161], v[66:81]
	ds_read_b128 v[138:141], v179 offset:8192
	v_mfma_f32_32x32x16_bf16 v[18:33], v[146:149], v[172:175], v[18:33]
	v_mfma_f32_32x32x16_bf16 v[2:17], v[146:149], v[150:153], v[2:17]
	ds_read_b128 v[146:149], v179 offset:12288
	v_add_u32_e32 v176, s9, v170
	s_waitcnt lgkmcnt(4)
	v_mfma_f32_32x32x16_bf16 v[98:113], v[142:145], v[154:157], v[98:113]
	ds_read_b128 v[154:157], v176
	v_mfma_f32_32x32x16_bf16 v[82:97], v[142:145], v[158:161], v[82:97]
	ds_read_b128 v[158:161], v176 offset:4096
	v_mfma_f32_32x32x16_bf16 v[50:65], v[142:145], v[172:175], v[50:65]
	v_mfma_f32_32x32x16_bf16 v[34:49], v[142:145], v[150:153], v[34:49]
	v_add_u32_e32 v174, s10, v169
	ds_read_b128 v[142:145], v174
	s_waitcnt lgkmcnt(2)
	v_mfma_f32_32x32x16_bf16 v[114:129], v[154:157], v[130:133], v[114:129]
	ds_read_b128 v[150:153], v174 offset:4096
	v_mfma_f32_32x32x16_bf16 v[66:81], v[154:157], v[134:137], v[66:81]
	ds_read_b128 v[170:173], v174 offset:8192
	v_mfma_f32_32x32x16_bf16 v[18:33], v[154:157], v[138:141], v[18:33]
	v_mfma_f32_32x32x16_bf16 v[2:17], v[154:157], v[146:149], v[2:17]
	ds_read_b128 v[154:157], v174 offset:12288
	v_add_u32_e32 v175, s9, v169
	s_waitcnt lgkmcnt(4)
	v_mfma_f32_32x32x16_bf16 v[98:113], v[158:161], v[130:133], v[98:113]
	ds_read_b128 v[130:133], v175
	v_mfma_f32_32x32x16_bf16 v[82:97], v[158:161], v[134:137], v[82:97]
	ds_read_b128 v[134:137], v175 offset:4096
	v_mfma_f32_32x32x16_bf16 v[50:65], v[158:161], v[138:141], v[50:65]
	v_mfma_f32_32x32x16_bf16 v[34:49], v[158:161], v[146:149], v[34:49]
	s_waitcnt vmcnt(0)
	s_waitcnt lgkmcnt(0)
	s_barrier
	s_lshr_b32 s100, s0, 5
	s_lshl_b32 s100, s100, 3
	s_and_b32 s101, s0, 7
	s_or_b32 s100, s100, s101
	s_mul_i32 s100, s100, 0x100
	s_lshr_b32 s101, s0, 3
	s_and_b32 s101, s101, 3
	s_lshl_b32 s101, s101, 9
	v_lshrrev_b32_e32 v237, 2, v163
	v_and_b32_e32 v238, 3, v163
	v_add_u32_e32 v237, s100, v237
	v_lshlrev_b32_e32 v237, 11, v237
	v_lshl_add_u32 v237, v238, 7, v237
	v_add_u32_e32 v237, s101, v237
	global_load_dword v239, v237, s[46:47]
	v_add_u32_e32 v237, 0x40000, v237
	global_load_dword v239, v237, s[46:47]
	v_add_u32_e32 v168, s16, v168
	v_add_u32_e32 v167, s16, v167
	v_mfma_f32_32x32x16_bf16 v[114:129], v[130:133], v[142:145], v[114:129]
	ds_read_b128 v[138:141], v168
	v_mfma_f32_32x32x16_bf16 v[66:81], v[130:133], v[150:153], v[66:81]
	ds_read_b128 v[146:149], v168 offset:4096
	v_mfma_f32_32x32x16_bf16 v[18:33], v[130:133], v[170:173], v[18:33]
	ds_read_b128 v[158:161], v168 offset:8192
	v_mfma_f32_32x32x16_bf16 v[2:17], v[130:133], v[154:157], v[2:17]
	ds_read_b128 v[130:133], v168 offset:12288
	v_mfma_f32_32x32x16_bf16 v[98:113], v[134:137], v[142:145], v[98:113]
	ds_read_b128 v[142:145], v167
	v_mfma_f32_32x32x16_bf16 v[82:97], v[134:137], v[150:153], v[82:97]
	ds_read_b128 v[150:153], v167 offset:4096
	v_mfma_f32_32x32x16_bf16 v[50:65], v[134:137], v[170:173], v[50:65]
	v_mfma_f32_32x32x16_bf16 v[34:49], v[134:137], v[154:157], v[34:49]
	ds_read_b128 v[134:137], v0 offset:32768
	s_waitcnt lgkmcnt(2)
	v_mfma_f32_32x32x16_bf16 v[114:129], v[142:145], v[138:141], v[114:129]
	ds_read_b128 v[154:157], v0 offset:36864
	v_mfma_f32_32x32x16_bf16 v[66:81], v[142:145], v[146:149], v[66:81]
	ds_read_b128 v[168:171], v0 offset:40960
	v_mfma_f32_32x32x16_bf16 v[18:33], v[142:145], v[158:161], v[18:33]
	v_mfma_f32_32x32x16_bf16 v[2:17], v[142:145], v[130:133], v[2:17]
	ds_read_b128 v[142:145], v0 offset:45056
	s_waitcnt lgkmcnt(4)
; DI f32x16 mfma32(bf8 a, bf8 b, f32x16 c) { return __builtin_amdgcn_mfma_f32_32x32x16_bf16(a, b, c, 0, 0, 0); }
; template <int MB, class Epi>
; DI void gemm_tile(const u16* __restrict__ A, int lda, int row0, int Mrows, const u16* __restrict__ Bt, int ldb, int K, char* smem, Epi& epi, int rot) {
;     ...
; #pragma unroll
;     for (int nb = 0; nb < 2; ++nb)
; #pragma unroll
;       for (int mb = 0; mb < MB; ++mb) acc[nb][mb] = mfma32(bfr[1][nb], af[1][mb], acc[nb][mb]);
; #pragma unroll
;     for (int gk = 0; gk < 2 * MB; ++gk) {
;       __builtin_amdgcn_sched_group_barrier(0x008, 1, 0);
;       __builtin_amdgcn_sched_group_barrier(0x100, 1, 0);
;     }
;     __builtin_amdgcn_sched_barrier(0);
;   }
;   __syncthreads();
;   epi(acc, wm, wn, r, h);
; }
;   DI void operator()(f32x16 (&acc)[2][MB], int wm, int wn, int r, int h) {
;     u16* slab = ostage + (wm * 4 + wn) * (64 * 72);
;     const int lane = h * 32 + r;
; #pragma unroll
;     for (int mb = 0; mb < MB; ++mb) {
;       const int tokl = (mb & 1) * 32 + r;
; #pragma unroll
;       for (int nb = 0; nb < 2; ++nb)
; #pragma unroll
;         for (int ig = 0; ig < 4; ++ig) {
;           u32x2 o;
;           o.x = pack2(acc[nb][mb][ig * 4 + 0], acc[nb][mb][ig * 4 + 1]);
;           o.y = pack2(acc[nb][mb][ig * 4 + 2], acc[nb][mb][ig * 4 + 3]);
;           *(u32x2*)(slab + tokl * 72 + nb * 32 + ig * 8 + h * 4) = o;
;         }
;       if ((mb & 1) || mb == MB - 1) {
;         asm volatile("s_waitcnt lgkmcnt(0)" ::: "memory");
;         const int ntok = (mb & 1) ? 64 : 32;
;         const int R0 = row0 + wm * (32 * MB) + (mb >> 1) * 64;
; #pragma unroll
;         for (int j = 0; j < 8; ++j) {
;           const int rowl = (lane >> 3) + 8 * j, ch = lane & 7;
;           if (rowl < ntok) {
;             const u32x4 yv = *(const u32x4*)(slab + rowl * 72 + ch * 8);
;             const int R = R0 + rowl;
;             const int mi = (R < NLAT) ? (R >> 11) : 16;
;             const int col = n0 + wn * 64 + ch * 8;
;             const float* g = gate + (size_t)mi * 6144 + col;
;             const f32x4n g0 = *(const f32x4n*)(g), g1 = *(const f32x4n*)(g + 4);
;             _Float16* xp = X + (size_t)R * 1024 + col;
;             const h8 xv = *(const h8*)xp;
;             const float y[8] = {__uint_as_float(yv.x << 16), __uint_as_float(yv.x & 0xffff0000u), __uint_as_float(yv.y << 16), __uint_as_float(yv.y & 0xffff0000u),
	v_mfma_f32_32x32x16_bf16 v[98:113], v[150:153], v[138:141], v[98:113]
	ds_read_b128 v[138:141], v178 offset:32768
	v_mfma_f32_32x32x16_bf16 v[82:97], v[150:153], v[146:149], v[82:97]
	ds_read_b128 v[146:149], v178 offset:36864
	v_mfma_f32_32x32x16_bf16 v[50:65], v[150:153], v[158:161], v[50:65]
	v_mfma_f32_32x32x16_bf16 v[34:49], v[150:153], v[130:133], v[34:49]
	ds_read_b128 v[130:133], v179 offset:32768
	s_waitcnt lgkmcnt(2)
	v_mfma_f32_32x32x16_bf16 v[114:129], v[138:141], v[134:137], v[114:129]
	ds_read_b128 v[150:153], v179 offset:36864
	v_mfma_f32_32x32x16_bf16 v[66:81], v[138:141], v[154:157], v[66:81]
	ds_read_b128 v[158:161], v179 offset:40960
	v_mfma_f32_32x32x16_bf16 v[18:33], v[138:141], v[168:171], v[18:33]
	v_mfma_f32_32x32x16_bf16 v[2:17], v[138:141], v[142:145], v[2:17]
	ds_read_b128 v[138:141], v179 offset:45056
	s_waitcnt lgkmcnt(4)
	v_mfma_f32_32x32x16_bf16 v[98:113], v[146:149], v[134:137], v[98:113]
	ds_read_b128 v[134:137], v176 offset:32768
	v_mfma_f32_32x32x16_bf16 v[82:97], v[146:149], v[154:157], v[82:97]
	ds_read_b128 v[154:157], v176 offset:36864
	v_mfma_f32_32x32x16_bf16 v[50:65], v[146:149], v[168:171], v[50:65]
	v_mfma_f32_32x32x16_bf16 v[34:49], v[146:149], v[142:145], v[34:49]
	ds_read_b128 v[142:145], v174 offset:32768
	s_waitcnt lgkmcnt(2)
	v_mfma_f32_32x32x16_bf16 v[114:129], v[134:137], v[130:133], v[114:129]
	ds_read_b128 v[146:149], v174 offset:36864
	v_mfma_f32_32x32x16_bf16 v[66:81], v[134:137], v[150:153], v[66:81]
	ds_read_b128 v[168:171], v174 offset:40960
	v_mfma_f32_32x32x16_bf16 v[18:33], v[134:137], v[158:161], v[18:33]
	v_mfma_f32_32x32x16_bf16 v[2:17], v[134:137], v[138:141], v[2:17]
	ds_read_b128 v[134:137], v174 offset:45056
	s_waitcnt lgkmcnt(4)
	v_mfma_f32_32x32x16_bf16 v[98:113], v[154:157], v[130:133], v[98:113]
	ds_read_b128 v[130:133], v175 offset:32768
	v_mfma_f32_32x32x16_bf16 v[82:97], v[154:157], v[150:153], v[82:97]
	ds_read_b128 v[150:153], v175 offset:36864
	v_mfma_f32_32x32x16_bf16 v[50:65], v[154:157], v[158:161], v[50:65]
	v_mfma_f32_32x32x16_bf16 v[34:49], v[154:157], v[138:141], v[34:49]
	s_waitcnt lgkmcnt(1)
	v_mfma_f32_32x32x16_bf16 v[114:129], v[130:133], v[142:145], v[114:129]
	v_mfma_f32_32x32x16_bf16 v[66:81], v[130:133], v[146:149], v[66:81]
	v_mfma_f32_32x32x16_bf16 v[18:33], v[130:133], v[168:171], v[18:33]
	v_mfma_f32_32x32x16_bf16 v[2:17], v[130:133], v[134:137], v[2:17]
	s_waitcnt lgkmcnt(0)
	v_mfma_f32_32x32x16_bf16 v[98:113], v[150:153], v[142:145], v[98:113]
	v_mfma_f32_32x32x16_bf16 v[82:97], v[150:153], v[146:149], v[82:97]
	v_mfma_f32_32x32x16_bf16 v[50:65], v[150:153], v[168:171], v[50:65]
	v_mfma_f32_32x32x16_bf16 v[34:49], v[150:153], v[134:137], v[34:49]
	s_lshl_b32 s10, s8, 2
	s_or_b32 s10, s10, s3
	s_mulk_i32 s10, 0x2400
	v_lshl_or_b32 v0, v166, 3, s10
	v_lshlrev_b32_e32 v130, 3, v165
	v_and_b32_e32 v132, 56, v130
	v_mad_u32_u24 v130, v165, s78, v0
	v_cvt_pk_bf16_f32 v66, v66, v67
	v_cvt_pk_bf16_f32 v67, v68, v69
	v_cvt_pk_bf16_f32 v68, v70, v71
	v_cvt_pk_bf16_f32 v69, v72, v73
	v_add_u32_e32 v70, 0x1000, v130
	s_barrier
	ds_write2_b64 v70, v[66:67], v[68:69] offset0:64 offset1:66
	v_cvt_pk_bf16_f32 v66, v74, v75
	v_cvt_pk_bf16_f32 v67, v76, v77
	v_cvt_pk_bf16_f32 v68, v78, v79
	v_cvt_pk_bf16_f32 v69, v80, v81
	s_lshl_b32 s8, s8, 7
	ds_write2_b64 v70, v[66:67], v[68:69] offset0:68 offset1:70
	v_cvt_pk_bf16_f32 v66, v82, v83
	v_cvt_pk_bf16_f32 v67, v84, v85
	v_cvt_pk_bf16_f32 v68, v86, v87
	v_cvt_pk_bf16_f32 v69, v88, v89
	s_lshl_b32 s9, s36, 8
	v_bfe_u32 v131, v164, 3, 3
	s_lshl_b32 s3, s3, 6
	ds_write2_b64 v70, v[66:67], v[68:69] offset0:72 offset1:74
	v_cvt_pk_bf16_f32 v66, v90, v91
	v_cvt_pk_bf16_f32 v67, v92, v93
	v_cvt_pk_bf16_f32 v68, v94, v95
	v_cvt_pk_bf16_f32 v69, v96, v97
	s_add_i32 s2, s8, s2
	ds_write2_b64 v70, v[66:67], v[68:69] offset0:76 offset1:78
	v_or_b32_e32 v66, s2, v131
	s_or_b32 s3, s3, s9
	v_cvt_pk_bf16_f32 v114, v114, v115
	v_cvt_pk_bf16_f32 v115, v116, v117
	v_cvt_pk_bf16_f32 v116, v118, v119
	v_cvt_pk_bf16_f32 v117, v120, v121
	v_cvt_pk_bf16_f32 v98, v98, v99
	v_cvt_pk_bf16_f32 v99, v100, v101
	v_cvt_pk_bf16_f32 v100, v102, v103
	v_cvt_pk_bf16_f32 v101, v104, v105
	v_or_b32_e32 v68, s3, v132
	v_ashrrev_i32_e32 v67, 31, v66
	ds_write2_b64 v130, v[114:115], v[116:117] offset1:2
	v_cvt_pk_bf16_f32 v114, v122, v123
	v_cvt_pk_bf16_f32 v115, v124, v125
	v_cvt_pk_bf16_f32 v116, v126, v127
	v_cvt_pk_bf16_f32 v117, v128, v129
	ds_write2_b64 v130, v[98:99], v[100:101] offset0:8 offset1:10
	v_cvt_pk_bf16_f32 v98, v106, v107
	v_cvt_pk_bf16_f32 v99, v108, v109
	v_cvt_pk_bf16_f32 v100, v110, v111
	v_cvt_pk_bf16_f32 v101, v112, v113
	v_min_i32_e32 v0, 0x8000, v66
	v_ashrrev_i32_e32 v69, 31, v68
	v_lshlrev_b64 v[66:67], 11, v[66:67]
	ds_write2_b64 v130, v[114:115], v[116:117] offset0:4 offset1:6
	ds_write2_b64 v130, v[98:99], v[100:101] offset0:12 offset1:14
	v_lshl_add_u64 v[72:73], s[46:47], 0, v[66:67]
	v_lshlrev_b64 v[66:67], 1, v[68:69]
	s_waitcnt lgkmcnt(0)
	v_lshl_add_u64 v[96:97], v[72:73], 0, v[66:67]
	global_load_dwordx4 v[72:75], v[96:97], off
	v_ashrrev_i32_e32 v0, 11, v0
	v_readlane_b32 s8, v234, 4
	v_mul_hi_i32_i24_e32 v77, 0x6000, v0
	v_mul_i32_i24_e32 v76, 0x6000, v0
	v_readlane_b32 s9, v234, 5
	v_lshlrev_b64 v[68:69], 2, v[68:69]
	v_or_b32_e32 v71, 8, v131
	v_lshl_add_u64 v[76:77], s[8:9], 0, v[76:77]
	v_lshl_add_u64 v[80:81], v[76:77], 0, v[68:69]
	global_load_dwordx4 v[76:79], v[80:81], off
	v_or_b32_e32 v98, s2, v71
	global_load_dwordx4 v[80:83], v[80:81], off offset:16
	v_ashrrev_i32_e32 v99, 31, v98
	v_lshl_or_b32 v0, v132, 1, s10
	v_lshlrev_b64 v[84:85], 11, v[98:99]
	v_mad_u32_u24 v0, v131, s78, v0
	v_lshl_add_u64 v[84:85], s[46:47], 0, v[84:85]
	v_lshl_add_u64 v[100:101], v[84:85], 0, v[66:67]
	ds_read_b128 v[84:87], v0
	global_load_dwordx4 v[92:95], v[100:101], off
	ds_read_b128 v[88:91], v0 offset:1152
	v_cvt_pk_bf16_f32 v2, v2, v3
	v_cvt_pk_bf16_f32 v3, v4, v5
	s_waitcnt lgkmcnt(1)
; DI unsigned pack2(float a, float b) { f2 v = {a, b}; bf2 r = __builtin_convertvector(v, bf2); return __builtin_bit_cast(unsigned, r); }
;   DI void operator()(f32x16 (&acc)[2][MB], int wm, int wn, int r, int h) {
;     ...
;     for (int mb = 0; mb < MB; ++mb) {
;       const int tokl = (mb & 1) * 32 + r;
; #pragma unroll
;       for (int nb = 0; nb < 2; ++nb)
; #pragma unroll
;         for (int ig = 0; ig < 4; ++ig) {
;           u32x2 o;
;           o.x = pack2(acc[nb][mb][ig * 4 + 0], acc[nb][mb][ig * 4 + 1]);
;           o.y = pack2(acc[nb][mb][ig * 4 + 2], acc[nb][mb][ig * 4 + 3]);
;           *(u32x2*)(slab + tokl * 72 + nb * 32 + ig * 8 + h * 4) = o;
;         }
;       if ((mb & 1) || mb == MB - 1) {
;         asm volatile("s_waitcnt lgkmcnt(0)" ::: "memory");
;         const int ntok = (mb & 1) ? 64 : 32;
;         const int R0 = row0 + wm * (32 * MB) + (mb >> 1) * 64;
; #pragma unroll
;         for (int j = 0; j < 8; ++j) {
;           const int rowl = (lane >> 3) + 8 * j, ch = lane & 7;
;           if (rowl < ntok) {
;             const u32x4 yv = *(const u32x4*)(slab + rowl * 72 + ch * 8);
;             const int R = R0 + rowl;
;             const int mi = (R < NLAT) ? (R >> 11) : 16;
;             const int col = n0 + wn * 64 + ch * 8;
;             const float* g = gate + (size_t)mi * 6144 + col;
;             const f32x4n g0 = *(const f32x4n*)(g), g1 = *(const f32x4n*)(g + 4);
;             _Float16* xp = X + (size_t)R * 1024 + col;
;             const h8 xv = *(const h8*)xp;
;             const float y[8] = {__uint_as_float(yv.x << 16), __uint_as_float(yv.x & 0xffff0000u), __uint_as_float(yv.y << 16), __uint_as_float(yv.y & 0xffff0000u),
;                                 __uint_as_float(yv.z << 16), __uint_as_float(yv.z & 0xffff0000u), __uint_as_float(yv.w << 16), __uint_as_float(yv.w & 0xffff0000u)};
;             const float gg[8] = {g0.x, g0.y, g0.z, g0.w, g1.x, g1.y, g1.z, g1.w};
;             h8 o;
; #pragma unroll
;             for (int q = 0; q < 8; ++q) o[q] = (_Float16)(ALPHA * (float)xv[q] + gg[q] * y[q]);
;             *(h8*)xp = o;
;           }
;         }
	v_lshlrev_b32_e32 v104, 16, v84
	v_and_b32_e32 v105, 0xffff0000, v84
	v_cvt_pk_bf16_f32 v4, v6, v7
	v_cvt_pk_bf16_f32 v5, v8, v9
	v_cvt_pk_bf16_f32 v6, v10, v11
	v_cvt_pk_bf16_f32 v7, v12, v13
	v_cvt_pk_bf16_f32 v8, v14, v15
	v_cvt_pk_bf16_f32 v9, v16, v17
	v_cvt_pk_bf16_f32 v10, v34, v35
	v_cvt_pk_bf16_f32 v11, v36, v37
	v_cvt_pk_bf16_f32 v12, v38, v39
	v_cvt_pk_bf16_f32 v13, v40, v41
	v_cvt_pk_bf16_f32 v14, v42, v43
	v_cvt_pk_bf16_f32 v15, v44, v45
	v_cvt_pk_bf16_f32 v16, v46, v47
	v_cvt_pk_bf16_f32 v17, v48, v49
	v_cvt_pk_bf16_f32 v18, v18, v19
	v_cvt_pk_bf16_f32 v19, v20, v21
	v_cvt_pk_bf16_f32 v20, v22, v23
	v_cvt_pk_bf16_f32 v21, v24, v25
	v_cvt_pk_bf16_f32 v22, v26, v27
	v_cvt_pk_bf16_f32 v23, v28, v29
	v_cvt_pk_bf16_f32 v24, v30, v31
	v_cvt_pk_bf16_f32 v25, v32, v33
	v_cvt_pk_bf16_f32 v26, v50, v51
	v_cvt_pk_bf16_f32 v27, v52, v53
	v_cvt_pk_bf16_f32 v28, v54, v55
	v_cvt_pk_bf16_f32 v29, v56, v57
	v_cvt_pk_bf16_f32 v30, v58, v59
	v_cvt_pk_bf16_f32 v31, v60, v61
	v_cvt_pk_bf16_f32 v32, v62, v63
	v_cvt_pk_bf16_f32 v33, v64, v65
	s_waitcnt vmcnt(3)
	v_cvt_f32_f16_e32 v102, v72
	v_cvt_f32_f16_sdwa v103, v72 dst_sel:DWORD dst_unused:UNUSED_PAD src0_sel:WORD_1
	v_cvt_f32_f16_e32 v106, v73
	v_cvt_f32_f16_sdwa v107, v73 dst_sel:DWORD dst_unused:UNUSED_PAD src0_sel:WORD_1
	v_pk_mul_f32 v[102:103], v[102:103], s[30:31] op_sel_hi:[1,0]
	s_waitcnt vmcnt(2)
	v_pk_fma_f32 v[76:77], v[76:77], v[104:105], v[102:103]
	s_nop 0
	v_cvt_pk_f16_f32 v72, v76, v77
	v_lshlrev_b32_e32 v76, 16, v85
	v_and_b32_e32 v77, 0xffff0000, v85
	v_pk_mul_f32 v[84:85], v[106:107], s[30:31] op_sel_hi:[1,0]
	s_waitcnt lgkmcnt(0)
	v_lshlrev_b32_e32 v102, 16, v90
	v_pk_fma_f32 v[76:77], v[78:79], v[76:77], v[84:85]
	v_cvt_f32_f16_e32 v78, v74
	v_cvt_f32_f16_sdwa v79, v74 dst_sel:DWORD dst_unused:UNUSED_PAD src0_sel:WORD_1
	v_cvt_pk_f16_f32 v73, v76, v77
	v_lshlrev_b32_e32 v76, 16, v86
	v_and_b32_e32 v77, 0xffff0000, v86
	v_pk_mul_f32 v[78:79], v[78:79], s[30:31] op_sel_hi:[1,0]
	s_waitcnt vmcnt(0)
	v_cvt_f32_f16_e32 v104, v92
	v_pk_fma_f32 v[76:77], v[80:81], v[76:77], v[78:79]
	v_cvt_f32_f16_e32 v78, v75
	v_cvt_f32_f16_sdwa v79, v75 dst_sel:DWORD dst_unused:UNUSED_PAD src0_sel:WORD_1
	v_cvt_pk_f16_f32 v74, v76, v77
	v_lshlrev_b32_e32 v76, 16, v87
	v_and_b32_e32 v77, 0xffff0000, v87
	v_pk_mul_f32 v[78:79], v[78:79], s[30:31] op_sel_hi:[1,0]
	v_cvt_f32_f16_sdwa v105, v92 dst_sel:DWORD dst_unused:UNUSED_PAD src0_sel:WORD_1
	v_pk_fma_f32 v[76:77], v[82:83], v[76:77], v[78:79]
	v_cvt_f32_f16_e32 v92, v93
	v_cvt_pk_f16_f32 v75, v76, v77
	global_store_dwordx4 v[96:97], v[72:75], off
	v_cvt_f32_f16_sdwa v93, v93 dst_sel:DWORD dst_unused:UNUSED_PAD src0_sel:WORD_1
	v_cvt_f32_f16_e32 v106, v94
	v_min_i32_e32 v72, 0x8000, v98
	v_ashrrev_i32_e32 v72, 11, v72
	v_mul_hi_i32_i24_e32 v73, 0x6000, v72
	v_mul_i32_i24_e32 v72, 0x6000, v72
	v_lshl_add_u64 v[72:73], s[8:9], 0, v[72:73]
	v_lshl_add_u64 v[72:73], v[72:73], 0, v[68:69]
	global_load_dwordx4 v[74:77], v[72:73], off
	global_load_dwordx4 v[78:81], v[72:73], off offset:16
	v_or_b32_e32 v72, 16, v131
	v_or_b32_e32 v82, s2, v72
	v_min_i32_e32 v73, 0x8000, v82
	v_ashrrev_i32_e32 v83, 31, v82
	v_ashrrev_i32_e32 v73, 11, v73
	v_lshlrev_b64 v[82:83], 11, v[82:83]
	v_cvt_f32_f16_sdwa v107, v94 dst_sel:DWORD dst_unused:UNUSED_PAD src0_sel:WORD_1
	v_cvt_f32_f16_e32 v94, v95
	v_cvt_f32_f16_sdwa v95, v95 dst_sel:DWORD dst_unused:UNUSED_PAD src0_sel:WORD_1
	v_mul_hi_i32_i24_e32 v85, 0x6000, v73
	v_mul_i32_i24_e32 v84, 0x6000, v73
	v_lshl_add_u64 v[82:83], s[46:47], 0, v[82:83]
	v_lshl_add_u64 v[84:85], s[8:9], 0, v[84:85]
	v_lshl_add_u64 v[98:99], v[82:83], 0, v[66:67]
	v_lshl_add_u64 v[86:87], v[84:85], 0, v[68:69]
	global_load_dwordx4 v[82:85], v[98:99], off
	v_lshlrev_b32_e32 v96, 16, v88
	v_and_b32_e32 v97, 0xffff0000, v88
	v_lshlrev_b32_e32 v88, 16, v89
	v_and_b32_e32 v89, 0xffff0000, v89
	v_and_b32_e32 v103, 0xffff0000, v90
	v_lshlrev_b32_e32 v90, 16, v91
	v_and_b32_e32 v91, 0xffff0000, v91
	v_pk_mul_f32 v[104:105], v[104:105], s[30:31] op_sel_hi:[1,0]
	v_pk_mul_f32 v[92:93], v[92:93], s[30:31] op_sel_hi:[1,0]
	v_pk_mul_f32 v[106:107], v[106:107], s[30:31] op_sel_hi:[1,0]
	v_pk_mul_f32 v[94:95], v[94:95], s[30:31] op_sel_hi:[1,0]
	v_or_b32_e32 v73, 24, v131
	s_waitcnt vmcnt(2)
	v_pk_fma_f32 v[74:75], v[74:75], v[96:97], v[104:105]
	v_pk_fma_f32 v[76:77], v[76:77], v[88:89], v[92:93]
	s_waitcnt vmcnt(1)
	v_pk_fma_f32 v[78:79], v[78:79], v[102:103], v[106:107]
	v_pk_fma_f32 v[80:81], v[80:81], v[90:91], v[94:95]
	v_cvt_pk_f16_f32 v74, v74, v75
	v_cvt_pk_f16_f32 v75, v76, v77
	v_cvt_pk_f16_f32 v76, v78, v79
	v_cvt_pk_f16_f32 v77, v80, v81
	global_store_dwordx4 v[100:101], v[74:77], off
	global_load_dwordx4 v[74:77], v[86:87], off
	s_waitcnt vmcnt(2)
	v_cvt_f32_f16_e32 v108, v82
	global_load_dwordx4 v[78:81], v[86:87], off offset:16
	v_or_b32_e32 v86, s2, v73
	v_min_i32_e32 v88, 0x8000, v86
	v_ashrrev_i32_e32 v87, 31, v86
	v_ashrrev_i32_e32 v88, 11, v88
	v_lshlrev_b64 v[86:87], 11, v[86:87]
	v_mul_hi_i32_i24_e32 v89, 0x6000, v88
	v_mul_i32_i24_e32 v88, 0x6000, v88
	v_lshl_add_u64 v[90:91], s[46:47], 0, v[86:87]
	v_lshl_add_u64 v[92:93], s[8:9], 0, v[88:89]
	ds_read_b128 v[86:89], v0 offset:2304
	v_cvt_f32_f16_sdwa v109, v82 dst_sel:DWORD dst_unused:UNUSED_PAD src0_sel:WORD_1
	v_cvt_f32_f16_e32 v82, v83
	v_cvt_f32_f16_sdwa v83, v83 dst_sel:DWORD dst_unused:UNUSED_PAD src0_sel:WORD_1
	v_cvt_f32_f16_e32 v110, v84
	v_cvt_f32_f16_sdwa v111, v84 dst_sel:DWORD dst_unused:UNUSED_PAD src0_sel:WORD_1
	v_cvt_f32_f16_e32 v84, v85
	v_cvt_f32_f16_sdwa v85, v85 dst_sel:DWORD dst_unused:UNUSED_PAD src0_sel:WORD_1
	v_lshl_add_u64 v[100:101], v[90:91], 0, v[66:67]
	global_load_dwordx4 v[94:97], v[100:101], off
	s_waitcnt lgkmcnt(0)
;   DI void operator()(f32x16 (&acc)[2][MB], int wm, int wn, int r, int h) {
;     ...
;         for (int j = 0; j < 8; ++j) {
;           const int rowl = (lane >> 3) + 8 * j, ch = lane & 7;
;           if (rowl < ntok) {
;             const u32x4 yv = *(const u32x4*)(slab + rowl * 72 + ch * 8);
;             const int R = R0 + rowl;
;             const int mi = (R < NLAT) ? (R >> 11) : 16;
;             const int col = n0 + wn * 64 + ch * 8;
;             const float* g = gate + (size_t)mi * 6144 + col;
;             const f32x4n g0 = *(const f32x4n*)(g), g1 = *(const f32x4n*)(g + 4);
;             _Float16* xp = X + (size_t)R * 1024 + col;
;             const h8 xv = *(const h8*)xp;
;             const float y[8] = {__uint_as_float(yv.x << 16), __uint_as_float(yv.x & 0xffff0000u), __uint_as_float(yv.y << 16), __uint_as_float(yv.y & 0xffff0000u),
;                                 __uint_as_float(yv.z << 16), __uint_as_float(yv.z & 0xffff0000u), __uint_as_float(yv.w << 16), __uint_as_float(yv.w & 0xffff0000u)};
;             const float gg[8] = {g0.x, g0.y, g0.z, g0.w, g1.x, g1.y, g1.z, g1.w};
;             h8 o;
; #pragma unroll
;             for (int q = 0; q < 8; ++q) o[q] = (_Float16)(ALPHA * (float)xv[q] + gg[q] * y[q]);
;             *(h8*)xp = o;
;           }
;         }
	v_lshlrev_b32_e32 v104, 16, v86
	v_and_b32_e32 v105, 0xffff0000, v86
	v_lshlrev_b32_e32 v86, 16, v87
	v_and_b32_e32 v87, 0xffff0000, v87
	v_lshlrev_b32_e32 v106, 16, v88
	v_and_b32_e32 v107, 0xffff0000, v88
	v_lshlrev_b32_e32 v88, 16, v89
	v_and_b32_e32 v89, 0xffff0000, v89
	v_pk_mul_f32 v[108:109], v[108:109], s[30:31] op_sel_hi:[1,0]
	v_pk_mul_f32 v[82:83], v[82:83], s[30:31] op_sel_hi:[1,0]
	v_pk_mul_f32 v[110:111], v[110:111], s[30:31] op_sel_hi:[1,0]
	v_pk_mul_f32 v[84:85], v[84:85], s[30:31] op_sel_hi:[1,0]
	v_lshl_add_u64 v[102:103], v[92:93], 0, v[68:69]
	ds_read_b128 v[90:93], v0 offset:3456
	s_waitcnt vmcnt(2)
	v_pk_fma_f32 v[74:75], v[74:75], v[104:105], v[108:109]
	v_pk_fma_f32 v[76:77], v[76:77], v[86:87], v[82:83]
	v_cvt_pk_f16_f32 v74, v74, v75
	v_cvt_pk_f16_f32 v75, v76, v77
	s_waitcnt lgkmcnt(0)
	v_lshlrev_b32_e32 v104, 16, v92
	v_and_b32_e32 v105, 0xffff0000, v92
	v_lshlrev_b32_e32 v92, 16, v93
	v_and_b32_e32 v93, 0xffff0000, v93
	s_waitcnt vmcnt(1)
	v_pk_fma_f32 v[78:79], v[78:79], v[106:107], v[110:111]
	v_pk_fma_f32 v[80:81], v[80:81], v[88:89], v[84:85]
	v_cvt_pk_f16_f32 v76, v78, v79
	v_cvt_pk_f16_f32 v77, v80, v81
	global_store_dwordx4 v[98:99], v[74:77], off
	global_load_dwordx4 v[76:79], v[102:103], off
	v_lshlrev_b32_e32 v98, 16, v90
	global_load_dwordx4 v[80:83], v[102:103], off offset:16
	v_or_b32_e32 v74, 32, v131
	v_or_b32_e32 v84, s2, v74
	v_min_i32_e32 v75, 0x8000, v84
	v_ashrrev_i32_e32 v85, 31, v84
	v_ashrrev_i32_e32 v75, 11, v75
	v_lshlrev_b64 v[84:85], 11, v[84:85]
	v_mul_hi_i32_i24_e32 v87, 0x6000, v75
	v_mul_i32_i24_e32 v86, 0x6000, v75
	v_lshl_add_u64 v[84:85], s[46:47], 0, v[84:85]
	v_lshl_add_u64 v[86:87], s[8:9], 0, v[86:87]
	v_lshl_add_u64 v[102:103], v[84:85], 0, v[66:67]
	s_waitcnt vmcnt(3)
	v_cvt_f32_f16_e32 v106, v94
	v_cvt_f32_f16_sdwa v107, v94 dst_sel:DWORD dst_unused:UNUSED_PAD src0_sel:WORD_1
	v_cvt_f32_f16_e32 v94, v95
	v_cvt_f32_f16_sdwa v95, v95 dst_sel:DWORD dst_unused:UNUSED_PAD src0_sel:WORD_1
	v_cvt_f32_f16_e32 v108, v96
	v_cvt_f32_f16_sdwa v109, v96 dst_sel:DWORD dst_unused:UNUSED_PAD src0_sel:WORD_1
	v_cvt_f32_f16_e32 v96, v97
	v_cvt_f32_f16_sdwa v97, v97 dst_sel:DWORD dst_unused:UNUSED_PAD src0_sel:WORD_1
	v_lshl_add_u64 v[88:89], v[86:87], 0, v[68:69]
	global_load_dwordx4 v[84:87], v[102:103], off
	v_and_b32_e32 v99, 0xffff0000, v90
	v_lshlrev_b32_e32 v90, 16, v91
	v_and_b32_e32 v91, 0xffff0000, v91
	v_pk_mul_f32 v[106:107], v[106:107], s[30:31] op_sel_hi:[1,0]
	v_pk_mul_f32 v[94:95], v[94:95], s[30:31] op_sel_hi:[1,0]
	v_pk_mul_f32 v[108:109], v[108:109], s[30:31] op_sel_hi:[1,0]
	v_pk_mul_f32 v[96:97], v[96:97], s[30:31] op_sel_hi:[1,0]
	v_or_b32_e32 v75, 40, v131
	s_waitcnt vmcnt(2)
	v_pk_fma_f32 v[76:77], v[76:77], v[98:99], v[106:107]
	v_pk_fma_f32 v[78:79], v[78:79], v[90:91], v[94:95]
	s_waitcnt vmcnt(1)
	v_pk_fma_f32 v[80:81], v[80:81], v[104:105], v[108:109]
	v_pk_fma_f32 v[82:83], v[82:83], v[92:93], v[96:97]
	v_cvt_pk_f16_f32 v76, v76, v77
	v_cvt_pk_f16_f32 v77, v78, v79
	v_cvt_pk_f16_f32 v78, v80, v81
	v_cvt_pk_f16_f32 v79, v82, v83
	global_store_dwordx4 v[100:101], v[76:79], off
	global_load_dwordx4 v[76:79], v[88:89], off
	s_waitcnt vmcnt(2)
	v_cvt_f32_f16_e32 v110, v84
	global_load_dwordx4 v[80:83], v[88:89], off offset:16
	v_or_b32_e32 v88, s2, v75
	v_min_i32_e32 v90, 0x8000, v88
	v_ashrrev_i32_e32 v89, 31, v88
	v_ashrrev_i32_e32 v90, 11, v90
	v_lshlrev_b64 v[88:89], 11, v[88:89]
	v_mul_hi_i32_i24_e32 v91, 0x6000, v90
	v_mul_i32_i24_e32 v90, 0x6000, v90
	v_lshl_add_u64 v[92:93], s[46:47], 0, v[88:89]
	v_lshl_add_u64 v[94:95], s[8:9], 0, v[90:91]
	ds_read_b128 v[88:91], v0 offset:4608
	v_cvt_f32_f16_sdwa v111, v84 dst_sel:DWORD dst_unused:UNUSED_PAD src0_sel:WORD_1
	v_cvt_f32_f16_e32 v84, v85
	v_cvt_f32_f16_sdwa v85, v85 dst_sel:DWORD dst_unused:UNUSED_PAD src0_sel:WORD_1
	v_cvt_f32_f16_e32 v112, v86
	v_cvt_f32_f16_sdwa v113, v86 dst_sel:DWORD dst_unused:UNUSED_PAD src0_sel:WORD_1
	v_cvt_f32_f16_e32 v86, v87
	v_cvt_f32_f16_sdwa v87, v87 dst_sel:DWORD dst_unused:UNUSED_PAD src0_sel:WORD_1
	v_lshl_add_u64 v[100:101], v[92:93], 0, v[66:67]
	global_load_dwordx4 v[96:99], v[100:101], off
	s_waitcnt lgkmcnt(0)
	v_lshlrev_b32_e32 v106, 16, v88
	v_and_b32_e32 v107, 0xffff0000, v88
	v_lshlrev_b32_e32 v88, 16, v89
	v_and_b32_e32 v89, 0xffff0000, v89
	v_lshlrev_b32_e32 v108, 16, v90
	v_and_b32_e32 v109, 0xffff0000, v90
	v_lshlrev_b32_e32 v90, 16, v91
	v_and_b32_e32 v91, 0xffff0000, v91
	v_pk_mul_f32 v[110:111], v[110:111], s[30:31] op_sel_hi:[1,0]
	v_pk_mul_f32 v[84:85], v[84:85], s[30:31] op_sel_hi:[1,0]
	v_pk_mul_f32 v[112:113], v[112:113], s[30:31] op_sel_hi:[1,0]
	v_pk_mul_f32 v[86:87], v[86:87], s[30:31] op_sel_hi:[1,0]
	v_lshl_add_u64 v[104:105], v[94:95], 0, v[68:69]
	ds_read_b128 v[92:95], v0 offset:5760
	s_waitcnt vmcnt(2)
	v_pk_fma_f32 v[76:77], v[76:77], v[106:107], v[110:111]
	v_pk_fma_f32 v[78:79], v[78:79], v[88:89], v[84:85]
	v_cvt_pk_f16_f32 v76, v76, v77
	v_cvt_pk_f16_f32 v77, v78, v79
	s_waitcnt lgkmcnt(0)
	v_lshlrev_b32_e32 v106, 16, v94
	v_and_b32_e32 v107, 0xffff0000, v94
	v_lshlrev_b32_e32 v94, 16, v95
	v_and_b32_e32 v95, 0xffff0000, v95
	s_waitcnt vmcnt(1)
	v_pk_fma_f32 v[80:81], v[80:81], v[108:109], v[112:113]
	v_pk_fma_f32 v[82:83], v[82:83], v[90:91], v[86:87]
	v_cvt_pk_f16_f32 v78, v80, v81
	v_cvt_pk_f16_f32 v79, v82, v83
	global_store_dwordx4 v[102:103], v[76:79], off
	global_load_dwordx4 v[78:81], v[104:105], off
	s_waitcnt vmcnt(2)
; DI unsigned pack2(float a, float b) { f2 v = {a, b}; bf2 r = __builtin_convertvector(v, bf2); return __builtin_bit_cast(unsigned, r); }
;   DI void operator()(f32x16 (&acc)[2][MB], int wm, int wn, int r, int h) {
;     ...
;     for (int mb = 0; mb < MB; ++mb) {
;       const int tokl = (mb & 1) * 32 + r;
; #pragma unroll
;       for (int nb = 0; nb < 2; ++nb)
; #pragma unroll
;         for (int ig = 0; ig < 4; ++ig) {
;           u32x2 o;
;           o.x = pack2(acc[nb][mb][ig * 4 + 0], acc[nb][mb][ig * 4 + 1]);
;           o.y = pack2(acc[nb][mb][ig * 4 + 2], acc[nb][mb][ig * 4 + 3]);
;           *(u32x2*)(slab + tokl * 72 + nb * 32 + ig * 8 + h * 4) = o;
;         }
;       if ((mb & 1) || mb == MB - 1) {
;         asm volatile("s_waitcnt lgkmcnt(0)" ::: "memory");
;         const int ntok = (mb & 1) ? 64 : 32;
;         const int R0 = row0 + wm * (32 * MB) + (mb >> 1) * 64;
; #pragma unroll
;         for (int j = 0; j < 8; ++j) {
;           const int rowl = (lane >> 3) + 8 * j, ch = lane & 7;
;           if (rowl < ntok) {
;             const u32x4 yv = *(const u32x4*)(slab + rowl * 72 + ch * 8);
;             const int R = R0 + rowl;
;             const int mi = (R < NLAT) ? (R >> 11) : 16;
;             const int col = n0 + wn * 64 + ch * 8;
;             const float* g = gate + (size_t)mi * 6144 + col;
;             const f32x4n g0 = *(const f32x4n*)(g), g1 = *(const f32x4n*)(g + 4);
;             _Float16* xp = X + (size_t)R * 1024 + col;
;             const h8 xv = *(const h8*)xp;
;             const float y[8] = {__uint_as_float(yv.x << 16), __uint_as_float(yv.x & 0xffff0000u), __uint_as_float(yv.y << 16), __uint_as_float(yv.y & 0xffff0000u),
;                                 __uint_as_float(yv.z << 16), __uint_as_float(yv.z & 0xffff0000u), __uint_as_float(yv.w << 16), __uint_as_float(yv.w & 0xffff0000u)};
;             const float gg[8] = {g0.x, g0.y, g0.z, g0.w, g1.x, g1.y, g1.z, g1.w};
;             h8 o;
; #pragma unroll
;             for (int q = 0; q < 8; ++q) o[q] = (_Float16)(ALPHA * (float)xv[q] + gg[q] * y[q]);
;             *(h8*)xp = o;
;           }
;         }
	v_cvt_f32_f16_e32 v108, v96
	global_load_dwordx4 v[82:85], v[104:105], off offset:16
	v_or_b32_e32 v76, 48, v131
	v_or_b32_e32 v86, s2, v76
	v_min_i32_e32 v77, 0x8000, v86
	v_ashrrev_i32_e32 v87, 31, v86
	v_ashrrev_i32_e32 v77, 11, v77
	v_lshlrev_b64 v[86:87], 11, v[86:87]
	v_cvt_f32_f16_sdwa v109, v96 dst_sel:DWORD dst_unused:UNUSED_PAD src0_sel:WORD_1
	v_cvt_f32_f16_e32 v96, v97
	v_cvt_f32_f16_sdwa v97, v97 dst_sel:DWORD dst_unused:UNUSED_PAD src0_sel:WORD_1
	v_cvt_f32_f16_e32 v110, v98
	v_cvt_f32_f16_sdwa v111, v98 dst_sel:DWORD dst_unused:UNUSED_PAD src0_sel:WORD_1
	v_cvt_f32_f16_e32 v98, v99
	v_cvt_f32_f16_sdwa v99, v99 dst_sel:DWORD dst_unused:UNUSED_PAD src0_sel:WORD_1
	v_mul_hi_i32_i24_e32 v89, 0x6000, v77
	v_mul_i32_i24_e32 v88, 0x6000, v77
	v_lshl_add_u64 v[86:87], s[46:47], 0, v[86:87]
	v_lshl_add_u64 v[88:89], s[8:9], 0, v[88:89]
	v_lshl_add_u64 v[102:103], v[86:87], 0, v[66:67]
	v_lshl_add_u64 v[90:91], v[88:89], 0, v[68:69]
	global_load_dwordx4 v[86:89], v[102:103], off
	v_lshlrev_b32_e32 v104, 16, v92
	v_and_b32_e32 v105, 0xffff0000, v92
	v_lshlrev_b32_e32 v92, 16, v93
	v_and_b32_e32 v93, 0xffff0000, v93
	v_pk_mul_f32 v[108:109], v[108:109], s[30:31] op_sel_hi:[1,0]
	v_pk_mul_f32 v[96:97], v[96:97], s[30:31] op_sel_hi:[1,0]
	v_pk_mul_f32 v[110:111], v[110:111], s[30:31] op_sel_hi:[1,0]
	v_pk_mul_f32 v[98:99], v[98:99], s[30:31] op_sel_hi:[1,0]
	v_or_b32_e32 v77, 56, v131
	s_waitcnt vmcnt(2)
	v_pk_fma_f32 v[78:79], v[78:79], v[104:105], v[108:109]
	v_pk_fma_f32 v[80:81], v[80:81], v[92:93], v[96:97]
	v_cvt_pk_f16_f32 v78, v78, v79
	v_cvt_pk_f16_f32 v79, v80, v81
	s_waitcnt vmcnt(1)
	v_pk_fma_f32 v[82:83], v[82:83], v[106:107], v[110:111]
	v_pk_fma_f32 v[84:85], v[84:85], v[94:95], v[98:99]
	v_cvt_pk_f16_f32 v80, v82, v83
	v_cvt_pk_f16_f32 v81, v84, v85
	global_store_dwordx4 v[100:101], v[78:81], off
	global_load_dwordx4 v[78:81], v[90:91], off
	s_waitcnt vmcnt(2)
	v_cvt_f32_f16_e32 v112, v86
	global_load_dwordx4 v[82:85], v[90:91], off offset:16
	v_or_b32_e32 v90, s2, v77
	v_min_i32_e32 v92, 0x8000, v90
	v_ashrrev_i32_e32 v91, 31, v90
	v_ashrrev_i32_e32 v92, 11, v92
	v_lshlrev_b64 v[90:91], 11, v[90:91]
	v_mul_hi_i32_i24_e32 v93, 0x6000, v92
	v_mul_i32_i24_e32 v92, 0x6000, v92
	v_lshl_add_u64 v[94:95], s[46:47], 0, v[90:91]
	v_lshl_add_u64 v[96:97], s[8:9], 0, v[92:93]
	ds_read_b128 v[90:93], v0 offset:6912
	v_cvt_f32_f16_sdwa v113, v86 dst_sel:DWORD dst_unused:UNUSED_PAD src0_sel:WORD_1
	v_cvt_f32_f16_e32 v86, v87
	v_cvt_f32_f16_sdwa v87, v87 dst_sel:DWORD dst_unused:UNUSED_PAD src0_sel:WORD_1
	v_cvt_f32_f16_e32 v114, v88
	v_cvt_f32_f16_sdwa v115, v88 dst_sel:DWORD dst_unused:UNUSED_PAD src0_sel:WORD_1
	v_cvt_f32_f16_e32 v88, v89
	v_cvt_f32_f16_sdwa v89, v89 dst_sel:DWORD dst_unused:UNUSED_PAD src0_sel:WORD_1
	v_lshl_add_u64 v[104:105], v[94:95], 0, v[66:67]
	global_load_dwordx4 v[98:101], v[104:105], off
	s_waitcnt lgkmcnt(0)
	v_lshlrev_b32_e32 v108, 16, v90
	v_and_b32_e32 v109, 0xffff0000, v90
	v_lshlrev_b32_e32 v90, 16, v91
	v_and_b32_e32 v91, 0xffff0000, v91
	v_lshlrev_b32_e32 v110, 16, v92
	v_and_b32_e32 v111, 0xffff0000, v92
	v_lshlrev_b32_e32 v92, 16, v93
	v_and_b32_e32 v93, 0xffff0000, v93
	v_pk_mul_f32 v[112:113], v[112:113], s[30:31] op_sel_hi:[1,0]
	v_pk_mul_f32 v[86:87], v[86:87], s[30:31] op_sel_hi:[1,0]
	v_pk_mul_f32 v[114:115], v[114:115], s[30:31] op_sel_hi:[1,0]
	v_pk_mul_f32 v[88:89], v[88:89], s[30:31] op_sel_hi:[1,0]
	v_lshl_add_u64 v[106:107], v[96:97], 0, v[68:69]
	ds_read_b128 v[94:97], v0 offset:8064
	ds_write2_b64 v70, v[10:11], v[12:13] offset0:72 offset1:74
	ds_write2_b64 v70, v[14:15], v[16:17] offset0:76 offset1:78
	s_add_i32 s2, s2, 64
	v_or_b32_e32 v34, s2, v131
	ds_write2_b64 v70, v[2:3], v[4:5] offset0:64 offset1:66
	ds_write2_b64 v70, v[6:7], v[8:9] offset0:68 offset1:70
	s_waitcnt lgkmcnt(4)
	v_lshlrev_b32_e32 v2, 16, v94
	v_and_b32_e32 v3, 0xffff0000, v94
	v_lshlrev_b32_e32 v4, 16, v95
	v_and_b32_e32 v5, 0xffff0000, v95
	v_lshlrev_b32_e32 v6, 16, v96
	v_and_b32_e32 v7, 0xffff0000, v96
	v_lshlrev_b32_e32 v8, 16, v97
	v_and_b32_e32 v9, 0xffff0000, v97
	v_ashrrev_i32_e32 v35, 31, v34
	v_lshlrev_b64 v[36:37], 11, v[34:35]
	v_lshl_add_u64 v[36:37], s[46:47], 0, v[36:37]
	ds_write2_b64 v130, v[18:19], v[20:21] offset1:2
	ds_write2_b64 v130, v[22:23], v[24:25] offset0:4 offset1:6
	ds_write2_b64 v130, v[26:27], v[28:29] offset0:8 offset1:10
	ds_write2_b64 v130, v[30:31], v[32:33] offset0:12 offset1:14
	v_lshl_add_u64 v[36:37], v[36:37], 0, v[66:67]
	s_waitcnt vmcnt(2)
	v_pk_fma_f32 v[78:79], v[78:79], v[108:109], v[112:113]
	v_pk_fma_f32 v[80:81], v[80:81], v[90:91], v[86:87]
	v_cvt_pk_f16_f32 v78, v78, v79
	v_cvt_pk_f16_f32 v79, v80, v81
	s_waitcnt vmcnt(1)
	v_pk_fma_f32 v[82:83], v[82:83], v[110:111], v[114:115]
	v_pk_fma_f32 v[84:85], v[84:85], v[92:93], v[88:89]
	v_cvt_pk_f16_f32 v80, v82, v83
	v_cvt_pk_f16_f32 v81, v84, v85
	global_store_dwordx4 v[102:103], v[78:81], off
	global_load_dwordx4 v[78:81], v[106:107], off
	s_waitcnt vmcnt(2)
	v_cvt_f32_f16_e32 v10, v98
	global_load_dwordx4 v[82:85], v[106:107], off offset:16
	v_cvt_f32_f16_sdwa v11, v98 dst_sel:DWORD dst_unused:UNUSED_PAD src0_sel:WORD_1
	v_cvt_f32_f16_e32 v12, v99
	v_cvt_f32_f16_sdwa v13, v99 dst_sel:DWORD dst_unused:UNUSED_PAD src0_sel:WORD_1
	v_cvt_f32_f16_e32 v14, v100
	v_cvt_f32_f16_sdwa v15, v100 dst_sel:DWORD dst_unused:UNUSED_PAD src0_sel:WORD_1
	v_cvt_f32_f16_e32 v16, v101
	v_cvt_f32_f16_sdwa v17, v101 dst_sel:DWORD dst_unused:UNUSED_PAD src0_sel:WORD_1
	v_pk_mul_f32 v[10:11], v[10:11], s[30:31] op_sel_hi:[1,0]
	v_pk_mul_f32 v[12:13], v[12:13], s[30:31] op_sel_hi:[1,0]
	v_pk_mul_f32 v[14:15], v[14:15], s[30:31] op_sel_hi:[1,0]
	v_pk_mul_f32 v[16:17], v[16:17], s[30:31] op_sel_hi:[1,0]
	s_waitcnt vmcnt(1)
;   DI void operator()(f32x16 (&acc)[2][MB], int wm, int wn, int r, int h) {
;     ...
;         for (int j = 0; j < 8; ++j) {
;           const int rowl = (lane >> 3) + 8 * j, ch = lane & 7;
;           if (rowl < ntok) {
;             const u32x4 yv = *(const u32x4*)(slab + rowl * 72 + ch * 8);
;             const int R = R0 + rowl;
;             const int mi = (R < NLAT) ? (R >> 11) : 16;
;             const int col = n0 + wn * 64 + ch * 8;
;             const float* g = gate + (size_t)mi * 6144 + col;
;             const f32x4n g0 = *(const f32x4n*)(g), g1 = *(const f32x4n*)(g + 4);
;             _Float16* xp = X + (size_t)R * 1024 + col;
;             const h8 xv = *(const h8*)xp;
;             const float y[8] = {__uint_as_float(yv.x << 16), __uint_as_float(yv.x & 0xffff0000u), __uint_as_float(yv.y << 16), __uint_as_float(yv.y & 0xffff0000u),
;                                 __uint_as_float(yv.z << 16), __uint_as_float(yv.z & 0xffff0000u), __uint_as_float(yv.w << 16), __uint_as_float(yv.w & 0xffff0000u)};
;             const float gg[8] = {g0.x, g0.y, g0.z, g0.w, g1.x, g1.y, g1.z, g1.w};
;             h8 o;
; #pragma unroll
;             for (int q = 0; q < 8; ++q) o[q] = (_Float16)(ALPHA * (float)xv[q] + gg[q] * y[q]);
;             *(h8*)xp = o;
;           }
;         }
	v_pk_fma_f32 v[2:3], v[78:79], v[2:3], v[10:11]
	v_pk_fma_f32 v[4:5], v[80:81], v[4:5], v[12:13]
	v_cvt_pk_f16_f32 v2, v2, v3
	v_cvt_pk_f16_f32 v3, v4, v5
	s_waitcnt vmcnt(0)
	v_pk_fma_f32 v[6:7], v[82:83], v[6:7], v[14:15]
	v_pk_fma_f32 v[8:9], v[84:85], v[8:9], v[16:17]
	v_cvt_pk_f16_f32 v4, v6, v7
	v_cvt_pk_f16_f32 v5, v8, v9
	global_store_dwordx4 v[104:105], v[2:5], off
	s_waitcnt lgkmcnt(0)
	global_load_dwordx4 v[2:5], v[36:37], off
	v_min_i32_e32 v6, 0x8000, v34
	v_ashrrev_i32_e32 v6, 11, v6
	v_mul_hi_i32_i24_e32 v7, 0x6000, v6
	v_mul_i32_i24_e32 v6, 0x6000, v6
	v_lshl_add_u64 v[6:7], s[8:9], 0, v[6:7]
	v_lshl_add_u64 v[10:11], v[6:7], 0, v[68:69]
	global_load_dwordx4 v[6:9], v[10:11], off
	v_or_b32_e32 v14, s2, v71
	global_load_dwordx4 v[10:13], v[10:11], off offset:16
	v_min_i32_e32 v16, 0x8000, v14
	v_ashrrev_i32_e32 v15, 31, v14
	v_ashrrev_i32_e32 v16, 11, v16
	v_lshlrev_b64 v[14:15], 11, v[14:15]
	v_mul_hi_i32_i24_e32 v17, 0x6000, v16
	v_mul_i32_i24_e32 v16, 0x6000, v16
	v_lshl_add_u64 v[18:19], s[46:47], 0, v[14:15]
	v_lshl_add_u64 v[20:21], s[8:9], 0, v[16:17]
	ds_read_b128 v[14:17], v0
	v_lshl_add_u64 v[26:27], v[18:19], 0, v[66:67]
	global_load_dwordx4 v[22:25], v[26:27], off
	v_lshl_add_u64 v[28:29], v[20:21], 0, v[68:69]
	ds_read_b128 v[18:21], v0 offset:1152
	s_waitcnt lgkmcnt(1)
	v_lshlrev_b32_e32 v30, 16, v14
	v_and_b32_e32 v31, 0xffff0000, v14
	v_lshlrev_b32_e32 v14, 16, v15
	v_and_b32_e32 v15, 0xffff0000, v15
	v_lshlrev_b32_e32 v32, 16, v16
	v_and_b32_e32 v33, 0xffff0000, v16
	v_lshlrev_b32_e32 v16, 16, v17
	v_and_b32_e32 v17, 0xffff0000, v17
	s_waitcnt vmcnt(3)
	v_cvt_f32_f16_e32 v34, v2
	v_cvt_f32_f16_sdwa v35, v2 dst_sel:DWORD dst_unused:UNUSED_PAD src0_sel:WORD_1
	v_cvt_f32_f16_e32 v2, v3
	v_cvt_f32_f16_sdwa v3, v3 dst_sel:DWORD dst_unused:UNUSED_PAD src0_sel:WORD_1
	v_cvt_f32_f16_e32 v38, v4
	v_cvt_f32_f16_sdwa v39, v4 dst_sel:DWORD dst_unused:UNUSED_PAD src0_sel:WORD_1
	v_cvt_f32_f16_e32 v4, v5
	v_cvt_f32_f16_sdwa v5, v5 dst_sel:DWORD dst_unused:UNUSED_PAD src0_sel:WORD_1
	v_pk_mul_f32 v[34:35], v[34:35], s[30:31] op_sel_hi:[1,0]
	v_pk_mul_f32 v[2:3], v[2:3], s[30:31] op_sel_hi:[1,0]
	v_pk_mul_f32 v[38:39], v[38:39], s[30:31] op_sel_hi:[1,0]
	v_pk_mul_f32 v[4:5], v[4:5], s[30:31] op_sel_hi:[1,0]
	s_waitcnt vmcnt(2)
	v_pk_fma_f32 v[6:7], v[6:7], v[30:31], v[34:35]
	v_pk_fma_f32 v[8:9], v[8:9], v[14:15], v[2:3]
	s_waitcnt vmcnt(1)
	v_pk_fma_f32 v[10:11], v[10:11], v[32:33], v[38:39]
	v_pk_fma_f32 v[12:13], v[12:13], v[16:17], v[4:5]
	v_cvt_pk_f16_f32 v2, v6, v7
	v_cvt_pk_f16_f32 v3, v8, v9
	v_cvt_pk_f16_f32 v4, v10, v11
	v_cvt_pk_f16_f32 v5, v12, v13
	global_store_dwordx4 v[36:37], v[2:5], off
	global_load_dwordx4 v[2:5], v[28:29], off
	v_or_b32_e32 v10, s2, v72
	global_load_dwordx4 v[6:9], v[28:29], off offset:16
	v_min_i32_e32 v12, 0x8000, v10
	v_ashrrev_i32_e32 v11, 31, v10
	v_ashrrev_i32_e32 v12, 11, v12
	v_lshlrev_b64 v[10:11], 11, v[10:11]
	s_waitcnt vmcnt(3)
	v_cvt_f32_f16_e32 v32, v22
	v_cvt_f32_f16_sdwa v33, v22 dst_sel:DWORD dst_unused:UNUSED_PAD src0_sel:WORD_1
	v_cvt_f32_f16_e32 v22, v23
	v_cvt_f32_f16_sdwa v23, v23 dst_sel:DWORD dst_unused:UNUSED_PAD src0_sel:WORD_1
	v_cvt_f32_f16_e32 v34, v24
	v_cvt_f32_f16_sdwa v35, v24 dst_sel:DWORD dst_unused:UNUSED_PAD src0_sel:WORD_1
	v_cvt_f32_f16_e32 v24, v25
	v_cvt_f32_f16_sdwa v25, v25 dst_sel:DWORD dst_unused:UNUSED_PAD src0_sel:WORD_1
	v_mul_hi_i32_i24_e32 v13, 0x6000, v12
	v_mul_i32_i24_e32 v12, 0x6000, v12
	v_lshl_add_u64 v[10:11], s[46:47], 0, v[10:11]
	v_lshl_add_u64 v[12:13], s[8:9], 0, v[12:13]
	v_lshl_add_u64 v[28:29], v[10:11], 0, v[66:67]
	v_lshl_add_u64 v[14:15], v[12:13], 0, v[68:69]
	global_load_dwordx4 v[10:13], v[28:29], off
	s_waitcnt lgkmcnt(0)
	v_lshlrev_b32_e32 v16, 16, v18
	v_and_b32_e32 v17, 0xffff0000, v18
	v_lshlrev_b32_e32 v18, 16, v19
	v_and_b32_e32 v19, 0xffff0000, v19
	v_lshlrev_b32_e32 v30, 16, v20
	v_and_b32_e32 v31, 0xffff0000, v20
	v_lshlrev_b32_e32 v20, 16, v21
	v_and_b32_e32 v21, 0xffff0000, v21
	v_pk_mul_f32 v[32:33], v[32:33], s[30:31] op_sel_hi:[1,0]
	v_pk_mul_f32 v[22:23], v[22:23], s[30:31] op_sel_hi:[1,0]
	v_pk_mul_f32 v[34:35], v[34:35], s[30:31] op_sel_hi:[1,0]
	v_pk_mul_f32 v[24:25], v[24:25], s[30:31] op_sel_hi:[1,0]
	s_waitcnt vmcnt(2)
	v_pk_fma_f32 v[2:3], v[2:3], v[16:17], v[32:33]
	v_pk_fma_f32 v[4:5], v[4:5], v[18:19], v[22:23]
	s_waitcnt vmcnt(1)
	v_pk_fma_f32 v[6:7], v[6:7], v[30:31], v[34:35]
	v_pk_fma_f32 v[8:9], v[8:9], v[20:21], v[24:25]
	v_cvt_pk_f16_f32 v2, v2, v3
	v_cvt_pk_f16_f32 v3, v4, v5
	v_cvt_pk_f16_f32 v4, v6, v7
	v_cvt_pk_f16_f32 v5, v8, v9
	global_store_dwordx4 v[26:27], v[2:5], off
	global_load_dwordx4 v[2:5], v[14:15], off
	s_waitcnt vmcnt(2)
	v_cvt_f32_f16_e32 v36, v10
	global_load_dwordx4 v[6:9], v[14:15], off offset:16
	v_or_b32_e32 v14, s2, v73
	v_min_i32_e32 v16, 0x8000, v14
	v_ashrrev_i32_e32 v15, 31, v14
	v_ashrrev_i32_e32 v16, 11, v16
	v_lshlrev_b64 v[14:15], 11, v[14:15]
	v_mul_hi_i32_i24_e32 v17, 0x6000, v16
	v_mul_i32_i24_e32 v16, 0x6000, v16
	v_lshl_add_u64 v[18:19], s[46:47], 0, v[14:15]
	v_lshl_add_u64 v[20:21], s[8:9], 0, v[16:17]
	ds_read_b128 v[14:17], v0 offset:2304
	v_cvt_f32_f16_sdwa v37, v10 dst_sel:DWORD dst_unused:UNUSED_PAD src0_sel:WORD_1
	v_cvt_f32_f16_e32 v10, v11
	v_cvt_f32_f16_sdwa v11, v11 dst_sel:DWORD dst_unused:UNUSED_PAD src0_sel:WORD_1
	v_cvt_f32_f16_e32 v38, v12
	v_cvt_f32_f16_sdwa v39, v12 dst_sel:DWORD dst_unused:UNUSED_PAD src0_sel:WORD_1
	v_cvt_f32_f16_e32 v12, v13
	v_cvt_f32_f16_sdwa v13, v13 dst_sel:DWORD dst_unused:UNUSED_PAD src0_sel:WORD_1
	v_lshl_add_u64 v[26:27], v[18:19], 0, v[66:67]
	global_load_dwordx4 v[22:25], v[26:27], off
	s_waitcnt lgkmcnt(0)
;   DI void operator()(f32x16 (&acc)[2][MB], int wm, int wn, int r, int h) {
;     ...
;         for (int j = 0; j < 8; ++j) {
;           const int rowl = (lane >> 3) + 8 * j, ch = lane & 7;
;           if (rowl < ntok) {
;             const u32x4 yv = *(const u32x4*)(slab + rowl * 72 + ch * 8);
;             const int R = R0 + rowl;
;             const int mi = (R < NLAT) ? (R >> 11) : 16;
;             const int col = n0 + wn * 64 + ch * 8;
;             const float* g = gate + (size_t)mi * 6144 + col;
;             const f32x4n g0 = *(const f32x4n*)(g), g1 = *(const f32x4n*)(g + 4);
;             _Float16* xp = X + (size_t)R * 1024 + col;
;             const h8 xv = *(const h8*)xp;
;             const float y[8] = {__uint_as_float(yv.x << 16), __uint_as_float(yv.x & 0xffff0000u), __uint_as_float(yv.y << 16), __uint_as_float(yv.y & 0xffff0000u),
;                                 __uint_as_float(yv.z << 16), __uint_as_float(yv.z & 0xffff0000u), __uint_as_float(yv.w << 16), __uint_as_float(yv.w & 0xffff0000u)};
;             const float gg[8] = {g0.x, g0.y, g0.z, g0.w, g1.x, g1.y, g1.z, g1.w};
;             h8 o;
; #pragma unroll
;             for (int q = 0; q < 8; ++q) o[q] = (_Float16)(ALPHA * (float)xv[q] + gg[q] * y[q]);
;             *(h8*)xp = o;
;           }
;         }
	v_lshlrev_b32_e32 v32, 16, v14
	v_and_b32_e32 v33, 0xffff0000, v14
	v_lshlrev_b32_e32 v14, 16, v15
	v_and_b32_e32 v15, 0xffff0000, v15
	v_lshlrev_b32_e32 v34, 16, v16
	v_and_b32_e32 v35, 0xffff0000, v16
	v_lshlrev_b32_e32 v16, 16, v17
	v_and_b32_e32 v17, 0xffff0000, v17
	v_pk_mul_f32 v[36:37], v[36:37], s[30:31] op_sel_hi:[1,0]
	v_pk_mul_f32 v[10:11], v[10:11], s[30:31] op_sel_hi:[1,0]
	v_pk_mul_f32 v[38:39], v[38:39], s[30:31] op_sel_hi:[1,0]
	v_pk_mul_f32 v[12:13], v[12:13], s[30:31] op_sel_hi:[1,0]
	v_lshl_add_u64 v[30:31], v[20:21], 0, v[68:69]
	ds_read_b128 v[18:21], v0 offset:3456
	s_waitcnt vmcnt(2)
	v_pk_fma_f32 v[2:3], v[2:3], v[32:33], v[36:37]
	v_pk_fma_f32 v[4:5], v[4:5], v[14:15], v[10:11]
	v_cvt_pk_f16_f32 v2, v2, v3
	v_cvt_pk_f16_f32 v3, v4, v5
	v_or_b32_e32 v10, s2, v74
	v_ashrrev_i32_e32 v11, 31, v10
	s_waitcnt vmcnt(1)
	v_pk_fma_f32 v[6:7], v[6:7], v[34:35], v[38:39]
	v_pk_fma_f32 v[8:9], v[8:9], v[16:17], v[12:13]
	v_cvt_pk_f16_f32 v4, v6, v7
	v_cvt_pk_f16_f32 v5, v8, v9
	global_store_dwordx4 v[28:29], v[2:5], off
	global_load_dwordx4 v[2:5], v[30:31], off
	v_min_i32_e32 v12, 0x8000, v10
	global_load_dwordx4 v[6:9], v[30:31], off offset:16
	v_ashrrev_i32_e32 v12, 11, v12
	v_lshlrev_b64 v[10:11], 11, v[10:11]
	v_mul_hi_i32_i24_e32 v13, 0x6000, v12
	v_mul_i32_i24_e32 v12, 0x6000, v12
	v_lshl_add_u64 v[10:11], s[46:47], 0, v[10:11]
	v_lshl_add_u64 v[12:13], s[8:9], 0, v[12:13]
	v_lshl_add_u64 v[28:29], v[10:11], 0, v[66:67]
	v_lshl_add_u64 v[14:15], v[12:13], 0, v[68:69]
	global_load_dwordx4 v[10:13], v[28:29], off
	s_waitcnt lgkmcnt(0)
	v_lshlrev_b32_e32 v16, 16, v18
	v_and_b32_e32 v17, 0xffff0000, v18
	s_waitcnt vmcnt(4)
	v_cvt_f32_f16_e32 v32, v22
	v_cvt_f32_f16_sdwa v33, v22 dst_sel:DWORD dst_unused:UNUSED_PAD src0_sel:WORD_1
	v_cvt_f32_f16_e32 v22, v23
	v_cvt_f32_f16_sdwa v23, v23 dst_sel:DWORD dst_unused:UNUSED_PAD src0_sel:WORD_1
	v_cvt_f32_f16_e32 v34, v24
	v_cvt_f32_f16_sdwa v35, v24 dst_sel:DWORD dst_unused:UNUSED_PAD src0_sel:WORD_1
	v_cvt_f32_f16_e32 v24, v25
	v_cvt_f32_f16_sdwa v25, v25 dst_sel:DWORD dst_unused:UNUSED_PAD src0_sel:WORD_1
	v_lshlrev_b32_e32 v18, 16, v19
	v_and_b32_e32 v19, 0xffff0000, v19
	v_lshlrev_b32_e32 v30, 16, v20
	v_and_b32_e32 v31, 0xffff0000, v20
	v_lshlrev_b32_e32 v20, 16, v21
	v_and_b32_e32 v21, 0xffff0000, v21
	v_pk_mul_f32 v[32:33], v[32:33], s[30:31] op_sel_hi:[1,0]
	v_pk_mul_f32 v[22:23], v[22:23], s[30:31] op_sel_hi:[1,0]
	v_pk_mul_f32 v[34:35], v[34:35], s[30:31] op_sel_hi:[1,0]
	v_pk_mul_f32 v[24:25], v[24:25], s[30:31] op_sel_hi:[1,0]
	s_waitcnt vmcnt(2)
	v_pk_fma_f32 v[2:3], v[2:3], v[16:17], v[32:33]
	v_pk_fma_f32 v[4:5], v[4:5], v[18:19], v[22:23]
	s_waitcnt vmcnt(1)
	v_pk_fma_f32 v[6:7], v[6:7], v[30:31], v[34:35]
	v_pk_fma_f32 v[8:9], v[8:9], v[20:21], v[24:25]
	v_cvt_pk_f16_f32 v2, v2, v3
	v_cvt_pk_f16_f32 v3, v4, v5
	v_cvt_pk_f16_f32 v4, v6, v7
	v_cvt_pk_f16_f32 v5, v8, v9
	global_store_dwordx4 v[26:27], v[2:5], off
	global_load_dwordx4 v[2:5], v[14:15], off
	s_waitcnt vmcnt(2)
	v_cvt_f32_f16_e32 v36, v10
	global_load_dwordx4 v[6:9], v[14:15], off offset:16
	v_or_b32_e32 v14, s2, v75
	v_min_i32_e32 v16, 0x8000, v14
	v_ashrrev_i32_e32 v15, 31, v14
	v_ashrrev_i32_e32 v16, 11, v16
	v_lshlrev_b64 v[14:15], 11, v[14:15]
	v_mul_hi_i32_i24_e32 v17, 0x6000, v16
	v_mul_i32_i24_e32 v16, 0x6000, v16
	v_lshl_add_u64 v[18:19], s[46:47], 0, v[14:15]
	v_lshl_add_u64 v[20:21], s[8:9], 0, v[16:17]
	ds_read_b128 v[14:17], v0 offset:4608
	v_cvt_f32_f16_sdwa v37, v10 dst_sel:DWORD dst_unused:UNUSED_PAD src0_sel:WORD_1
	v_cvt_f32_f16_e32 v10, v11
	v_cvt_f32_f16_sdwa v11, v11 dst_sel:DWORD dst_unused:UNUSED_PAD src0_sel:WORD_1
	v_cvt_f32_f16_e32 v38, v12
	v_cvt_f32_f16_sdwa v39, v12 dst_sel:DWORD dst_unused:UNUSED_PAD src0_sel:WORD_1
	v_cvt_f32_f16_e32 v12, v13
	v_cvt_f32_f16_sdwa v13, v13 dst_sel:DWORD dst_unused:UNUSED_PAD src0_sel:WORD_1
	v_lshl_add_u64 v[26:27], v[18:19], 0, v[66:67]
	global_load_dwordx4 v[22:25], v[26:27], off
	s_waitcnt lgkmcnt(0)
	v_lshlrev_b32_e32 v32, 16, v14
	v_and_b32_e32 v33, 0xffff0000, v14
	v_lshlrev_b32_e32 v14, 16, v15
	v_and_b32_e32 v15, 0xffff0000, v15
	v_lshlrev_b32_e32 v34, 16, v16
	v_and_b32_e32 v35, 0xffff0000, v16
	v_lshlrev_b32_e32 v16, 16, v17
	v_and_b32_e32 v17, 0xffff0000, v17
	v_pk_mul_f32 v[36:37], v[36:37], s[30:31] op_sel_hi:[1,0]
	v_pk_mul_f32 v[10:11], v[10:11], s[30:31] op_sel_hi:[1,0]
	v_pk_mul_f32 v[38:39], v[38:39], s[30:31] op_sel_hi:[1,0]
	v_pk_mul_f32 v[12:13], v[12:13], s[30:31] op_sel_hi:[1,0]
	v_lshl_add_u64 v[30:31], v[20:21], 0, v[68:69]
	ds_read_b128 v[18:21], v0 offset:5760
	s_waitcnt vmcnt(2)
	v_pk_fma_f32 v[2:3], v[2:3], v[32:33], v[36:37]
	v_pk_fma_f32 v[4:5], v[4:5], v[14:15], v[10:11]
	v_cvt_pk_f16_f32 v2, v2, v3
	s_waitcnt vmcnt(1)
	v_pk_fma_f32 v[6:7], v[6:7], v[34:35], v[38:39]
	v_pk_fma_f32 v[8:9], v[8:9], v[16:17], v[12:13]
	v_cvt_pk_f16_f32 v3, v4, v5
	v_cvt_pk_f16_f32 v4, v6, v7
	v_cvt_pk_f16_f32 v5, v8, v9
	global_store_dwordx4 v[28:29], v[2:5], off
	global_load_dwordx4 v[2:5], v[30:31], off
	v_or_b32_e32 v10, s2, v76
	global_load_dwordx4 v[6:9], v[30:31], off offset:16
	v_min_i32_e32 v12, 0x8000, v10
	v_ashrrev_i32_e32 v11, 31, v10
	v_ashrrev_i32_e32 v12, 11, v12
	v_lshlrev_b64 v[10:11], 11, v[10:11]
	v_mul_hi_i32_i24_e32 v13, 0x6000, v12
	v_mul_i32_i24_e32 v12, 0x6000, v12
	v_lshl_add_u64 v[10:11], s[46:47], 0, v[10:11]
	v_lshl_add_u64 v[12:13], s[8:9], 0, v[12:13]
	v_lshl_add_u64 v[28:29], v[10:11], 0, v[66:67]
	v_lshl_add_u64 v[14:15], v[12:13], 0, v[68:69]
	s_waitcnt vmcnt(3)
;   DI void operator()(f32x16 (&acc)[2][MB], int wm, int wn, int r, int h) {
;     ...
;         for (int j = 0; j < 8; ++j) {
;           const int rowl = (lane >> 3) + 8 * j, ch = lane & 7;
;           if (rowl < ntok) {
;             const u32x4 yv = *(const u32x4*)(slab + rowl * 72 + ch * 8);
;             const int R = R0 + rowl;
;             const int mi = (R < NLAT) ? (R >> 11) : 16;
;             const int col = n0 + wn * 64 + ch * 8;
;             const float* g = gate + (size_t)mi * 6144 + col;
;             const f32x4n g0 = *(const f32x4n*)(g), g1 = *(const f32x4n*)(g + 4);
;             _Float16* xp = X + (size_t)R * 1024 + col;
;             const h8 xv = *(const h8*)xp;
;             const float y[8] = {__uint_as_float(yv.x << 16), __uint_as_float(yv.x & 0xffff0000u), __uint_as_float(yv.y << 16), __uint_as_float(yv.y & 0xffff0000u),
;                                 __uint_as_float(yv.z << 16), __uint_as_float(yv.z & 0xffff0000u), __uint_as_float(yv.w << 16), __uint_as_float(yv.w & 0xffff0000u)};
;             const float gg[8] = {g0.x, g0.y, g0.z, g0.w, g1.x, g1.y, g1.z, g1.w};
;             h8 o;
; #pragma unroll
;             for (int q = 0; q < 8; ++q) o[q] = (_Float16)(ALPHA * (float)xv[q] + gg[q] * y[q]);
;             *(h8*)xp = o;
;           }
;         }
;       }
;     }
;     __syncthreads();
	v_cvt_f32_f16_e32 v32, v22
	v_cvt_f32_f16_sdwa v33, v22 dst_sel:DWORD dst_unused:UNUSED_PAD src0_sel:WORD_1
	v_cvt_f32_f16_e32 v22, v23
	v_cvt_f32_f16_sdwa v23, v23 dst_sel:DWORD dst_unused:UNUSED_PAD src0_sel:WORD_1
	v_cvt_f32_f16_e32 v34, v24
	v_cvt_f32_f16_sdwa v35, v24 dst_sel:DWORD dst_unused:UNUSED_PAD src0_sel:WORD_1
	v_cvt_f32_f16_e32 v24, v25
	v_cvt_f32_f16_sdwa v25, v25 dst_sel:DWORD dst_unused:UNUSED_PAD src0_sel:WORD_1
	global_load_dwordx4 v[10:13], v[28:29], off
	s_waitcnt lgkmcnt(0)
	v_lshlrev_b32_e32 v16, 16, v18
	v_and_b32_e32 v17, 0xffff0000, v18
	v_lshlrev_b32_e32 v18, 16, v19
	v_and_b32_e32 v19, 0xffff0000, v19
	v_lshlrev_b32_e32 v30, 16, v20
	v_and_b32_e32 v31, 0xffff0000, v20
	v_lshlrev_b32_e32 v20, 16, v21
	v_and_b32_e32 v21, 0xffff0000, v21
	v_pk_mul_f32 v[32:33], v[32:33], s[30:31] op_sel_hi:[1,0]
	v_pk_mul_f32 v[22:23], v[22:23], s[30:31] op_sel_hi:[1,0]
	v_pk_mul_f32 v[34:35], v[34:35], s[30:31] op_sel_hi:[1,0]
	v_pk_mul_f32 v[24:25], v[24:25], s[30:31] op_sel_hi:[1,0]
	s_waitcnt vmcnt(2)
	v_pk_fma_f32 v[2:3], v[2:3], v[16:17], v[32:33]
	v_pk_fma_f32 v[4:5], v[4:5], v[18:19], v[22:23]
	s_waitcnt vmcnt(1)
	v_pk_fma_f32 v[6:7], v[6:7], v[30:31], v[34:35]
	v_pk_fma_f32 v[8:9], v[8:9], v[20:21], v[24:25]
	v_cvt_pk_f16_f32 v2, v2, v3
	v_cvt_pk_f16_f32 v3, v4, v5
	v_cvt_pk_f16_f32 v4, v6, v7
	v_cvt_pk_f16_f32 v5, v8, v9
	global_store_dwordx4 v[26:27], v[2:5], off
	global_load_dwordx4 v[2:5], v[14:15], off
	s_waitcnt vmcnt(2)
	v_cvt_f32_f16_e32 v36, v10
	global_load_dwordx4 v[6:9], v[14:15], off offset:16
	v_or_b32_e32 v14, s2, v77
	v_min_i32_e32 v16, 0x8000, v14
	v_ashrrev_i32_e32 v15, 31, v14
	v_ashrrev_i32_e32 v16, 11, v16
	v_lshlrev_b64 v[14:15], 11, v[14:15]
	v_mul_hi_i32_i24_e32 v17, 0x6000, v16
	v_mul_i32_i24_e32 v16, 0x6000, v16
	v_lshl_add_u64 v[18:19], s[46:47], 0, v[14:15]
	v_lshl_add_u64 v[20:21], s[8:9], 0, v[16:17]
	ds_read_b128 v[14:17], v0 offset:6912
	v_cvt_f32_f16_sdwa v37, v10 dst_sel:DWORD dst_unused:UNUSED_PAD src0_sel:WORD_1
	v_cvt_f32_f16_e32 v10, v11
	v_cvt_f32_f16_sdwa v11, v11 dst_sel:DWORD dst_unused:UNUSED_PAD src0_sel:WORD_1
	v_cvt_f32_f16_e32 v38, v12
	v_cvt_f32_f16_sdwa v39, v12 dst_sel:DWORD dst_unused:UNUSED_PAD src0_sel:WORD_1
	v_cvt_f32_f16_e32 v12, v13
	v_cvt_f32_f16_sdwa v13, v13 dst_sel:DWORD dst_unused:UNUSED_PAD src0_sel:WORD_1
	v_lshl_add_u64 v[26:27], v[18:19], 0, v[66:67]
	global_load_dwordx4 v[22:25], v[26:27], off
	s_waitcnt lgkmcnt(0)
	v_lshlrev_b32_e32 v32, 16, v14
	v_and_b32_e32 v33, 0xffff0000, v14
	v_lshlrev_b32_e32 v14, 16, v15
	v_and_b32_e32 v15, 0xffff0000, v15
	v_lshlrev_b32_e32 v34, 16, v16
	v_and_b32_e32 v35, 0xffff0000, v16
	v_lshlrev_b32_e32 v16, 16, v17
	v_and_b32_e32 v17, 0xffff0000, v17
	v_pk_mul_f32 v[36:37], v[36:37], s[30:31] op_sel_hi:[1,0]
	v_pk_mul_f32 v[10:11], v[10:11], s[30:31] op_sel_hi:[1,0]
	v_pk_mul_f32 v[38:39], v[38:39], s[30:31] op_sel_hi:[1,0]
	v_pk_mul_f32 v[12:13], v[12:13], s[30:31] op_sel_hi:[1,0]
	v_lshl_add_u64 v[30:31], v[20:21], 0, v[68:69]
	ds_read_b128 v[18:21], v0 offset:8064
	s_waitcnt vmcnt(2)
	v_pk_fma_f32 v[2:3], v[2:3], v[32:33], v[36:37]
	v_pk_fma_f32 v[4:5], v[4:5], v[14:15], v[10:11]
	v_cvt_pk_f16_f32 v2, v2, v3
	v_cvt_pk_f16_f32 v3, v4, v5
	s_waitcnt lgkmcnt(0)
	v_lshlrev_b32_e32 v10, 16, v18
	v_and_b32_e32 v11, 0xffff0000, v18
	v_lshlrev_b32_e32 v14, 16, v20
	v_and_b32_e32 v15, 0xffff0000, v20
	s_waitcnt vmcnt(1)
	v_pk_fma_f32 v[6:7], v[6:7], v[34:35], v[38:39]
	v_pk_fma_f32 v[8:9], v[8:9], v[16:17], v[12:13]
	v_cvt_pk_f16_f32 v4, v6, v7
	v_cvt_pk_f16_f32 v5, v8, v9
	global_store_dwordx4 v[28:29], v[2:5], off
	global_load_dwordx4 v[2:5], v[30:31], off
	v_lshlrev_b32_e32 v12, 16, v19
	global_load_dwordx4 v[6:9], v[30:31], off offset:16
	v_and_b32_e32 v13, 0xffff0000, v19
	v_lshlrev_b32_e32 v16, 16, v21
	v_and_b32_e32 v17, 0xffff0000, v21
	s_waitcnt vmcnt(3)
	v_cvt_f32_f16_e32 v18, v22
	v_cvt_f32_f16_sdwa v19, v22 dst_sel:DWORD dst_unused:UNUSED_PAD src0_sel:WORD_1
	v_cvt_f32_f16_e32 v20, v23
	v_cvt_f32_f16_sdwa v21, v23 dst_sel:DWORD dst_unused:UNUSED_PAD src0_sel:WORD_1
	v_cvt_f32_f16_e32 v22, v24
	v_cvt_f32_f16_sdwa v23, v24 dst_sel:DWORD dst_unused:UNUSED_PAD src0_sel:WORD_1
	v_cvt_f32_f16_e32 v24, v25
	v_cvt_f32_f16_sdwa v25, v25 dst_sel:DWORD dst_unused:UNUSED_PAD src0_sel:WORD_1
	v_pk_mul_f32 v[18:19], v[18:19], s[30:31] op_sel_hi:[1,0]
	v_pk_mul_f32 v[20:21], v[20:21], s[30:31] op_sel_hi:[1,0]
	v_pk_mul_f32 v[22:23], v[22:23], s[30:31] op_sel_hi:[1,0]
	v_pk_mul_f32 v[24:25], v[24:25], s[30:31] op_sel_hi:[1,0]
	s_waitcnt vmcnt(1)
	v_pk_fma_f32 v[2:3], v[2:3], v[10:11], v[18:19]
	v_pk_fma_f32 v[4:5], v[4:5], v[12:13], v[20:21]
	s_waitcnt vmcnt(0)
	v_pk_fma_f32 v[6:7], v[6:7], v[14:15], v[22:23]
	v_pk_fma_f32 v[8:9], v[8:9], v[16:17], v[24:25]
	v_cvt_pk_f16_f32 v2, v2, v3
	v_cvt_pk_f16_f32 v3, v4, v5
	v_cvt_pk_f16_f32 v4, v6, v7
	v_cvt_pk_f16_f32 v5, v8, v9
	global_store_dwordx4 v[26:27], v[2:5], off
	s_barrier
	s_branch .LBB0_654

; template <int MB, class Epi>
; DI void gemm_tile(const u16* __restrict__ A, int lda, int row0, int Mrows, const u16* __restrict__ Bt, int ldb, int K, char* smem, Epi& epi, int rot) {
;     ...
;   for (int kt = 0; kt < KT; ++kt) {
;     const bool more = (kt + 1 < KT);
;     const bool more2 = (kt + 2 < KT);
;     const int nstg = (kt + 1) & 1;
;     const char* as = As + (kt & 1) * 32768 + wm * (32 * MB) * 128;
;     const char* bs = Bs + (kt & 1) * 32768 + wn * 64 * 128;
;     int k1_ = kbase + kt + 1; if (k1_ >= KT) k1_ -= KT;
;     int k2_ = kbase + kt + 2; if (k2_ >= KT) k2_ -= KT; if (k2_ >= KT) k2_ -= KT;
; #pragma unroll
;     for (int ks = 0; ks < 3; ++ks) {
; #pragma unroll
;       for (int idx = 0; idx < 2 * MB; ++idx) {
;         const int nb = idx / MB, mb = idx % MB;
;         acc[nb][mb] = mfma32(bfr[ks & 1][nb], af[ks & 1][mb], acc[nb][mb]);
;         if (idx < MB) af[(ks + 1) & 1][idx] = *(const bf8*)(as + idx * 32 * 128 + foff[ks + 1]);
;         else if (idx < MB + 2) bfr[(ks + 1) & 1][idx - MB] = *(const bf8*)(bs + (idx - MB) * 32 * 128 + foff[ks + 1]);
;         if (more && ks < 2 && idx < 3) {
;           const int ko_ = k1_ * 64;
;           GEMM_PIECE(nstg, 3 + ks * 3 + idx)
;         }
;         __builtin_amdgcn_sched_barrier(0);
;       }
;     }
;     if (more) {
;       asm volatile("s_waitcnt vmcnt(0)" ::: "memory");
;       __syncthreads();
;       if (more2) {
;         const int ko_ = k2_ * 64;
; #pragma unroll
;         for (int pc = 0; pc < 3; ++pc) GEMM_PIECE(kt & 1, pc)
;       }
;       __builtin_amdgcn_sched_barrier(0);
;       const char* asn = As + nstg * 32768 + wm * (32 * MB) * 128;
;       const char* bsn = Bs + nstg * 32768 + wn * 64 * 128;
; #pragma unroll
;       for (int mb = 0; mb < MB; ++mb) af[0][mb] = *(const bf8*)(asn + mb * 32 * 128 + foff[0]);
; #pragma unroll
;       for (int nb = 0; nb < 2; ++nb) bfr[0][nb] = *(const bf8*)(bsn + nb * 32 * 128 + foff[0]);
;     }
; #pragma unroll
;     for (int nb = 0; nb < 2; ++nb)
; #pragma unroll
;       for (int mb = 0; mb < MB; ++mb) acc[nb][mb] = mfma32(bfr[1][nb], af[1][mb], acc[nb][mb]);
; #pragma unroll
;     for (int gk = 0; gk < 2 * MB; ++gk) {
;       __builtin_amdgcn_sched_group_barrier(0x008, 1, 0);
;       __builtin_amdgcn_sched_group_barrier(0x100, 1, 0);
;     }
;     __builtin_amdgcn_sched_barrier(0);
;   }
.LBB0_856:
	s_and_b32 s23, s15, 0x8000
	s_add_i32 s19, s22, 1
	s_add_i32 s28, s13, s23
	s_add_i32 s25, s11, s23
	s_add_i32 s22, s16, s22
	s_cmp_lt_i32 s22, 43
	s_cselect_b32 s18, 0, 0xffffffd4
	s_waitcnt lgkmcnt(1)
	v_mfma_f32_32x32x16_bf16 v[66:81], v[114:117], v[110:113], v[66:81]
	s_add_i32 s18, s22, s18
	s_lshl_b32 s18, s18, 6
	s_add_i32 s26, s18, 64
	s_add_i32 s15, s15, 0x8000
	v_add_u32_e32 v144, s28, v129
	s_ashr_i32 s27, s26, 31
	s_and_b32 s18, s15, 0x8000
	ds_read_b128 v[132:135], v144
	v_lshl_add_u64 v[140:141], s[26:27], 1, v[120:121]
	s_add_i32 s26, s18, s17
	s_mov_b32 m0, s26
	s_nop 0
	global_load_lds_dwordx4 v[140:141], off
	v_mfma_f32_32x32x16_bf16 v[34:49], v[114:117], v[106:109], v[34:49]
	ds_read_b128 v[136:139], v144 offset:4096
	v_lshl_add_u64 v[142:143], v[140:141], 0, s[40:41]
	s_add_i32 s27, s26, 0x2000
	s_mov_b32 m0, s27
	s_nop 0
	global_load_lds_dwordx4 v[142:143], off
	v_mfma_f32_32x32x16_bf16 v[2:17], v[114:117], v[98:101], v[2:17]
	ds_read_b128 v[114:117], v144 offset:8192
	v_lshl_add_u64 v[142:143], v[140:141], 0, s[48:49]
	s_add_i32 s27, s26, 0x4000
	s_mov_b32 m0, s27
	s_nop 0
	global_load_lds_dwordx4 v[142:143], off
	s_waitcnt lgkmcnt(3)
	v_mfma_f32_32x32x16_bf16 v[82:97], v[102:105], v[110:113], v[82:97]
	v_add_u32_e32 v142, s25, v129
	ds_read_b128 v[110:113], v142
	v_mfma_f32_32x32x16_bf16 v[50:65], v[102:105], v[106:109], v[50:65]
	ds_read_b128 v[106:109], v142 offset:4096
	v_mfma_f32_32x32x16_bf16 v[18:33], v[102:105], v[98:101], v[18:33]
	s_waitcnt lgkmcnt(1)
	v_mfma_f32_32x32x16_bf16 v[66:81], v[110:113], v[132:135], v[66:81]
	v_add_u32_e32 v142, s28, v128
	ds_read_b128 v[98:101], v142
	v_lshl_add_u64 v[102:103], v[140:141], 0, s[54:55]
	s_addk_i32 s26, 0x6000
	s_mov_b32 m0, s26
	s_nop 0
	global_load_lds_dwordx4 v[102:103], off
	v_mfma_f32_32x32x16_bf16 v[34:49], v[110:113], v[136:139], v[34:49]
	ds_read_b128 v[102:105], v142 offset:4096
	v_mfma_f32_32x32x16_bf16 v[2:17], v[110:113], v[114:117], v[2:17]
	ds_read_b128 v[110:113], v142 offset:8192
	s_waitcnt lgkmcnt(3)
	v_mfma_f32_32x32x16_bf16 v[82:97], v[106:109], v[132:135], v[82:97]
	v_add_u32_e32 v140, s25, v128
	ds_read_b128 v[132:135], v140
	v_mfma_f32_32x32x16_bf16 v[50:65], v[106:109], v[136:139], v[50:65]
	ds_read_b128 v[136:139], v140 offset:4096
	v_mfma_f32_32x32x16_bf16 v[18:33], v[106:109], v[114:117], v[18:33]
	s_waitcnt lgkmcnt(1)
	v_mfma_f32_32x32x16_bf16 v[66:81], v[132:135], v[98:101], v[66:81]
	v_add_u32_e32 v106, s28, v127
	ds_read_b128 v[114:117], v106
	v_mfma_f32_32x32x16_bf16 v[34:49], v[132:135], v[102:105], v[34:49]
	ds_read_b128 v[140:143], v106 offset:4096
	v_mfma_f32_32x32x16_bf16 v[2:17], v[132:135], v[110:113], v[2:17]
	ds_read_b128 v[132:135], v106 offset:8192
	s_waitcnt lgkmcnt(3)
	v_mfma_f32_32x32x16_bf16 v[82:97], v[136:139], v[98:101], v[82:97]
	v_add_u32_e32 v106, s25, v127
	ds_read_b128 v[98:101], v106
	v_mfma_f32_32x32x16_bf16 v[50:65], v[136:139], v[102:105], v[50:65]
	ds_read_b128 v[144:147], v106 offset:4096
	v_mfma_f32_32x32x16_bf16 v[18:33], v[136:139], v[110:113], v[18:33]
	s_cmp_lt_i32 s22, 42
	s_cselect_b32 s25, 0, 0xffffffd4
	s_add_i32 s26, s22, s25
	s_add_i32 s26, s26, 2
	s_cmp_lt_i32 s26, 44
	s_cselect_b32 s26, 0, 0xffffffd4
	s_add_i32 s25, s25, s26
	s_add_i32 s22, s22, s25
	s_lshl_b32 s22, s22, 6
	s_add_i32 s26, s22, 0x80
	s_ashr_i32 s27, s26, 31
	s_lshl_b64 s[26:27], s[26:27], 1
	s_add_u32 s26, s20, s26
	s_addc_u32 s27, s21, s27
	s_waitcnt vmcnt(0)
	s_waitcnt lgkmcnt(0)
	s_barrier
	s_add_i32 s22, s23, s14
	v_lshl_add_u64 v[102:103], v[0:1], 1, s[26:27]
	s_mov_b32 m0, s22
	s_nop 0
	global_load_lds_dwordx4 v[102:103], off
	v_lshl_add_u64 v[102:103], v[118:119], 1, s[26:27]
	s_add_i32 s23, s22, 0x2000
	s_mov_b32 m0, s23
	s_nop 0
	global_load_lds_dwordx4 v[102:103], off
	v_lshl_add_u64 v[102:103], v[122:123], 1, s[26:27]
	s_addk_i32 s22, 0x4000
	s_mov_b32 m0, s22
	s_nop 0
	global_load_lds_dwordx4 v[102:103], off
	v_add_u32_e32 v102, s18, v131
	v_mfma_f32_32x32x16_bf16 v[66:81], v[98:101], v[114:117], v[66:81]
	ds_read_b128 v[110:113], v102
	v_mfma_f32_32x32x16_bf16 v[34:49], v[98:101], v[140:143], v[34:49]
	ds_read_b128 v[106:109], v102 offset:4096
	v_mfma_f32_32x32x16_bf16 v[2:17], v[98:101], v[132:135], v[2:17]
	ds_read_b128 v[98:101], v102 offset:8192
	v_add_u32_e32 v102, s18, v130
	v_mfma_f32_32x32x16_bf16 v[82:97], v[144:147], v[114:117], v[82:97]
	ds_read_b128 v[114:117], v102
	v_mfma_f32_32x32x16_bf16 v[50:65], v[144:147], v[140:143], v[50:65]
	ds_read_b128 v[102:105], v102 offset:4096
	v_mfma_f32_32x32x16_bf16 v[18:33], v[144:147], v[132:135], v[18:33]
	s_cmp_eq_u32 s19, 42
	s_mov_b32 s22, s19
	s_cbranch_scc0 .LBB0_856
; DI f32x16 mfma32(bf8 a, bf8 b, f32x16 c) { return __builtin_amdgcn_mfma_f32_32x32x16_bf16(a, b, c, 0, 0, 0); }
; template <int MB, class Epi>
; DI void gemm_tile(const u16* __restrict__ A, int lda, int row0, int Mrows, const u16* __restrict__ Bt, int ldb, int K, char* smem, Epi& epi, int rot) {
;     ...
;     if (more) {
;       asm volatile("s_waitcnt vmcnt(0)" ::: "memory");
;       __syncthreads();
;       if (more2) {
;         const int ko_ = k2_ * 64;
; #pragma unroll
;         for (int pc = 0; pc < 3; ++pc) GEMM_PIECE(kt & 1, pc)
;       }
;       __builtin_amdgcn_sched_barrier(0);
;       const char* asn = As + nstg * 32768 + wm * (32 * MB) * 128;
;       const char* bsn = Bs + nstg * 32768 + wn * 64 * 128;
; #pragma unroll
;       for (int mb = 0; mb < MB; ++mb) af[0][mb] = *(const bf8*)(asn + mb * 32 * 128 + foff[0]);
; #pragma unroll
;       for (int nb = 0; nb < 2; ++nb) bfr[0][nb] = *(const bf8*)(bsn + nb * 32 * 128 + foff[0]);
;     }
; #pragma unroll
;     for (int nb = 0; nb < 2; ++nb)
; #pragma unroll
;       for (int mb = 0; mb < MB; ++mb) acc[nb][mb] = mfma32(bfr[1][nb], af[1][mb], acc[nb][mb]);
; #pragma unroll
;     for (int gk = 0; gk < 2 * MB; ++gk) {
;       __builtin_amdgcn_sched_group_barrier(0x008, 1, 0);
;       __builtin_amdgcn_sched_group_barrier(0x100, 1, 0);
;     }
;     __builtin_amdgcn_sched_barrier(0);
;   }
	s_add_i32 s15, s13, s18
	s_add_i32 s18, s11, s18
	s_add_i32 s16, s16, 42
	s_cmp_lt_i32 s16, 43
	s_cselect_b32 s17, 0, 0xffffffd4
	s_add_i32 s16, s16, s17
	s_lshl_b32 s16, s16, 6
	s_add_i32 s16, s16, 64
	s_ashr_i32 s17, s16, 31
	v_add_u32_e32 v0, s15, v129
	v_lshl_add_u64 v[122:123], s[16:17], 1, v[120:121]
	ds_read_b128 v[118:121], v0
	s_add_i32 s16, s14, 0x18000
	s_mov_b32 m0, s16
	s_nop 0
	global_load_lds_dwordx4 v[122:123], off
	s_waitcnt lgkmcnt(2)
	v_mfma_f32_32x32x16_bf16 v[66:81], v[114:117], v[110:113], v[66:81]
	ds_read_b128 v[132:135], v0 offset:4096
	v_lshl_add_u64 v[136:137], v[122:123], 0, s[40:41]
	s_add_i32 s16, s14, 0x1a000
	s_mov_b32 m0, s16
	s_nop 0
	global_load_lds_dwordx4 v[136:137], off
	v_mfma_f32_32x32x16_bf16 v[34:49], v[114:117], v[106:109], v[34:49]
	v_mfma_f32_32x32x16_bf16 v[2:17], v[114:117], v[98:101], v[2:17]
	ds_read_b128 v[114:117], v0 offset:8192
	v_lshl_add_u64 v[136:137], v[122:123], 0, s[48:49]
	s_add_i32 s16, s14, 0x1c000
	s_mov_b32 m0, s16
	s_nop 0
	global_load_lds_dwordx4 v[136:137], off
	v_add_u32_e32 v0, s18, v129
	s_waitcnt lgkmcnt(3)
	v_mfma_f32_32x32x16_bf16 v[82:97], v[102:105], v[110:113], v[82:97]
	ds_read_b128 v[110:113], v0
	v_mfma_f32_32x32x16_bf16 v[50:65], v[102:105], v[106:109], v[50:65]
	ds_read_b128 v[106:109], v0 offset:4096
	v_mfma_f32_32x32x16_bf16 v[18:33], v[102:105], v[98:101], v[18:33]
	v_add_u32_e32 v0, s15, v128
	ds_read_b128 v[98:101], v0
	v_lshl_add_u64 v[102:103], v[122:123], 0, s[54:55]
	s_add_i32 s14, s14, 0x1e000
	s_mov_b32 m0, s14
	s_nop 0
	global_load_lds_dwordx4 v[102:103], off
	s_waitcnt lgkmcnt(2)
	v_mfma_f32_32x32x16_bf16 v[66:81], v[110:113], v[118:121], v[66:81]
	ds_read_b128 v[102:105], v0 offset:4096
	v_mfma_f32_32x32x16_bf16 v[34:49], v[110:113], v[132:135], v[34:49]
	v_mfma_f32_32x32x16_bf16 v[2:17], v[110:113], v[114:117], v[2:17]
	ds_read_b128 v[110:113], v0 offset:8192
	v_add_u32_e32 v0, s18, v128
	s_waitcnt lgkmcnt(3)
	v_mfma_f32_32x32x16_bf16 v[82:97], v[106:109], v[118:121], v[82:97]
	ds_read_b128 v[118:121], v0
	v_mfma_f32_32x32x16_bf16 v[50:65], v[106:109], v[132:135], v[50:65]
	ds_read_b128 v[132:135], v0 offset:4096
	v_mfma_f32_32x32x16_bf16 v[18:33], v[106:109], v[114:117], v[18:33]
	v_add_u32_e32 v0, s15, v127
	ds_read_b128 v[106:109], v0
	s_waitcnt lgkmcnt(2)
	v_mfma_f32_32x32x16_bf16 v[66:81], v[118:121], v[98:101], v[66:81]
	ds_read_b128 v[114:117], v0 offset:4096
	v_mfma_f32_32x32x16_bf16 v[34:49], v[118:121], v[102:105], v[34:49]
	v_mfma_f32_32x32x16_bf16 v[2:17], v[118:121], v[110:113], v[2:17]
	ds_read_b128 v[118:121], v0 offset:8192
	v_add_u32_e32 v0, s18, v127
	s_waitcnt lgkmcnt(3)
	v_mfma_f32_32x32x16_bf16 v[82:97], v[132:135], v[98:101], v[82:97]
	ds_read_b128 v[98:101], v0
	v_mfma_f32_32x32x16_bf16 v[50:65], v[132:135], v[102:105], v[50:65]
	ds_read_b128 v[102:105], v0 offset:4096
	v_mfma_f32_32x32x16_bf16 v[18:33], v[132:135], v[110:113], v[18:33]
	s_waitcnt vmcnt(0)
	s_waitcnt lgkmcnt(0)
	s_barrier
	s_lshr_b32 s100, s0, 5
	s_lshl_b32 s100, s100, 3
	s_and_b32 s101, s0, 7
	s_or_b32 s100, s100, s101
	s_mul_i32 s100, s100, 0xc0
	s_lshr_b32 s101, s0, 3
	s_and_b32 s101, s101, 3
	s_lshl_b32 s101, s101, 9
	v_lshrrev_b32_e32 v237, 2, v163
	v_and_b32_e32 v238, 3, v163
	v_add_u32_e32 v237, s100, v237
	v_lshlrev_b32_e32 v237, 11, v237
	v_lshl_add_u32 v237, v238, 7, v237
	v_add_u32_e32 v237, s101, v237
	global_load_dword v239, v237, s[46:47]
	v_add_u32_e32 v237, 0x40000, v237
	global_load_dword v239, v237, s[46:47]
	v_mfma_f32_32x32x16_bf16 v[66:81], v[98:101], v[106:109], v[66:81]
	ds_read_b128 v[110:113], v131 offset:32768
	v_mfma_f32_32x32x16_bf16 v[34:49], v[98:101], v[114:117], v[34:49]
	ds_read_b128 v[132:135], v131 offset:36864
	v_mfma_f32_32x32x16_bf16 v[2:17], v[98:101], v[118:121], v[2:17]
	ds_read_b128 v[98:101], v131 offset:40960
	v_mfma_f32_32x32x16_bf16 v[82:97], v[102:105], v[106:109], v[82:97]
	ds_read_b128 v[106:109], v130 offset:32768
	v_mfma_f32_32x32x16_bf16 v[50:65], v[102:105], v[114:117], v[50:65]
	ds_read_b128 v[114:117], v130 offset:36864
	v_mfma_f32_32x32x16_bf16 v[18:33], v[102:105], v[118:121], v[18:33]
	v_add_u32_e32 v0, s13, v129
	ds_read_b128 v[102:105], v0 offset:32768
	s_lshl_b32 s12, s12, 8
	s_waitcnt lgkmcnt(2)
	v_mfma_f32_32x32x16_bf16 v[66:81], v[106:109], v[110:113], v[66:81]
	ds_read_b128 v[118:121], v0 offset:36864
	v_mfma_f32_32x32x16_bf16 v[34:49], v[106:109], v[132:135], v[34:49]
	v_mfma_f32_32x32x16_bf16 v[2:17], v[106:109], v[98:101], v[2:17]
	ds_read_b128 v[106:109], v0 offset:40960
	v_add_u32_e32 v0, s11, v129
	s_waitcnt lgkmcnt(3)
	v_mfma_f32_32x32x16_bf16 v[82:97], v[114:117], v[110:113], v[82:97]
	ds_read_b128 v[110:113], v0 offset:32768
	v_mfma_f32_32x32x16_bf16 v[50:65], v[114:117], v[132:135], v[50:65]
	ds_read_b128 v[130:133], v0 offset:36864
	v_mfma_f32_32x32x16_bf16 v[18:33], v[114:117], v[98:101], v[18:33]
	v_add_u32_e32 v0, s13, v128
	ds_read_b128 v[98:101], v0 offset:32768
	s_waitcnt lgkmcnt(2)
	v_mfma_f32_32x32x16_bf16 v[66:81], v[110:113], v[102:105], v[66:81]
	ds_read_b128 v[114:117], v0 offset:36864
	v_mfma_f32_32x32x16_bf16 v[34:49], v[110:113], v[118:121], v[34:49]
	v_mfma_f32_32x32x16_bf16 v[2:17], v[110:113], v[106:109], v[2:17]
	ds_read_b128 v[110:113], v0 offset:40960
	v_add_u32_e32 v0, s11, v128
	s_waitcnt lgkmcnt(3)
	v_mfma_f32_32x32x16_bf16 v[82:97], v[130:133], v[102:105], v[82:97]
	ds_read_b128 v[102:105], v0 offset:32768
	v_mfma_f32_32x32x16_bf16 v[50:65], v[130:133], v[118:121], v[50:65]
	ds_read_b128 v[118:121], v0 offset:36864
	v_mfma_f32_32x32x16_bf16 v[18:33], v[130:133], v[106:109], v[18:33]
	v_add_u32_e32 v0, s13, v127
	ds_read_b128 v[106:109], v0 offset:32768
	s_waitcnt lgkmcnt(2)
; DI f32x16 mfma32(bf8 a, bf8 b, f32x16 c) { return __builtin_amdgcn_mfma_f32_32x32x16_bf16(a, b, c, 0, 0, 0); }
; template <int MB, class Epi>
; DI void gemm_tile(const u16* __restrict__ A, int lda, int row0, int Mrows, const u16* __restrict__ Bt, int ldb, int K, char* smem, Epi& epi, int rot) {
;     ...
; #pragma unroll
;     for (int nb = 0; nb < 2; ++nb)
; #pragma unroll
;       for (int mb = 0; mb < MB; ++mb) acc[nb][mb] = mfma32(bfr[1][nb], af[1][mb], acc[nb][mb]);
; #pragma unroll
;     for (int gk = 0; gk < 2 * MB; ++gk) {
;       __builtin_amdgcn_sched_group_barrier(0x008, 1, 0);
;       __builtin_amdgcn_sched_group_barrier(0x100, 1, 0);
;     }
;     __builtin_amdgcn_sched_barrier(0);
;   }
;   __syncthreads();
;   epi(acc, wm, wn, r, h);
; }
;   DI void operator()(f32x16 (&acc)[2][MB], int wm, int wn, int r, int h) {
;     u16* slab = ostage + (wm * 4 + wn) * (64 * 72);
;     const int lane = h * 32 + r;
; #pragma unroll
;     for (int mb = 0; mb < MB; ++mb) {
;       const int tokl = (mb & 1) * 32 + r;
; #pragma unroll
;       for (int nb = 0; nb < 2; ++nb)
; #pragma unroll
;         for (int ig = 0; ig < 4; ++ig) {
;           u32x2 o;
;           o.x = pack2(acc[nb][mb][ig * 4 + 0], acc[nb][mb][ig * 4 + 1]);
;           o.y = pack2(acc[nb][mb][ig * 4 + 2], acc[nb][mb][ig * 4 + 3]);
;           *(u32x2*)(slab + tokl * 72 + nb * 32 + ig * 8 + h * 4) = o;
;         }
;       if ((mb & 1) || mb == MB - 1) {
;         asm volatile("s_waitcnt lgkmcnt(0)" ::: "memory");
;         const int ntok = (mb & 1) ? 64 : 32;
;         const int R0 = row0 + wm * (32 * MB) + (mb >> 1) * 64;
; #pragma unroll
;         for (int j = 0; j < 8; ++j) {
;           const int rowl = (lane >> 3) + 8 * j, ch = lane & 7;
;           if (rowl < ntok) {
;             const u32x4 yv = *(const u32x4*)(slab + rowl * 72 + ch * 8);
;             const int R = R0 + rowl;
;             const int mi = (R < NLAT) ? (R >> 11) : 16;
;             const int col = n0 + wn * 64 + ch * 8;
;             const float* g = gate + (size_t)mi * 6144 + col;
;             const f32x4n g0 = *(const f32x4n*)(g), g1 = *(const f32x4n*)(g + 4);
;             _Float16* xp = X + (size_t)R * 1024 + col;
;             const h8 xv = *(const h8*)xp;
;             const float y[8] = {__uint_as_float(yv.x << 16), __uint_as_float(yv.x & 0xffff0000u), __uint_as_float(yv.y << 16), __uint_as_float(yv.y & 0xffff0000u),
	v_mfma_f32_32x32x16_bf16 v[66:81], v[102:105], v[98:101], v[66:81]
	ds_read_b128 v[128:131], v0 offset:36864
	v_mfma_f32_32x32x16_bf16 v[34:49], v[102:105], v[114:117], v[34:49]
	v_mfma_f32_32x32x16_bf16 v[2:17], v[102:105], v[110:113], v[2:17]
	ds_read_b128 v[102:105], v0 offset:40960
	v_add_u32_e32 v0, s11, v127
	s_waitcnt lgkmcnt(3)
	v_mfma_f32_32x32x16_bf16 v[82:97], v[118:121], v[98:101], v[82:97]
	ds_read_b128 v[98:101], v0 offset:32768
	v_mfma_f32_32x32x16_bf16 v[50:65], v[118:121], v[114:117], v[50:65]
	ds_read_b128 v[114:117], v0 offset:36864
	v_mfma_f32_32x32x16_bf16 v[18:33], v[118:121], v[110:113], v[18:33]
	s_waitcnt lgkmcnt(1)
	v_mfma_f32_32x32x16_bf16 v[66:81], v[98:101], v[106:109], v[66:81]
	v_mfma_f32_32x32x16_bf16 v[34:49], v[98:101], v[128:131], v[34:49]
	v_mfma_f32_32x32x16_bf16 v[2:17], v[98:101], v[102:105], v[2:17]
	s_waitcnt lgkmcnt(0)
	v_mfma_f32_32x32x16_bf16 v[82:97], v[114:117], v[106:109], v[82:97]
	v_mfma_f32_32x32x16_bf16 v[50:65], v[114:117], v[128:131], v[50:65]
	v_mfma_f32_32x32x16_bf16 v[18:33], v[114:117], v[102:105], v[18:33]
	s_lshl_b32 s11, s10, 2
	s_or_b32 s11, s11, s9
	s_mulk_i32 s11, 0x2400
	v_lshl_or_b32 v0, v126, 3, s11
	v_lshlrev_b32_e32 v98, 3, v125
	v_and_b32_e32 v100, 56, v98
	v_mad_u32_u24 v98, v125, s78, v0
	v_cvt_pk_bf16_f32 v34, v34, v35
	v_cvt_pk_bf16_f32 v35, v36, v37
	v_cvt_pk_bf16_f32 v36, v38, v39
	v_cvt_pk_bf16_f32 v37, v40, v41
	v_add_u32_e32 v0, 0x1000, v98
	s_barrier
	ds_write2_b64 v0, v[34:35], v[36:37] offset0:64 offset1:66
	v_cvt_pk_bf16_f32 v34, v42, v43
	v_cvt_pk_bf16_f32 v35, v44, v45
	v_cvt_pk_bf16_f32 v36, v46, v47
	v_cvt_pk_bf16_f32 v37, v48, v49
	s_mulk_i32 s10, 0x60
	ds_write2_b64 v0, v[34:35], v[36:37] offset0:68 offset1:70
	v_cvt_pk_bf16_f32 v34, v50, v51
	v_cvt_pk_bf16_f32 v35, v52, v53
	v_cvt_pk_bf16_f32 v36, v54, v55
	v_cvt_pk_bf16_f32 v37, v56, v57
	v_bfe_u32 v99, v124, 3, 3
	s_lshl_b32 s9, s9, 6
	v_cvt_pk_bf16_f32 v66, v66, v67
	v_cvt_pk_bf16_f32 v67, v68, v69
	v_cvt_pk_bf16_f32 v68, v70, v71
	v_cvt_pk_bf16_f32 v69, v72, v73
	ds_write2_b64 v0, v[34:35], v[36:37] offset0:72 offset1:74
	v_cvt_pk_bf16_f32 v34, v58, v59
	v_cvt_pk_bf16_f32 v35, v60, v61
	v_cvt_pk_bf16_f32 v36, v62, v63
	v_cvt_pk_bf16_f32 v37, v64, v65
	s_add_i32 s8, s10, s8
	ds_write2_b64 v98, v[66:67], v[68:69] offset1:2
	v_cvt_pk_bf16_f32 v66, v74, v75
	v_cvt_pk_bf16_f32 v67, v76, v77
	v_cvt_pk_bf16_f32 v68, v78, v79
	v_cvt_pk_bf16_f32 v69, v80, v81
	ds_write2_b64 v0, v[34:35], v[36:37] offset0:76 offset1:78
	v_or_b32_e32 v34, s8, v99
	s_or_b32 s9, s9, s12
	ds_write2_b64 v98, v[66:67], v[68:69] offset0:4 offset1:6
	v_cvt_pk_bf16_f32 v66, v82, v83
	v_cvt_pk_bf16_f32 v67, v84, v85
	v_cvt_pk_bf16_f32 v68, v86, v87
	v_cvt_pk_bf16_f32 v69, v88, v89
	v_or_b32_e32 v36, s9, v100
	v_ashrrev_i32_e32 v35, 31, v34
	ds_write2_b64 v98, v[66:67], v[68:69] offset0:8 offset1:10
	v_cvt_pk_bf16_f32 v66, v90, v91
	v_cvt_pk_bf16_f32 v67, v92, v93
	v_cvt_pk_bf16_f32 v68, v94, v95
	v_cvt_pk_bf16_f32 v69, v96, v97
	v_min_i32_e32 v0, 0x8000, v34
	v_ashrrev_i32_e32 v37, 31, v36
	v_lshlrev_b64 v[34:35], 11, v[34:35]
	ds_write2_b64 v98, v[66:67], v[68:69] offset0:12 offset1:14
	v_lshl_add_u64 v[38:39], s[46:47], 0, v[34:35]
	v_lshlrev_b64 v[34:35], 1, v[36:37]
	s_waitcnt lgkmcnt(0)
	v_lshl_add_u64 v[64:65], v[38:39], 0, v[34:35]
	global_load_dwordx4 v[40:43], v[64:65], off
	v_ashrrev_i32_e32 v0, 11, v0
	v_mul_hi_i32_i24_e32 v39, 0x6000, v0
	v_mul_i32_i24_e32 v38, 0x6000, v0
	v_lshl_add_u64 v[38:39], s[36:37], 0, v[38:39]
	v_lshlrev_b64 v[36:37], 2, v[36:37]
	v_lshl_add_u64 v[38:39], v[38:39], 0, v[36:37]
	global_load_dwordx4 v[44:47], v[38:39], off
	global_load_dwordx4 v[48:51], v[38:39], off offset:16
	v_lshl_or_b32 v0, v100, 1, s11
	v_mad_u32_u24 v0, v99, s78, v0
	ds_read_b128 v[52:55], v0
	v_or_b32_e32 v38, 8, v99
	v_or_b32_e32 v66, s8, v38
	v_ashrrev_i32_e32 v67, 31, v66
	v_lshlrev_b64 v[56:57], 11, v[66:67]
	s_waitcnt lgkmcnt(0)
	v_lshlrev_b32_e32 v70, 16, v52
	v_and_b32_e32 v71, 0xffff0000, v52
	v_lshl_add_u64 v[56:57], s[46:47], 0, v[56:57]
	v_lshl_add_u64 v[68:69], v[56:57], 0, v[34:35]
	global_load_dwordx4 v[60:63], v[68:69], off
	v_min_i32_e32 v39, 0x8000, v66
	v_ashrrev_i32_e32 v39, 11, v39
	ds_read_b128 v[56:59], v0 offset:1152
	v_cvt_pk_bf16_f32 v2, v2, v3
	v_cvt_pk_bf16_f32 v3, v4, v5
	v_cvt_pk_bf16_f32 v4, v6, v7
	v_cvt_pk_bf16_f32 v5, v8, v9
	v_cvt_pk_bf16_f32 v6, v10, v11
	v_cvt_pk_bf16_f32 v7, v12, v13
	v_cvt_pk_bf16_f32 v8, v14, v15
	v_cvt_pk_bf16_f32 v9, v16, v17
	v_cvt_pk_bf16_f32 v10, v18, v19
	v_cvt_pk_bf16_f32 v11, v20, v21
	v_cvt_pk_bf16_f32 v12, v22, v23
	v_cvt_pk_bf16_f32 v13, v24, v25
	v_cvt_pk_bf16_f32 v14, v26, v27
	v_cvt_pk_bf16_f32 v15, v28, v29
	v_cvt_pk_bf16_f32 v16, v30, v31
	v_cvt_pk_bf16_f32 v17, v32, v33
	s_mov_b32 s40, s76
	s_waitcnt vmcnt(3)
	v_cvt_f32_f16_e32 v72, v40
	v_cvt_f32_f16_sdwa v73, v40 dst_sel:DWORD dst_unused:UNUSED_PAD src0_sel:WORD_1
	v_cvt_f32_f16_e32 v74, v41
	v_cvt_f32_f16_sdwa v75, v41 dst_sel:DWORD dst_unused:UNUSED_PAD src0_sel:WORD_1
	v_pk_mul_f32 v[40:41], v[72:73], s[30:31] op_sel_hi:[1,0]
	s_waitcnt vmcnt(2)
	v_pk_fma_f32 v[40:41], v[44:45], v[70:71], v[40:41]
	v_lshlrev_b32_e32 v44, 16, v53
	v_and_b32_e32 v45, 0xffff0000, v53
	v_pk_mul_f32 v[52:53], v[74:75], s[30:31] op_sel_hi:[1,0]
	v_cvt_pk_f16_f32 v40, v40, v41
	v_pk_fma_f32 v[44:45], v[46:47], v[44:45], v[52:53]
	v_cvt_f32_f16_e32 v46, v42
	v_cvt_f32_f16_sdwa v47, v42 dst_sel:DWORD dst_unused:UNUSED_PAD src0_sel:WORD_1
	v_cvt_pk_f16_f32 v41, v44, v45
	v_lshlrev_b32_e32 v44, 16, v54
	v_and_b32_e32 v45, 0xffff0000, v54
	v_pk_mul_f32 v[46:47], v[46:47], s[30:31] op_sel_hi:[1,0]
	s_waitcnt lgkmcnt(0)
;   DI void operator()(f32x16 (&acc)[2][MB], int wm, int wn, int r, int h) {
;     ...
;         for (int j = 0; j < 8; ++j) {
;           const int rowl = (lane >> 3) + 8 * j, ch = lane & 7;
;           if (rowl < ntok) {
;             const u32x4 yv = *(const u32x4*)(slab + rowl * 72 + ch * 8);
;             const int R = R0 + rowl;
;             const int mi = (R < NLAT) ? (R >> 11) : 16;
;             const int col = n0 + wn * 64 + ch * 8;
;             const float* g = gate + (size_t)mi * 6144 + col;
;             const f32x4n g0 = *(const f32x4n*)(g), g1 = *(const f32x4n*)(g + 4);
;             _Float16* xp = X + (size_t)R * 1024 + col;
;             const h8 xv = *(const h8*)xp;
;             const float y[8] = {__uint_as_float(yv.x << 16), __uint_as_float(yv.x & 0xffff0000u), __uint_as_float(yv.y << 16), __uint_as_float(yv.y & 0xffff0000u),
;                                 __uint_as_float(yv.z << 16), __uint_as_float(yv.z & 0xffff0000u), __uint_as_float(yv.w << 16), __uint_as_float(yv.w & 0xffff0000u)};
;             const float gg[8] = {g0.x, g0.y, g0.z, g0.w, g1.x, g1.y, g1.z, g1.w};
;             h8 o;
; #pragma unroll
;             for (int q = 0; q < 8; ++q) o[q] = (_Float16)(ALPHA * (float)xv[q] + gg[q] * y[q]);
;             *(h8*)xp = o;
	v_lshlrev_b32_e32 v54, 16, v56
	s_waitcnt vmcnt(1)
	v_pk_fma_f32 v[44:45], v[48:49], v[44:45], v[46:47]
	v_cvt_f32_f16_e32 v46, v43
	v_cvt_f32_f16_sdwa v47, v43 dst_sel:DWORD dst_unused:UNUSED_PAD src0_sel:WORD_1
	v_cvt_pk_f16_f32 v42, v44, v45
	v_lshlrev_b32_e32 v44, 16, v55
	v_and_b32_e32 v45, 0xffff0000, v55
	v_pk_mul_f32 v[46:47], v[46:47], s[30:31] op_sel_hi:[1,0]
	s_waitcnt vmcnt(0)
	v_cvt_f32_f16_e32 v66, v60
	v_pk_fma_f32 v[44:45], v[50:51], v[44:45], v[46:47]
	v_cvt_f32_f16_sdwa v67, v60 dst_sel:DWORD dst_unused:UNUSED_PAD src0_sel:WORD_1
	v_cvt_pk_f16_f32 v43, v44, v45
	global_store_dwordx4 v[64:65], v[40:43], off
	v_cvt_f32_f16_e32 v60, v61
	v_cvt_f32_f16_sdwa v61, v61 dst_sel:DWORD dst_unused:UNUSED_PAD src0_sel:WORD_1
	v_mul_hi_i32_i24_e32 v41, 0x6000, v39
	v_mul_i32_i24_e32 v40, 0x6000, v39
	v_lshl_add_u64 v[40:41], s[36:37], 0, v[40:41]
	v_lshl_add_u64 v[44:45], v[40:41], 0, v[36:37]
	global_load_dwordx4 v[40:43], v[44:45], off
	v_or_b32_e32 v39, 16, v99
	global_load_dwordx4 v[44:47], v[44:45], off offset:16
	v_or_b32_e32 v48, s8, v39
	v_min_i32_e32 v50, 0x8000, v48
	v_ashrrev_i32_e32 v49, 31, v48
	v_ashrrev_i32_e32 v50, 11, v50
	v_lshlrev_b64 v[48:49], 11, v[48:49]
	v_cvt_f32_f16_e32 v72, v62
	v_cvt_f32_f16_sdwa v73, v62 dst_sel:DWORD dst_unused:UNUSED_PAD src0_sel:WORD_1
	v_cvt_f32_f16_e32 v62, v63
	v_cvt_f32_f16_sdwa v63, v63 dst_sel:DWORD dst_unused:UNUSED_PAD src0_sel:WORD_1
	v_mul_hi_i32_i24_e32 v51, 0x6000, v50
	v_mul_i32_i24_e32 v50, 0x6000, v50
	v_lshl_add_u64 v[48:49], s[46:47], 0, v[48:49]
	v_lshl_add_u64 v[50:51], s[36:37], 0, v[50:51]
	v_lshl_add_u64 v[70:71], v[48:49], 0, v[34:35]
	v_lshl_add_u64 v[52:53], v[50:51], 0, v[36:37]
	global_load_dwordx4 v[48:51], v[70:71], off
	v_and_b32_e32 v55, 0xffff0000, v56
	v_lshlrev_b32_e32 v56, 16, v57
	v_and_b32_e32 v57, 0xffff0000, v57
	v_lshlrev_b32_e32 v64, 16, v58
	v_and_b32_e32 v65, 0xffff0000, v58
	v_lshlrev_b32_e32 v58, 16, v59
	v_and_b32_e32 v59, 0xffff0000, v59
	v_pk_mul_f32 v[66:67], v[66:67], s[30:31] op_sel_hi:[1,0]
	v_pk_mul_f32 v[60:61], v[60:61], s[30:31] op_sel_hi:[1,0]
	v_pk_mul_f32 v[72:73], v[72:73], s[30:31] op_sel_hi:[1,0]
	v_pk_mul_f32 v[62:63], v[62:63], s[30:31] op_sel_hi:[1,0]
	s_waitcnt vmcnt(2)
	v_pk_fma_f32 v[40:41], v[40:41], v[54:55], v[66:67]
	v_pk_fma_f32 v[42:43], v[42:43], v[56:57], v[60:61]
	s_waitcnt vmcnt(1)
	v_pk_fma_f32 v[44:45], v[44:45], v[64:65], v[72:73]
	v_pk_fma_f32 v[46:47], v[46:47], v[58:59], v[62:63]
	v_cvt_pk_f16_f32 v40, v40, v41
	v_cvt_pk_f16_f32 v41, v42, v43
	v_cvt_pk_f16_f32 v42, v44, v45
	v_cvt_pk_f16_f32 v43, v46, v47
	global_store_dwordx4 v[68:69], v[40:43], off
	global_load_dwordx4 v[42:45], v[52:53], off
	s_waitcnt vmcnt(2)
	v_cvt_f32_f16_e32 v76, v48
	global_load_dwordx4 v[52:55], v[52:53], off offset:16
	v_or_b32_e32 v40, 24, v99
	v_or_b32_e32 v46, s8, v40
	v_min_i32_e32 v41, 0x8000, v46
	v_ashrrev_i32_e32 v41, 11, v41
	v_ashrrev_i32_e32 v47, 31, v46
	v_mul_hi_i32_i24_e32 v57, 0x6000, v41
	v_mul_i32_i24_e32 v56, 0x6000, v41
	v_lshlrev_b64 v[46:47], 11, v[46:47]
	v_lshl_add_u64 v[60:61], s[36:37], 0, v[56:57]
	ds_read_b128 v[56:59], v0 offset:2304
	v_lshl_add_u64 v[46:47], s[46:47], 0, v[46:47]
	v_cvt_f32_f16_sdwa v77, v48 dst_sel:DWORD dst_unused:UNUSED_PAD src0_sel:WORD_1
	v_cvt_f32_f16_e32 v48, v49
	v_cvt_f32_f16_sdwa v49, v49 dst_sel:DWORD dst_unused:UNUSED_PAD src0_sel:WORD_1
	v_cvt_f32_f16_e32 v78, v50
	v_cvt_f32_f16_sdwa v79, v50 dst_sel:DWORD dst_unused:UNUSED_PAD src0_sel:WORD_1
	v_cvt_f32_f16_e32 v50, v51
	v_cvt_f32_f16_sdwa v51, v51 dst_sel:DWORD dst_unused:UNUSED_PAD src0_sel:WORD_1
	v_lshl_add_u64 v[68:69], v[46:47], 0, v[34:35]
	global_load_dwordx4 v[64:67], v[68:69], off
	s_waitcnt lgkmcnt(0)
	v_lshlrev_b32_e32 v72, 16, v56
	v_and_b32_e32 v73, 0xffff0000, v56
	v_lshlrev_b32_e32 v56, 16, v57
	v_and_b32_e32 v57, 0xffff0000, v57
	v_lshlrev_b32_e32 v74, 16, v58
	v_and_b32_e32 v75, 0xffff0000, v58
	v_lshlrev_b32_e32 v58, 16, v59
	v_and_b32_e32 v59, 0xffff0000, v59
	v_pk_mul_f32 v[76:77], v[76:77], s[30:31] op_sel_hi:[1,0]
	v_pk_mul_f32 v[48:49], v[48:49], s[30:31] op_sel_hi:[1,0]
	v_pk_mul_f32 v[78:79], v[78:79], s[30:31] op_sel_hi:[1,0]
	v_pk_mul_f32 v[50:51], v[50:51], s[30:31] op_sel_hi:[1,0]
	v_lshl_add_u64 v[46:47], v[60:61], 0, v[36:37]
	v_add_u32_e32 v41, s8, v99
	ds_read_b128 v[60:63], v0 offset:3456
	s_add_i32 s8, s8, 64
	v_or_b32_e32 v18, s8, v99
	v_ashrrev_i32_e32 v19, 31, v18
	v_lshlrev_b64 v[20:21], 11, v[18:19]
	v_lshl_add_u64 v[20:21], s[46:47], 0, v[20:21]
	v_lshl_add_u64 v[26:27], v[20:21], 0, v[34:35]
	s_waitcnt vmcnt(2)
	v_pk_fma_f32 v[42:43], v[42:43], v[72:73], v[76:77]
	v_pk_fma_f32 v[44:45], v[44:45], v[56:57], v[48:49]
	v_cvt_pk_f16_f32 v42, v42, v43
	v_cvt_pk_f16_f32 v43, v44, v45
	s_waitcnt lgkmcnt(0)
	v_lshlrev_b32_e32 v56, 16, v60
	v_and_b32_e32 v57, 0xffff0000, v60
	v_lshlrev_b32_e32 v60, 16, v62
	s_waitcnt vmcnt(1)
	v_pk_fma_f32 v[48:49], v[52:53], v[74:75], v[78:79]
	v_pk_fma_f32 v[50:51], v[54:55], v[58:59], v[50:51]
	v_cvt_pk_f16_f32 v44, v48, v49
	v_cvt_pk_f16_f32 v45, v50, v51
	global_store_dwordx4 v[70:71], v[42:45], off
	global_load_dwordx4 v[42:45], v[46:47], off
	v_add_u32_e32 v50, 32, v41
	global_load_dwordx4 v[46:49], v[46:47], off offset:16
	v_min_i32_e32 v52, 0x8000, v50
	v_ashrrev_i32_e32 v51, 31, v50
	v_ashrrev_i32_e32 v52, 11, v52
	v_lshlrev_b64 v[50:51], 11, v[50:51]
	v_mul_hi_i32_i24_e32 v53, 0x6000, v52
	v_mul_i32_i24_e32 v52, 0x6000, v52
	v_lshl_add_u64 v[50:51], s[46:47], 0, v[50:51]
	v_lshl_add_u64 v[52:53], s[36:37], 0, v[52:53]
	v_lshl_add_u64 v[70:71], v[50:51], 0, v[34:35]
	v_lshl_add_u64 v[54:55], v[52:53], 0, v[36:37]
	v_lshlrev_b32_e32 v58, 16, v61
	v_and_b32_e32 v59, 0xffff0000, v61
	s_waitcnt vmcnt(3)
;   DI void operator()(f32x16 (&acc)[2][MB], int wm, int wn, int r, int h) {
;     ...
;         for (int j = 0; j < 8; ++j) {
;           const int rowl = (lane >> 3) + 8 * j, ch = lane & 7;
;           if (rowl < ntok) {
;             const u32x4 yv = *(const u32x4*)(slab + rowl * 72 + ch * 8);
;             const int R = R0 + rowl;
;             const int mi = (R < NLAT) ? (R >> 11) : 16;
;             const int col = n0 + wn * 64 + ch * 8;
;             const float* g = gate + (size_t)mi * 6144 + col;
;             const f32x4n g0 = *(const f32x4n*)(g), g1 = *(const f32x4n*)(g + 4);
;             _Float16* xp = X + (size_t)R * 1024 + col;
;             const h8 xv = *(const h8*)xp;
;             const float y[8] = {__uint_as_float(yv.x << 16), __uint_as_float(yv.x & 0xffff0000u), __uint_as_float(yv.y << 16), __uint_as_float(yv.y & 0xffff0000u),
;                                 __uint_as_float(yv.z << 16), __uint_as_float(yv.z & 0xffff0000u), __uint_as_float(yv.w << 16), __uint_as_float(yv.w & 0xffff0000u)};
;             const float gg[8] = {g0.x, g0.y, g0.z, g0.w, g1.x, g1.y, g1.z, g1.w};
;             h8 o;
; #pragma unroll
;             for (int q = 0; q < 8; ++q) o[q] = (_Float16)(ALPHA * (float)xv[q] + gg[q] * y[q]);
;             *(h8*)xp = o;
	v_cvt_f32_f16_e32 v50, v64
	v_cvt_f32_f16_sdwa v51, v64 dst_sel:DWORD dst_unused:UNUSED_PAD src0_sel:WORD_1
	v_cvt_f32_f16_e32 v52, v65
	v_cvt_f32_f16_sdwa v53, v65 dst_sel:DWORD dst_unused:UNUSED_PAD src0_sel:WORD_1
	v_cvt_f32_f16_e32 v64, v66
	v_cvt_f32_f16_sdwa v65, v66 dst_sel:DWORD dst_unused:UNUSED_PAD src0_sel:WORD_1
	v_cvt_f32_f16_e32 v66, v67
	v_cvt_f32_f16_sdwa v67, v67 dst_sel:DWORD dst_unused:UNUSED_PAD src0_sel:WORD_1
	v_pk_mul_f32 v[72:73], v[50:51], s[30:31] op_sel_hi:[1,0]
	v_pk_mul_f32 v[74:75], v[52:53], s[30:31] op_sel_hi:[1,0]
	global_load_dwordx4 v[50:53], v[70:71], off
	v_and_b32_e32 v61, 0xffff0000, v62
	v_lshlrev_b32_e32 v62, 16, v63
	v_and_b32_e32 v63, 0xffff0000, v63
	v_pk_mul_f32 v[64:65], v[64:65], s[30:31] op_sel_hi:[1,0]
	v_pk_mul_f32 v[66:67], v[66:67], s[30:31] op_sel_hi:[1,0]
	s_waitcnt vmcnt(2)
	v_pk_fma_f32 v[42:43], v[42:43], v[56:57], v[72:73]
	v_pk_fma_f32 v[44:45], v[44:45], v[58:59], v[74:75]
	s_waitcnt vmcnt(1)
	v_pk_fma_f32 v[46:47], v[46:47], v[60:61], v[64:65]
	v_pk_fma_f32 v[48:49], v[48:49], v[62:63], v[66:67]
	v_cvt_pk_f16_f32 v42, v42, v43
	v_cvt_pk_f16_f32 v43, v44, v45
	v_cvt_pk_f16_f32 v44, v46, v47
	v_cvt_pk_f16_f32 v45, v48, v49
	global_store_dwordx4 v[68:69], v[42:45], off
	global_load_dwordx4 v[42:45], v[54:55], off
	s_waitcnt vmcnt(2)
	v_cvt_f32_f16_e32 v76, v50
	global_load_dwordx4 v[46:49], v[54:55], off offset:16
	v_add_u32_e32 v54, 40, v41
	v_min_i32_e32 v56, 0x8000, v54
	v_ashrrev_i32_e32 v55, 31, v54
	v_ashrrev_i32_e32 v56, 11, v56
	v_lshlrev_b64 v[54:55], 11, v[54:55]
	v_mul_hi_i32_i24_e32 v59, 0x6000, v56
	v_mul_i32_i24_e32 v58, 0x6000, v56
	v_lshl_add_u64 v[60:61], s[46:47], 0, v[54:55]
	ds_read_b128 v[54:57], v0 offset:4608
	v_cvt_f32_f16_sdwa v77, v50 dst_sel:DWORD dst_unused:UNUSED_PAD src0_sel:WORD_1
	v_cvt_f32_f16_e32 v50, v51
	v_cvt_f32_f16_sdwa v51, v51 dst_sel:DWORD dst_unused:UNUSED_PAD src0_sel:WORD_1
	v_cvt_f32_f16_e32 v78, v52
	v_cvt_f32_f16_sdwa v79, v52 dst_sel:DWORD dst_unused:UNUSED_PAD src0_sel:WORD_1
	v_cvt_f32_f16_e32 v52, v53
	v_cvt_f32_f16_sdwa v53, v53 dst_sel:DWORD dst_unused:UNUSED_PAD src0_sel:WORD_1
	v_lshl_add_u64 v[64:65], v[60:61], 0, v[34:35]
	s_waitcnt lgkmcnt(0)
	v_lshlrev_b32_e32 v66, 16, v54
	v_and_b32_e32 v67, 0xffff0000, v54
	v_lshlrev_b32_e32 v68, 16, v55
	v_and_b32_e32 v69, 0xffff0000, v55
	v_lshlrev_b32_e32 v72, 16, v56
	v_and_b32_e32 v73, 0xffff0000, v56
	v_lshlrev_b32_e32 v74, 16, v57
	v_and_b32_e32 v75, 0xffff0000, v57
	global_load_dwordx4 v[54:57], v[64:65], off
	v_pk_mul_f32 v[76:77], v[76:77], s[30:31] op_sel_hi:[1,0]
	v_pk_mul_f32 v[50:51], v[50:51], s[30:31] op_sel_hi:[1,0]
	v_pk_mul_f32 v[78:79], v[78:79], s[30:31] op_sel_hi:[1,0]
	v_pk_mul_f32 v[52:53], v[52:53], s[30:31] op_sel_hi:[1,0]
	v_lshl_add_u64 v[62:63], s[36:37], 0, v[58:59]
	v_lshl_add_u64 v[62:63], v[62:63], 0, v[36:37]
	ds_read_b128 v[58:61], v0 offset:5760
	s_waitcnt vmcnt(2)
	v_pk_fma_f32 v[42:43], v[42:43], v[66:67], v[76:77]
	v_pk_fma_f32 v[44:45], v[44:45], v[68:69], v[50:51]
	v_cvt_pk_f16_f32 v42, v42, v43
	v_cvt_pk_f16_f32 v43, v44, v45
	v_add_u32_e32 v50, 48, v41
	v_ashrrev_i32_e32 v51, 31, v50
	s_waitcnt lgkmcnt(0)
	v_lshlrev_b32_e32 v68, 16, v58
	v_and_b32_e32 v69, 0xffff0000, v58
	v_lshlrev_b32_e32 v58, 16, v59
	v_and_b32_e32 v59, 0xffff0000, v59
	s_waitcnt vmcnt(1)
	v_pk_fma_f32 v[46:47], v[46:47], v[72:73], v[78:79]
	v_pk_fma_f32 v[48:49], v[48:49], v[74:75], v[52:53]
	v_cvt_pk_f16_f32 v44, v46, v47
	v_cvt_pk_f16_f32 v45, v48, v49
	global_store_dwordx4 v[70:71], v[42:45], off
	global_load_dwordx4 v[42:45], v[62:63], off
	v_min_i32_e32 v52, 0x8000, v50
	global_load_dwordx4 v[46:49], v[62:63], off offset:16
	v_ashrrev_i32_e32 v52, 11, v52
	v_lshlrev_b64 v[50:51], 11, v[50:51]
	v_mul_hi_i32_i24_e32 v53, 0x6000, v52
	v_mul_i32_i24_e32 v52, 0x6000, v52
	v_lshl_add_u64 v[50:51], s[46:47], 0, v[50:51]
	v_lshl_add_u64 v[52:53], s[36:37], 0, v[52:53]
	v_lshl_add_u64 v[62:63], v[50:51], 0, v[34:35]
	v_lshl_add_u64 v[66:67], v[52:53], 0, v[36:37]
	global_load_dwordx4 v[50:53], v[62:63], off
	v_lshlrev_b32_e32 v70, 16, v60
	v_and_b32_e32 v71, 0xffff0000, v60
	v_lshlrev_b32_e32 v60, 16, v61
	v_and_b32_e32 v61, 0xffff0000, v61
	s_waitcnt vmcnt(4)
	v_cvt_f32_f16_e32 v72, v54
	v_cvt_f32_f16_sdwa v73, v54 dst_sel:DWORD dst_unused:UNUSED_PAD src0_sel:WORD_1
	v_cvt_f32_f16_e32 v54, v55
	v_cvt_f32_f16_sdwa v55, v55 dst_sel:DWORD dst_unused:UNUSED_PAD src0_sel:WORD_1
	v_cvt_f32_f16_e32 v74, v56
	v_cvt_f32_f16_sdwa v75, v56 dst_sel:DWORD dst_unused:UNUSED_PAD src0_sel:WORD_1
	v_cvt_f32_f16_e32 v56, v57
	v_cvt_f32_f16_sdwa v57, v57 dst_sel:DWORD dst_unused:UNUSED_PAD src0_sel:WORD_1
	v_pk_mul_f32 v[72:73], v[72:73], s[30:31] op_sel_hi:[1,0]
	v_pk_mul_f32 v[54:55], v[54:55], s[30:31] op_sel_hi:[1,0]
	v_pk_mul_f32 v[74:75], v[74:75], s[30:31] op_sel_hi:[1,0]
	v_pk_mul_f32 v[56:57], v[56:57], s[30:31] op_sel_hi:[1,0]
	s_waitcnt vmcnt(2)
	v_pk_fma_f32 v[42:43], v[42:43], v[68:69], v[72:73]
	v_pk_fma_f32 v[44:45], v[44:45], v[58:59], v[54:55]
	s_waitcnt vmcnt(1)
	v_pk_fma_f32 v[46:47], v[46:47], v[70:71], v[74:75]
	v_pk_fma_f32 v[48:49], v[48:49], v[60:61], v[56:57]
	v_cvt_pk_f16_f32 v42, v42, v43
	v_cvt_pk_f16_f32 v43, v44, v45
	v_cvt_pk_f16_f32 v44, v46, v47
	v_cvt_pk_f16_f32 v45, v48, v49
	global_store_dwordx4 v[64:65], v[42:45], off
	global_load_dwordx4 v[42:45], v[66:67], off
	v_add_u32_e32 v54, 56, v41
	global_load_dwordx4 v[46:49], v[66:67], off offset:16
	v_ashrrev_i32_e32 v55, 31, v54
	v_min_i32_e32 v41, 0x8000, v54
	v_lshlrev_b64 v[54:55], 11, v[54:55]
	v_lshl_add_u64 v[60:61], s[46:47], 0, v[54:55]
	ds_read_b128 v[54:57], v0 offset:6912
	s_waitcnt vmcnt(3)
; DI unsigned pack2(float a, float b) { f2 v = {a, b}; bf2 r = __builtin_convertvector(v, bf2); return __builtin_bit_cast(unsigned, r); }
;   DI void operator()(f32x16 (&acc)[2][MB], int wm, int wn, int r, int h) {
;     ...
;     for (int mb = 0; mb < MB; ++mb) {
;       const int tokl = (mb & 1) * 32 + r;
; #pragma unroll
;       for (int nb = 0; nb < 2; ++nb)
; #pragma unroll
;         for (int ig = 0; ig < 4; ++ig) {
;           u32x2 o;
;           o.x = pack2(acc[nb][mb][ig * 4 + 0], acc[nb][mb][ig * 4 + 1]);
;           o.y = pack2(acc[nb][mb][ig * 4 + 2], acc[nb][mb][ig * 4 + 3]);
;           *(u32x2*)(slab + tokl * 72 + nb * 32 + ig * 8 + h * 4) = o;
;         }
;       if ((mb & 1) || mb == MB - 1) {
;         asm volatile("s_waitcnt lgkmcnt(0)" ::: "memory");
;         const int ntok = (mb & 1) ? 64 : 32;
;         const int R0 = row0 + wm * (32 * MB) + (mb >> 1) * 64;
; #pragma unroll
;         for (int j = 0; j < 8; ++j) {
;           const int rowl = (lane >> 3) + 8 * j, ch = lane & 7;
;           if (rowl < ntok) {
;             const u32x4 yv = *(const u32x4*)(slab + rowl * 72 + ch * 8);
;             const int R = R0 + rowl;
;             const int mi = (R < NLAT) ? (R >> 11) : 16;
;             const int col = n0 + wn * 64 + ch * 8;
;             const float* g = gate + (size_t)mi * 6144 + col;
;             const f32x4n g0 = *(const f32x4n*)(g), g1 = *(const f32x4n*)(g + 4);
;             _Float16* xp = X + (size_t)R * 1024 + col;
;             const h8 xv = *(const h8*)xp;
;             const float y[8] = {__uint_as_float(yv.x << 16), __uint_as_float(yv.x & 0xffff0000u), __uint_as_float(yv.y << 16), __uint_as_float(yv.y & 0xffff0000u),
;                                 __uint_as_float(yv.z << 16), __uint_as_float(yv.z & 0xffff0000u), __uint_as_float(yv.w << 16), __uint_as_float(yv.w & 0xffff0000u)};
;             const float gg[8] = {g0.x, g0.y, g0.z, g0.w, g1.x, g1.y, g1.z, g1.w};
;             h8 o;
; #pragma unroll
;             for (int q = 0; q < 8; ++q) o[q] = (_Float16)(ALPHA * (float)xv[q] + gg[q] * y[q]);
;             *(h8*)xp = o;
	v_cvt_f32_f16_e32 v76, v50
	v_cvt_f32_f16_sdwa v77, v50 dst_sel:DWORD dst_unused:UNUSED_PAD src0_sel:WORD_1
	v_cvt_f32_f16_e32 v50, v51
	v_cvt_f32_f16_sdwa v51, v51 dst_sel:DWORD dst_unused:UNUSED_PAD src0_sel:WORD_1
	v_cvt_f32_f16_e32 v78, v52
	v_cvt_f32_f16_sdwa v79, v52 dst_sel:DWORD dst_unused:UNUSED_PAD src0_sel:WORD_1
	v_cvt_f32_f16_e32 v52, v53
	v_cvt_f32_f16_sdwa v53, v53 dst_sel:DWORD dst_unused:UNUSED_PAD src0_sel:WORD_1
	v_lshl_add_u64 v[66:67], v[60:61], 0, v[34:35]
	s_waitcnt lgkmcnt(0)
	v_lshlrev_b32_e32 v68, 16, v54
	v_and_b32_e32 v69, 0xffff0000, v54
	v_lshlrev_b32_e32 v70, 16, v55
	v_and_b32_e32 v71, 0xffff0000, v55
	v_lshlrev_b32_e32 v72, 16, v56
	v_and_b32_e32 v73, 0xffff0000, v56
	v_lshlrev_b32_e32 v74, 16, v57
	v_and_b32_e32 v75, 0xffff0000, v57
	global_load_dwordx4 v[54:57], v[66:67], off
	v_ashrrev_i32_e32 v41, 11, v41
	v_pk_mul_f32 v[76:77], v[76:77], s[30:31] op_sel_hi:[1,0]
	v_pk_mul_f32 v[50:51], v[50:51], s[30:31] op_sel_hi:[1,0]
	v_pk_mul_f32 v[78:79], v[78:79], s[30:31] op_sel_hi:[1,0]
	v_pk_mul_f32 v[52:53], v[52:53], s[30:31] op_sel_hi:[1,0]
	v_mul_hi_i32_i24_e32 v59, 0x6000, v41
	v_mul_i32_i24_e32 v58, 0x6000, v41
	v_lshl_add_u64 v[64:65], s[36:37], 0, v[58:59]
	v_lshl_add_u64 v[64:65], v[64:65], 0, v[36:37]
	ds_read_b128 v[58:61], v0 offset:8064
	ds_write2_b64 v98, v[10:11], v[12:13] offset0:8 offset1:10
	ds_write2_b64 v98, v[14:15], v[16:17] offset0:12 offset1:14
	ds_write2_b64 v98, v[2:3], v[4:5] offset1:2
	ds_write2_b64 v98, v[6:7], v[8:9] offset0:4 offset1:6
	s_waitcnt lgkmcnt(4)
	v_lshlrev_b32_e32 v2, 16, v58
	v_and_b32_e32 v3, 0xffff0000, v58
	v_lshlrev_b32_e32 v4, 16, v59
	v_and_b32_e32 v5, 0xffff0000, v59
	v_lshlrev_b32_e32 v6, 16, v60
	v_and_b32_e32 v7, 0xffff0000, v60
	v_lshlrev_b32_e32 v8, 16, v61
	v_and_b32_e32 v9, 0xffff0000, v61
	s_waitcnt vmcnt(2)
	v_pk_fma_f32 v[42:43], v[42:43], v[68:69], v[76:77]
	v_pk_fma_f32 v[44:45], v[44:45], v[70:71], v[50:51]
	s_waitcnt vmcnt(1)
	v_pk_fma_f32 v[46:47], v[46:47], v[72:73], v[78:79]
	v_pk_fma_f32 v[48:49], v[48:49], v[74:75], v[52:53]
	v_cvt_pk_f16_f32 v42, v42, v43
	v_cvt_pk_f16_f32 v43, v44, v45
	v_cvt_pk_f16_f32 v44, v46, v47
	v_cvt_pk_f16_f32 v45, v48, v49
	global_store_dwordx4 v[62:63], v[42:45], off
	global_load_dwordx4 v[42:45], v[64:65], off
	s_waitcnt vmcnt(2)
	v_cvt_f32_f16_e32 v10, v54
	global_load_dwordx4 v[46:49], v[64:65], off offset:16
	v_cvt_f32_f16_sdwa v11, v54 dst_sel:DWORD dst_unused:UNUSED_PAD src0_sel:WORD_1
	v_cvt_f32_f16_e32 v12, v55
	v_cvt_f32_f16_sdwa v13, v55 dst_sel:DWORD dst_unused:UNUSED_PAD src0_sel:WORD_1
	v_cvt_f32_f16_e32 v14, v56
	v_cvt_f32_f16_sdwa v15, v56 dst_sel:DWORD dst_unused:UNUSED_PAD src0_sel:WORD_1
	v_cvt_f32_f16_e32 v16, v57
	v_cvt_f32_f16_sdwa v17, v57 dst_sel:DWORD dst_unused:UNUSED_PAD src0_sel:WORD_1
	v_pk_mul_f32 v[10:11], v[10:11], s[30:31] op_sel_hi:[1,0]
	v_pk_mul_f32 v[12:13], v[12:13], s[30:31] op_sel_hi:[1,0]
	v_pk_mul_f32 v[14:15], v[14:15], s[30:31] op_sel_hi:[1,0]
	v_pk_mul_f32 v[16:17], v[16:17], s[30:31] op_sel_hi:[1,0]
	s_waitcnt vmcnt(1)
	v_pk_fma_f32 v[2:3], v[42:43], v[2:3], v[10:11]
	v_pk_fma_f32 v[4:5], v[44:45], v[4:5], v[12:13]
	v_cvt_pk_f16_f32 v2, v2, v3
	v_cvt_pk_f16_f32 v3, v4, v5
	s_waitcnt vmcnt(0)
	v_pk_fma_f32 v[6:7], v[46:47], v[6:7], v[14:15]
	v_pk_fma_f32 v[8:9], v[48:49], v[8:9], v[16:17]
	v_cvt_pk_f16_f32 v4, v6, v7
	v_cvt_pk_f16_f32 v5, v8, v9
	global_store_dwordx4 v[66:67], v[2:5], off
	s_waitcnt lgkmcnt(0)
	global_load_dwordx4 v[2:5], v[26:27], off
	v_min_i32_e32 v6, 0x8000, v18
	v_ashrrev_i32_e32 v6, 11, v6
	v_mul_hi_i32_i24_e32 v7, 0x6000, v6
	v_mul_i32_i24_e32 v6, 0x6000, v6
	v_lshl_add_u64 v[6:7], s[36:37], 0, v[6:7]
	v_lshl_add_u64 v[10:11], v[6:7], 0, v[36:37]
	global_load_dwordx4 v[6:9], v[10:11], off
	v_or_b32_e32 v14, s8, v38
	global_load_dwordx4 v[10:13], v[10:11], off offset:16
	v_min_i32_e32 v16, 0x8000, v14
	v_ashrrev_i32_e32 v15, 31, v14
	v_ashrrev_i32_e32 v16, 11, v16
	v_lshlrev_b64 v[14:15], 11, v[14:15]
	v_mul_hi_i32_i24_e32 v17, 0x6000, v16
	v_mul_i32_i24_e32 v16, 0x6000, v16
	v_lshl_add_u64 v[18:19], s[46:47], 0, v[14:15]
	v_lshl_add_u64 v[20:21], s[36:37], 0, v[16:17]
	ds_read_b128 v[14:17], v0
	v_lshl_add_u64 v[28:29], v[18:19], 0, v[34:35]
	global_load_dwordx4 v[22:25], v[28:29], off
	v_lshl_add_u64 v[30:31], v[20:21], 0, v[36:37]
	ds_read_b128 v[18:21], v0 offset:1152
	s_waitcnt lgkmcnt(1)
	v_lshlrev_b32_e32 v32, 16, v14
	v_and_b32_e32 v33, 0xffff0000, v14
	v_lshlrev_b32_e32 v14, 16, v15
	v_and_b32_e32 v15, 0xffff0000, v15
	v_lshlrev_b32_e32 v42, 16, v16
	v_and_b32_e32 v43, 0xffff0000, v16
	v_lshlrev_b32_e32 v16, 16, v17
	v_and_b32_e32 v17, 0xffff0000, v17
	s_waitcnt vmcnt(3)
	v_cvt_f32_f16_e32 v44, v2
	v_cvt_f32_f16_sdwa v45, v2 dst_sel:DWORD dst_unused:UNUSED_PAD src0_sel:WORD_1
	v_cvt_f32_f16_e32 v2, v3
	v_cvt_f32_f16_sdwa v3, v3 dst_sel:DWORD dst_unused:UNUSED_PAD src0_sel:WORD_1
	v_cvt_f32_f16_e32 v46, v4
	v_cvt_f32_f16_sdwa v47, v4 dst_sel:DWORD dst_unused:UNUSED_PAD src0_sel:WORD_1
	v_cvt_f32_f16_e32 v4, v5
	v_cvt_f32_f16_sdwa v5, v5 dst_sel:DWORD dst_unused:UNUSED_PAD src0_sel:WORD_1
	v_pk_mul_f32 v[44:45], v[44:45], s[30:31] op_sel_hi:[1,0]
	v_pk_mul_f32 v[2:3], v[2:3], s[30:31] op_sel_hi:[1,0]
	v_pk_mul_f32 v[46:47], v[46:47], s[30:31] op_sel_hi:[1,0]
	v_pk_mul_f32 v[4:5], v[4:5], s[30:31] op_sel_hi:[1,0]
	s_waitcnt vmcnt(2)
	v_pk_fma_f32 v[6:7], v[6:7], v[32:33], v[44:45]
	v_pk_fma_f32 v[8:9], v[8:9], v[14:15], v[2:3]
	s_waitcnt vmcnt(1)
;   DI void operator()(f32x16 (&acc)[2][MB], int wm, int wn, int r, int h) {
;     ...
;         for (int j = 0; j < 8; ++j) {
;           const int rowl = (lane >> 3) + 8 * j, ch = lane & 7;
;           if (rowl < ntok) {
;             const u32x4 yv = *(const u32x4*)(slab + rowl * 72 + ch * 8);
;             const int R = R0 + rowl;
;             const int mi = (R < NLAT) ? (R >> 11) : 16;
;             const int col = n0 + wn * 64 + ch * 8;
;             const float* g = gate + (size_t)mi * 6144 + col;
;             const f32x4n g0 = *(const f32x4n*)(g), g1 = *(const f32x4n*)(g + 4);
;             _Float16* xp = X + (size_t)R * 1024 + col;
;             const h8 xv = *(const h8*)xp;
;             const float y[8] = {__uint_as_float(yv.x << 16), __uint_as_float(yv.x & 0xffff0000u), __uint_as_float(yv.y << 16), __uint_as_float(yv.y & 0xffff0000u),
;                                 __uint_as_float(yv.z << 16), __uint_as_float(yv.z & 0xffff0000u), __uint_as_float(yv.w << 16), __uint_as_float(yv.w & 0xffff0000u)};
;             const float gg[8] = {g0.x, g0.y, g0.z, g0.w, g1.x, g1.y, g1.z, g1.w};
;             h8 o;
; #pragma unroll
;             for (int q = 0; q < 8; ++q) o[q] = (_Float16)(ALPHA * (float)xv[q] + gg[q] * y[q]);
;             *(h8*)xp = o;
;           }
;         }
;       }
;     }
;     __syncthreads();
	v_pk_fma_f32 v[10:11], v[10:11], v[42:43], v[46:47]
	v_pk_fma_f32 v[12:13], v[12:13], v[16:17], v[4:5]
	v_cvt_pk_f16_f32 v2, v6, v7
	v_cvt_pk_f16_f32 v3, v8, v9
	v_cvt_pk_f16_f32 v4, v10, v11
	v_cvt_pk_f16_f32 v5, v12, v13
	global_store_dwordx4 v[26:27], v[2:5], off
	global_load_dwordx4 v[2:5], v[30:31], off
	v_or_b32_e32 v10, s8, v39
	global_load_dwordx4 v[6:9], v[30:31], off offset:16
	v_min_i32_e32 v12, 0x8000, v10
	v_ashrrev_i32_e32 v11, 31, v10
	v_ashrrev_i32_e32 v12, 11, v12
	v_lshlrev_b64 v[10:11], 11, v[10:11]
	s_waitcnt vmcnt(3)
	v_cvt_f32_f16_e32 v32, v22
	v_cvt_f32_f16_sdwa v33, v22 dst_sel:DWORD dst_unused:UNUSED_PAD src0_sel:WORD_1
	v_cvt_f32_f16_e32 v22, v23
	v_cvt_f32_f16_sdwa v23, v23 dst_sel:DWORD dst_unused:UNUSED_PAD src0_sel:WORD_1
	v_cvt_f32_f16_e32 v38, v24
	v_cvt_f32_f16_sdwa v39, v24 dst_sel:DWORD dst_unused:UNUSED_PAD src0_sel:WORD_1
	v_cvt_f32_f16_e32 v24, v25
	v_cvt_f32_f16_sdwa v25, v25 dst_sel:DWORD dst_unused:UNUSED_PAD src0_sel:WORD_1
	v_mul_hi_i32_i24_e32 v13, 0x6000, v12
	v_mul_i32_i24_e32 v12, 0x6000, v12
	v_lshl_add_u64 v[10:11], s[46:47], 0, v[10:11]
	v_lshl_add_u64 v[12:13], s[36:37], 0, v[12:13]
	v_lshl_add_u64 v[26:27], v[10:11], 0, v[34:35]
	v_lshl_add_u64 v[14:15], v[12:13], 0, v[36:37]
	global_load_dwordx4 v[10:13], v[26:27], off
	s_waitcnt lgkmcnt(0)
	v_lshlrev_b32_e32 v16, 16, v18
	v_and_b32_e32 v17, 0xffff0000, v18
	v_lshlrev_b32_e32 v18, 16, v19
	v_and_b32_e32 v19, 0xffff0000, v19
	v_lshlrev_b32_e32 v30, 16, v20
	v_and_b32_e32 v31, 0xffff0000, v20
	v_lshlrev_b32_e32 v20, 16, v21
	v_and_b32_e32 v21, 0xffff0000, v21
	v_pk_mul_f32 v[32:33], v[32:33], s[30:31] op_sel_hi:[1,0]
	v_pk_mul_f32 v[22:23], v[22:23], s[30:31] op_sel_hi:[1,0]
	v_pk_mul_f32 v[38:39], v[38:39], s[30:31] op_sel_hi:[1,0]
	v_pk_mul_f32 v[24:25], v[24:25], s[30:31] op_sel_hi:[1,0]
	s_waitcnt vmcnt(2)
	v_pk_fma_f32 v[2:3], v[2:3], v[16:17], v[32:33]
	v_pk_fma_f32 v[4:5], v[4:5], v[18:19], v[22:23]
	s_waitcnt vmcnt(1)
	v_pk_fma_f32 v[6:7], v[6:7], v[30:31], v[38:39]
	v_pk_fma_f32 v[8:9], v[8:9], v[20:21], v[24:25]
	v_cvt_pk_f16_f32 v2, v2, v3
	v_cvt_pk_f16_f32 v3, v4, v5
	v_cvt_pk_f16_f32 v4, v6, v7
	v_cvt_pk_f16_f32 v5, v8, v9
	global_store_dwordx4 v[28:29], v[2:5], off
	global_load_dwordx4 v[2:5], v[14:15], off
	s_waitcnt vmcnt(2)
	v_cvt_f32_f16_e32 v38, v12
	global_load_dwordx4 v[6:9], v[14:15], off offset:16
	v_or_b32_e32 v14, s8, v40
	v_min_i32_e32 v16, 0x8000, v14
	v_ashrrev_i32_e32 v15, 31, v14
	v_ashrrev_i32_e32 v16, 11, v16
	v_lshlrev_b64 v[14:15], 11, v[14:15]
	v_mul_hi_i32_i24_e32 v17, 0x6000, v16
	v_mul_i32_i24_e32 v16, 0x6000, v16
	v_lshl_add_u64 v[18:19], s[46:47], 0, v[14:15]
	v_lshl_add_u64 v[20:21], s[36:37], 0, v[16:17]
	ds_read_b128 v[14:17], v0 offset:2304
	v_lshl_add_u64 v[30:31], v[20:21], 0, v[36:37]
	v_cvt_f32_f16_e32 v36, v10
	v_cvt_f32_f16_sdwa v37, v10 dst_sel:DWORD dst_unused:UNUSED_PAD src0_sel:WORD_1
	v_cvt_f32_f16_e32 v10, v11
	v_cvt_f32_f16_sdwa v11, v11 dst_sel:DWORD dst_unused:UNUSED_PAD src0_sel:WORD_1
	v_cvt_f32_f16_sdwa v39, v12 dst_sel:DWORD dst_unused:UNUSED_PAD src0_sel:WORD_1
	v_cvt_f32_f16_e32 v12, v13
	v_cvt_f32_f16_sdwa v13, v13 dst_sel:DWORD dst_unused:UNUSED_PAD src0_sel:WORD_1
	v_lshl_add_u64 v[28:29], v[18:19], 0, v[34:35]
	global_load_dwordx4 v[22:25], v[28:29], off
	s_waitcnt lgkmcnt(0)
	v_lshlrev_b32_e32 v32, 16, v14
	v_and_b32_e32 v33, 0xffff0000, v14
	v_lshlrev_b32_e32 v14, 16, v15
	v_and_b32_e32 v15, 0xffff0000, v15
	v_lshlrev_b32_e32 v34, 16, v16
	v_and_b32_e32 v35, 0xffff0000, v16
	v_lshlrev_b32_e32 v16, 16, v17
	v_and_b32_e32 v17, 0xffff0000, v17
	v_pk_mul_f32 v[36:37], v[36:37], s[30:31] op_sel_hi:[1,0]
	v_pk_mul_f32 v[10:11], v[10:11], s[30:31] op_sel_hi:[1,0]
	v_pk_mul_f32 v[38:39], v[38:39], s[30:31] op_sel_hi:[1,0]
	v_pk_mul_f32 v[12:13], v[12:13], s[30:31] op_sel_hi:[1,0]
	ds_read_b128 v[18:21], v0 offset:3456
	s_waitcnt vmcnt(2)
	v_pk_fma_f32 v[2:3], v[2:3], v[32:33], v[36:37]
	v_pk_fma_f32 v[4:5], v[4:5], v[14:15], v[10:11]
	v_cvt_pk_f16_f32 v2, v2, v3
	v_cvt_pk_f16_f32 v3, v4, v5
	s_waitcnt lgkmcnt(0)
	v_lshlrev_b32_e32 v10, 16, v18
	v_and_b32_e32 v11, 0xffff0000, v18
	v_lshlrev_b32_e32 v14, 16, v20
	v_and_b32_e32 v15, 0xffff0000, v20
	s_waitcnt vmcnt(1)
	v_pk_fma_f32 v[6:7], v[6:7], v[34:35], v[38:39]
	v_pk_fma_f32 v[8:9], v[8:9], v[16:17], v[12:13]
	v_cvt_pk_f16_f32 v4, v6, v7
	v_cvt_pk_f16_f32 v5, v8, v9
	global_store_dwordx4 v[26:27], v[2:5], off
	global_load_dwordx4 v[2:5], v[30:31], off
	v_lshlrev_b32_e32 v12, 16, v19
	global_load_dwordx4 v[6:9], v[30:31], off offset:16
	v_and_b32_e32 v13, 0xffff0000, v19
	v_lshlrev_b32_e32 v16, 16, v21
	v_and_b32_e32 v17, 0xffff0000, v21
	s_waitcnt vmcnt(3)
	v_cvt_f32_f16_e32 v18, v22
	v_cvt_f32_f16_sdwa v19, v22 dst_sel:DWORD dst_unused:UNUSED_PAD src0_sel:WORD_1
	v_cvt_f32_f16_e32 v20, v23
	v_cvt_f32_f16_sdwa v21, v23 dst_sel:DWORD dst_unused:UNUSED_PAD src0_sel:WORD_1
	v_cvt_f32_f16_e32 v22, v24
	v_cvt_f32_f16_sdwa v23, v24 dst_sel:DWORD dst_unused:UNUSED_PAD src0_sel:WORD_1
	v_cvt_f32_f16_e32 v24, v25
	v_cvt_f32_f16_sdwa v25, v25 dst_sel:DWORD dst_unused:UNUSED_PAD src0_sel:WORD_1
	v_pk_mul_f32 v[18:19], v[18:19], s[30:31] op_sel_hi:[1,0]
	v_pk_mul_f32 v[20:21], v[20:21], s[30:31] op_sel_hi:[1,0]
	v_pk_mul_f32 v[22:23], v[22:23], s[30:31] op_sel_hi:[1,0]
	v_pk_mul_f32 v[24:25], v[24:25], s[30:31] op_sel_hi:[1,0]
	s_waitcnt vmcnt(1)
	v_pk_fma_f32 v[2:3], v[2:3], v[10:11], v[18:19]
	v_pk_fma_f32 v[4:5], v[4:5], v[12:13], v[20:21]
	s_waitcnt vmcnt(0)
	v_pk_fma_f32 v[6:7], v[6:7], v[14:15], v[22:23]
	v_pk_fma_f32 v[8:9], v[8:9], v[16:17], v[24:25]
	v_cvt_pk_f16_f32 v2, v2, v3
	v_cvt_pk_f16_f32 v3, v4, v5
	v_cvt_pk_f16_f32 v4, v6, v7
	v_cvt_pk_f16_f32 v5, v8, v9
	global_store_dwordx4 v[28:29], v[2:5], off
	s_barrier
	s_branch .LBB0_853

; template <int MB, class Epi>
; DI void gemm_tile(const u16* __restrict__ A, int lda, int row0, int Mrows, const u16* __restrict__ Bt, int ldb, int K, char* smem, Epi& epi, int rot) {
;     ...
;   for (int kt = 0; kt < KT; ++kt) {
;     const bool more = (kt + 1 < KT);
;     const bool more2 = (kt + 2 < KT);
;     const int nstg = (kt + 1) & 1;
;     const char* as = As + (kt & 1) * 32768 + wm * (32 * MB) * 128;
;     const char* bs = Bs + (kt & 1) * 32768 + wn * 64 * 128;
;     int k1_ = kbase + kt + 1; if (k1_ >= KT) k1_ -= KT;
;     int k2_ = kbase + kt + 2; if (k2_ >= KT) k2_ -= KT; if (k2_ >= KT) k2_ -= KT;
; #pragma unroll
;     for (int ks = 0; ks < 3; ++ks) {
; #pragma unroll
;       for (int idx = 0; idx < 2 * MB; ++idx) {
;         const int nb = idx / MB, mb = idx % MB;
;         acc[nb][mb] = mfma32(bfr[ks & 1][nb], af[ks & 1][mb], acc[nb][mb]);
;         if (idx < MB) af[(ks + 1) & 1][idx] = *(const bf8*)(as + idx * 32 * 128 + foff[ks + 1]);
;         else if (idx < MB + 2) bfr[(ks + 1) & 1][idx - MB] = *(const bf8*)(bs + (idx - MB) * 32 * 128 + foff[ks + 1]);
;         if (more && ks < 2 && idx < 3) {
;           const int ko_ = k1_ * 64;
;           GEMM_PIECE(nstg, 3 + ks * 3 + idx)
;         }
;         __builtin_amdgcn_sched_barrier(0);
;       }
;     }
;     if (more) {
;       asm volatile("s_waitcnt vmcnt(0)" ::: "memory");
;       __syncthreads();
;       if (more2) {
;         const int ko_ = k2_ * 64;
; #pragma unroll
;         for (int pc = 0; pc < 3; ++pc) GEMM_PIECE(kt & 1, pc)
;       }
;       __builtin_amdgcn_sched_barrier(0);
;       const char* asn = As + nstg * 32768 + wm * (32 * MB) * 128;
;       const char* bsn = Bs + nstg * 32768 + wn * 64 * 128;
; #pragma unroll
;       for (int mb = 0; mb < MB; ++mb) af[0][mb] = *(const bf8*)(asn + mb * 32 * 128 + foff[0]);
; #pragma unroll
;       for (int nb = 0; nb < 2; ++nb) bfr[0][nb] = *(const bf8*)(bsn + nb * 32 * 128 + foff[0]);
;     }
; #pragma unroll
;     for (int nb = 0; nb < 2; ++nb)
; #pragma unroll
;       for (int mb = 0; mb < MB; ++mb) acc[nb][mb] = mfma32(bfr[1][nb], af[1][mb], acc[nb][mb]);
; #pragma unroll
;     for (int gk = 0; gk < 2 * MB; ++gk) {
;       __builtin_amdgcn_sched_group_barrier(0x008, 1, 0);
;       __builtin_amdgcn_sched_group_barrier(0x100, 1, 0);
;     }
;     __builtin_amdgcn_sched_barrier(0);
;   }
.LBB0_865:
	s_and_b32 s17, s12, 0x8000
	s_add_i32 s19, s18, 1
	s_add_i32 s25, s11, s17
	s_add_i32 s23, s10, s17
	s_add_i32 s22, s14, s18
	s_cmp_lt_i32 s22, 43
	s_cselect_b32 s18, 0, 0xffffffd4
	s_add_i32 s18, s22, s18
	s_waitcnt lgkmcnt(1)
	v_mfma_f32_32x32x16_bf16 v[114:129], v[150:153], v[146:149], v[114:129]
	s_lshl_b32 s18, s18, 6
	s_add_i32 s26, s18, 64
	s_ashr_i32 s27, s26, 31
	s_add_i32 s12, s12, 0x8000
	v_add_u32_e32 v188, s25, v171
	s_lshl_b64 s[26:27], s[26:27], 1
	s_and_b32 s18, s12, 0x8000
	ds_read_b128 v[172:175], v188
	s_add_i32 s29, s18, s16
	v_lshl_add_u64 v[176:177], v[160:161], 0, s[26:27]
	s_mov_b32 m0, s29
	s_nop 0
	global_load_lds_dwordx4 v[176:177], off
	v_lshl_add_u64 v[184:185], v[158:159], 0, s[26:27]
	s_add_i32 s28, s18, s13
	v_mfma_f32_32x32x16_bf16 v[66:81], v[150:153], v[142:145], v[66:81]
	ds_read_b128 v[176:179], v188 offset:4096
	s_mov_b32 m0, s28
	s_nop 0
	global_load_lds_dwordx4 v[184:185], off
	v_mfma_f32_32x32x16_bf16 v[18:33], v[150:153], v[134:137], v[18:33]
	ds_read_b128 v[180:183], v188 offset:8192
	s_add_i32 s26, s28, 0x2000
	v_lshl_add_u64 v[186:187], v[184:185], 0, s[36:37]
	s_mov_b32 m0, s26
	s_nop 0
	global_load_lds_dwordx4 v[186:187], off
	v_mfma_f32_32x32x16_bf16 v[2:17], v[150:153], v[130:133], v[2:17]
	ds_read_b128 v[150:153], v188 offset:12288
	s_waitcnt lgkmcnt(4)
	v_mfma_f32_32x32x16_bf16 v[98:113], v[138:141], v[146:149], v[98:113]
	v_add_u32_e32 v186, s23, v171
	ds_read_b128 v[146:149], v186
	v_mfma_f32_32x32x16_bf16 v[82:97], v[138:141], v[142:145], v[82:97]
	ds_read_b128 v[142:145], v186 offset:4096
	v_mfma_f32_32x32x16_bf16 v[50:65], v[138:141], v[134:137], v[50:65]
	v_mfma_f32_32x32x16_bf16 v[34:49], v[138:141], v[130:133], v[34:49]
	s_waitcnt lgkmcnt(1)
	v_mfma_f32_32x32x16_bf16 v[114:129], v[146:149], v[172:175], v[114:129]
	v_add_u32_e32 v186, s25, v170
	ds_read_b128 v[130:133], v186
	s_add_i32 s26, s28, 0x4000
	v_lshl_add_u64 v[134:135], v[184:185], 0, s[40:41]
	s_mov_b32 m0, s26
	s_nop 0
	global_load_lds_dwordx4 v[134:135], off
	v_mfma_f32_32x32x16_bf16 v[66:81], v[146:149], v[176:179], v[66:81]
	ds_read_b128 v[134:137], v186 offset:4096
	s_addk_i32 s28, 0x6000
	v_lshl_add_u64 v[138:139], v[184:185], 0, s[48:49]
	s_mov_b32 m0, s28
	s_nop 0
	global_load_lds_dwordx4 v[138:139], off
	v_mfma_f32_32x32x16_bf16 v[18:33], v[146:149], v[180:183], v[18:33]
	ds_read_b128 v[138:141], v186 offset:8192
	v_mfma_f32_32x32x16_bf16 v[2:17], v[146:149], v[150:153], v[2:17]
	ds_read_b128 v[146:149], v186 offset:12288
	s_waitcnt lgkmcnt(4)
	v_mfma_f32_32x32x16_bf16 v[98:113], v[142:145], v[172:175], v[98:113]
	v_add_u32_e32 v184, s23, v170
	ds_read_b128 v[172:175], v184
	v_mfma_f32_32x32x16_bf16 v[82:97], v[142:145], v[176:179], v[82:97]
	ds_read_b128 v[176:179], v184 offset:4096
	v_mfma_f32_32x32x16_bf16 v[50:65], v[142:145], v[180:183], v[50:65]
	v_mfma_f32_32x32x16_bf16 v[34:49], v[142:145], v[150:153], v[34:49]
	s_waitcnt lgkmcnt(1)
	v_mfma_f32_32x32x16_bf16 v[114:129], v[172:175], v[130:133], v[114:129]
	v_add_u32_e32 v142, s25, v169
	ds_read_b128 v[150:153], v142
	v_mfma_f32_32x32x16_bf16 v[66:81], v[172:175], v[134:137], v[66:81]
	ds_read_b128 v[180:183], v142 offset:4096
	v_mfma_f32_32x32x16_bf16 v[18:33], v[172:175], v[138:141], v[18:33]
	ds_read_b128 v[184:187], v142 offset:8192
	v_mfma_f32_32x32x16_bf16 v[2:17], v[172:175], v[146:149], v[2:17]
	ds_read_b128 v[172:175], v142 offset:12288
	s_waitcnt lgkmcnt(4)
	v_mfma_f32_32x32x16_bf16 v[98:113], v[176:179], v[130:133], v[98:113]
	v_add_u32_e32 v142, s23, v169
	ds_read_b128 v[130:133], v142
	v_mfma_f32_32x32x16_bf16 v[82:97], v[176:179], v[134:137], v[82:97]
	ds_read_b128 v[188:191], v142 offset:4096
	v_mfma_f32_32x32x16_bf16 v[50:65], v[176:179], v[138:141], v[50:65]
	v_mfma_f32_32x32x16_bf16 v[34:49], v[176:179], v[146:149], v[34:49]
	s_cmp_lt_i32 s22, 42
	s_cselect_b32 s23, 0, 0xffffffd4
	s_add_i32 s25, s22, s23
	s_add_i32 s25, s25, 2
	s_cmp_lt_i32 s25, 44
	s_cselect_b32 s25, 0, 0xffffffd4
	s_add_i32 s23, s23, s25
	s_add_i32 s22, s22, s23
	s_lshl_b32 s22, s22, 6
	s_addk_i32 s22, 0x80
	s_ashr_i32 s23, s22, 31
	s_lshl_b64 s[22:23], s[22:23], 1
	s_add_u32 s22, s20, s22
	s_addc_u32 s23, s21, s23
	s_waitcnt vmcnt(0)
	s_waitcnt lgkmcnt(0)
	s_barrier
	s_add_i32 s25, s17, s15
	v_lshl_add_u64 v[134:135], v[0:1], 1, s[22:23]
	s_mov_b32 m0, s25
	s_nop 0
	global_load_lds_dwordx4 v[134:135], off
	v_lshl_add_u64 v[134:135], v[154:155], 1, s[22:23]
	s_add_i32 s26, s25, 0x2000
	s_mov_b32 m0, s26
	s_nop 0
	global_load_lds_dwordx4 v[134:135], off
	v_lshl_add_u64 v[134:135], v[156:157], 1, s[22:23]
	s_addk_i32 s25, 0x4000
	s_mov_b32 m0, s25
	s_nop 0
	global_load_lds_dwordx4 v[134:135], off
	v_add_u32_e32 v138, s18, v168
	v_mfma_f32_32x32x16_bf16 v[114:129], v[130:133], v[150:153], v[114:129]
	ds_read_b128 v[146:149], v138
	v_mfma_f32_32x32x16_bf16 v[66:81], v[130:133], v[180:183], v[66:81]
	ds_read_b128 v[142:145], v138 offset:4096
	v_mfma_f32_32x32x16_bf16 v[18:33], v[130:133], v[184:187], v[18:33]
	ds_read_b128 v[134:137], v138 offset:8192
	v_mfma_f32_32x32x16_bf16 v[2:17], v[130:133], v[172:175], v[2:17]
	ds_read_b128 v[130:133], v138 offset:12288
	v_add_u32_e32 v138, s18, v167
	v_mfma_f32_32x32x16_bf16 v[98:113], v[188:191], v[150:153], v[98:113]
	ds_read_b128 v[150:153], v138
	v_mfma_f32_32x32x16_bf16 v[82:97], v[188:191], v[180:183], v[82:97]
	ds_read_b128 v[138:141], v138 offset:4096
	v_mfma_f32_32x32x16_bf16 v[50:65], v[188:191], v[184:187], v[50:65]
	v_mfma_f32_32x32x16_bf16 v[34:49], v[188:191], v[172:175], v[34:49]
	s_cmp_lg_u32 s19, 42
	s_mov_b32 s18, s19
	s_cbranch_scc1 .LBB0_865
; DI f32x16 mfma32(bf8 a, bf8 b, f32x16 c) { return __builtin_amdgcn_mfma_f32_32x32x16_bf16(a, b, c, 0, 0, 0); }
; template <int MB, class Epi>
; DI void gemm_tile(const u16* __restrict__ A, int lda, int row0, int Mrows, const u16* __restrict__ Bt, int ldb, int K, char* smem, Epi& epi, int rot) {
;     ...
;     if (more) {
;       asm volatile("s_waitcnt vmcnt(0)" ::: "memory");
;       __syncthreads();
;       if (more2) {
;         const int ko_ = k2_ * 64;
; #pragma unroll
;         for (int pc = 0; pc < 3; ++pc) GEMM_PIECE(kt & 1, pc)
;       }
;       __builtin_amdgcn_sched_barrier(0);
;       const char* asn = As + nstg * 32768 + wm * (32 * MB) * 128;
;       const char* bsn = Bs + nstg * 32768 + wn * 64 * 128;
; #pragma unroll
;       for (int mb = 0; mb < MB; ++mb) af[0][mb] = *(const bf8*)(asn + mb * 32 * 128 + foff[0]);
; #pragma unroll
;       for (int nb = 0; nb < 2; ++nb) bfr[0][nb] = *(const bf8*)(bsn + nb * 32 * 128 + foff[0]);
;     }
; #pragma unroll
;     for (int nb = 0; nb < 2; ++nb)
; #pragma unroll
;       for (int mb = 0; mb < MB; ++mb) acc[nb][mb] = mfma32(bfr[1][nb], af[1][mb], acc[nb][mb]);
; #pragma unroll
;     for (int gk = 0; gk < 2 * MB; ++gk) {
;       __builtin_amdgcn_sched_group_barrier(0x008, 1, 0);
;       __builtin_amdgcn_sched_group_barrier(0x100, 1, 0);
;     }
;     __builtin_amdgcn_sched_barrier(0);
;   }
	s_add_i32 s12, s14, 42
	s_cmp_lt_i32 s12, 43
	s_cselect_b32 s14, 0, 0xffffffd4
	s_add_i32 s12, s12, s14
	s_lshl_b32 s12, s12, 6
	s_add_i32 s14, s12, 64
	s_ashr_i32 s15, s14, 31
	v_add_u32_e32 v0, s11, v171
	s_lshl_b64 s[14:15], s[14:15], 1
	ds_read_b128 v[154:157], v0
	v_lshl_add_u64 v[176:177], v[158:159], 0, s[14:15]
	s_add_i32 s12, s17, s13
	s_add_i32 s13, s17, s16
	v_lshl_add_u64 v[158:159], v[160:161], 0, s[14:15]
	s_mov_b32 m0, s13
	s_nop 0
	global_load_lds_dwordx4 v[158:159], off
	s_waitcnt lgkmcnt(2)
	v_mfma_f32_32x32x16_bf16 v[114:129], v[150:153], v[146:149], v[114:129]
	ds_read_b128 v[158:161], v0 offset:4096
	s_mov_b32 m0, s12
	s_nop 0
	global_load_lds_dwordx4 v[176:177], off
	v_mfma_f32_32x32x16_bf16 v[66:81], v[150:153], v[142:145], v[66:81]
	ds_read_b128 v[172:175], v0 offset:8192
	s_add_i32 s13, s12, 0x2000
	v_lshl_add_u64 v[178:179], v[176:177], 0, s[36:37]
	s_mov_b32 m0, s13
	s_nop 0
	global_load_lds_dwordx4 v[178:179], off
	v_mfma_f32_32x32x16_bf16 v[18:33], v[150:153], v[134:137], v[18:33]
	v_mfma_f32_32x32x16_bf16 v[2:17], v[150:153], v[130:133], v[2:17]
	ds_read_b128 v[150:153], v0 offset:12288
	v_add_u32_e32 v178, s10, v171
	s_waitcnt lgkmcnt(4)
	v_mfma_f32_32x32x16_bf16 v[98:113], v[138:141], v[146:149], v[98:113]
	ds_read_b128 v[146:149], v178
	v_mfma_f32_32x32x16_bf16 v[82:97], v[138:141], v[142:145], v[82:97]
	ds_read_b128 v[142:145], v178 offset:4096
	v_mfma_f32_32x32x16_bf16 v[50:65], v[138:141], v[134:137], v[50:65]
	v_mfma_f32_32x32x16_bf16 v[34:49], v[138:141], v[130:133], v[34:49]
	v_add_u32_e32 v179, s11, v170
	ds_read_b128 v[130:133], v179
	s_add_i32 s13, s12, 0x4000
	v_lshl_add_u64 v[134:135], v[176:177], 0, s[40:41]
	s_mov_b32 m0, s13
	s_nop 0
	global_load_lds_dwordx4 v[134:135], off
	s_waitcnt lgkmcnt(2)
	v_mfma_f32_32x32x16_bf16 v[114:129], v[146:149], v[154:157], v[114:129]
	ds_read_b128 v[134:137], v179 offset:4096
	s_addk_i32 s12, 0x6000
	v_lshl_add_u64 v[138:139], v[176:177], 0, s[48:49]
	s_mov_b32 m0, s12
	s_nop 0
	global_load_lds_dwordx4 v[138:139], off
	v_mfma_f32_32x32x16_bf16 v[66:81], v[146:149], v[158:161], v[66:81]
	ds_read_b128 v[138:141], v179 offset:8192
	v_mfma_f32_32x32x16_bf16 v[18:33], v[146:149], v[172:175], v[18:33]
	v_mfma_f32_32x32x16_bf16 v[2:17], v[146:149], v[150:153], v[2:17]
	ds_read_b128 v[146:149], v179 offset:12288
	v_add_u32_e32 v176, s10, v170
	s_waitcnt lgkmcnt(4)
	v_mfma_f32_32x32x16_bf16 v[98:113], v[142:145], v[154:157], v[98:113]
	ds_read_b128 v[154:157], v176
	v_mfma_f32_32x32x16_bf16 v[82:97], v[142:145], v[158:161], v[82:97]
	ds_read_b128 v[158:161], v176 offset:4096
	v_mfma_f32_32x32x16_bf16 v[50:65], v[142:145], v[172:175], v[50:65]
	v_mfma_f32_32x32x16_bf16 v[34:49], v[142:145], v[150:153], v[34:49]
	v_add_u32_e32 v174, s11, v169
	ds_read_b128 v[142:145], v174
	s_waitcnt lgkmcnt(2)
	v_mfma_f32_32x32x16_bf16 v[114:129], v[154:157], v[130:133], v[114:129]
	ds_read_b128 v[150:153], v174 offset:4096
	v_mfma_f32_32x32x16_bf16 v[66:81], v[154:157], v[134:137], v[66:81]
	ds_read_b128 v[170:173], v174 offset:8192
	v_mfma_f32_32x32x16_bf16 v[18:33], v[154:157], v[138:141], v[18:33]
	v_mfma_f32_32x32x16_bf16 v[2:17], v[154:157], v[146:149], v[2:17]
	ds_read_b128 v[154:157], v174 offset:12288
	v_add_u32_e32 v175, s10, v169
	s_waitcnt lgkmcnt(4)
	v_mfma_f32_32x32x16_bf16 v[98:113], v[158:161], v[130:133], v[98:113]
	ds_read_b128 v[130:133], v175
	v_mfma_f32_32x32x16_bf16 v[82:97], v[158:161], v[134:137], v[82:97]
	ds_read_b128 v[134:137], v175 offset:4096
	v_mfma_f32_32x32x16_bf16 v[50:65], v[158:161], v[138:141], v[50:65]
	v_mfma_f32_32x32x16_bf16 v[34:49], v[158:161], v[146:149], v[34:49]
	s_waitcnt vmcnt(0)
	s_waitcnt lgkmcnt(0)
	s_barrier
	s_lshr_b32 s100, s0, 5
	s_lshl_b32 s100, s100, 3
	s_and_b32 s101, s0, 7
	s_or_b32 s100, s100, s101
	s_mul_i32 s100, s100, 0x100
	s_lshr_b32 s101, s0, 3
	s_and_b32 s101, s101, 3
	s_lshl_b32 s101, s101, 9
	v_lshrrev_b32_e32 v237, 2, v163
	v_and_b32_e32 v238, 3, v163
	v_add_u32_e32 v237, s100, v237
	v_lshlrev_b32_e32 v237, 11, v237
	v_lshl_add_u32 v237, v238, 7, v237
	v_add_u32_e32 v237, s101, v237
	global_load_dword v239, v237, s[46:47]
	v_add_u32_e32 v237, 0x40000, v237
	global_load_dword v239, v237, s[46:47]
	v_add_u32_e32 v168, s17, v168
	v_add_u32_e32 v167, s17, v167
	v_mfma_f32_32x32x16_bf16 v[114:129], v[130:133], v[142:145], v[114:129]
	ds_read_b128 v[138:141], v168
	v_mfma_f32_32x32x16_bf16 v[66:81], v[130:133], v[150:153], v[66:81]
	ds_read_b128 v[146:149], v168 offset:4096
	v_mfma_f32_32x32x16_bf16 v[18:33], v[130:133], v[170:173], v[18:33]
	ds_read_b128 v[158:161], v168 offset:8192
	v_mfma_f32_32x32x16_bf16 v[2:17], v[130:133], v[154:157], v[2:17]
	ds_read_b128 v[130:133], v168 offset:12288
	v_mfma_f32_32x32x16_bf16 v[98:113], v[134:137], v[142:145], v[98:113]
	ds_read_b128 v[142:145], v167
	v_mfma_f32_32x32x16_bf16 v[82:97], v[134:137], v[150:153], v[82:97]
	ds_read_b128 v[150:153], v167 offset:4096
	v_mfma_f32_32x32x16_bf16 v[50:65], v[134:137], v[170:173], v[50:65]
	v_mfma_f32_32x32x16_bf16 v[34:49], v[134:137], v[154:157], v[34:49]
	ds_read_b128 v[134:137], v0 offset:32768
	s_waitcnt lgkmcnt(2)
	v_mfma_f32_32x32x16_bf16 v[114:129], v[142:145], v[138:141], v[114:129]
	ds_read_b128 v[154:157], v0 offset:36864
	v_mfma_f32_32x32x16_bf16 v[66:81], v[142:145], v[146:149], v[66:81]
	ds_read_b128 v[168:171], v0 offset:40960
	v_mfma_f32_32x32x16_bf16 v[18:33], v[142:145], v[158:161], v[18:33]
	v_mfma_f32_32x32x16_bf16 v[2:17], v[142:145], v[130:133], v[2:17]
	ds_read_b128 v[142:145], v0 offset:45056
	s_waitcnt lgkmcnt(4)
; DI f32x16 mfma32(bf8 a, bf8 b, f32x16 c) { return __builtin_amdgcn_mfma_f32_32x32x16_bf16(a, b, c, 0, 0, 0); }
; template <int MB, class Epi>
; DI void gemm_tile(const u16* __restrict__ A, int lda, int row0, int Mrows, const u16* __restrict__ Bt, int ldb, int K, char* smem, Epi& epi, int rot) {
;     ...
; #pragma unroll
;     for (int nb = 0; nb < 2; ++nb)
; #pragma unroll
;       for (int mb = 0; mb < MB; ++mb) acc[nb][mb] = mfma32(bfr[1][nb], af[1][mb], acc[nb][mb]);
; #pragma unroll
;     for (int gk = 0; gk < 2 * MB; ++gk) {
;       __builtin_amdgcn_sched_group_barrier(0x008, 1, 0);
;       __builtin_amdgcn_sched_group_barrier(0x100, 1, 0);
;     }
;     __builtin_amdgcn_sched_barrier(0);
;   }
;   __syncthreads();
;   epi(acc, wm, wn, r, h);
; }
;   DI void operator()(f32x16 (&acc)[2][MB], int wm, int wn, int r, int h) {
;     u16* slab = ostage + (wm * 4 + wn) * (64 * 72);
;     const int lane = h * 32 + r;
; #pragma unroll
;     for (int mb = 0; mb < MB; ++mb) {
;       const int tokl = (mb & 1) * 32 + r;
; #pragma unroll
;       for (int nb = 0; nb < 2; ++nb)
; #pragma unroll
;         for (int ig = 0; ig < 4; ++ig) {
;           u32x2 o;
;           o.x = pack2(acc[nb][mb][ig * 4 + 0], acc[nb][mb][ig * 4 + 1]);
;           o.y = pack2(acc[nb][mb][ig * 4 + 2], acc[nb][mb][ig * 4 + 3]);
;           *(u32x2*)(slab + tokl * 72 + nb * 32 + ig * 8 + h * 4) = o;
;         }
;       if ((mb & 1) || mb == MB - 1) {
;         asm volatile("s_waitcnt lgkmcnt(0)" ::: "memory");
;         const int ntok = (mb & 1) ? 64 : 32;
;         const int R0 = row0 + wm * (32 * MB) + (mb >> 1) * 64;
; #pragma unroll
;         for (int j = 0; j < 8; ++j) {
;           const int rowl = (lane >> 3) + 8 * j, ch = lane & 7;
;           if (rowl < ntok) {
;             const u32x4 yv = *(const u32x4*)(slab + rowl * 72 + ch * 8);
;             const int R = R0 + rowl;
;             const int mi = (R < NLAT) ? (R >> 11) : 16;
;             const int col = n0 + wn * 64 + ch * 8;
;             const float* g = gate + (size_t)mi * 6144 + col;
;             const f32x4n g0 = *(const f32x4n*)(g), g1 = *(const f32x4n*)(g + 4);
;             _Float16* xp = X + (size_t)R * 1024 + col;
;             const h8 xv = *(const h8*)xp;
;             const float y[8] = {__uint_as_float(yv.x << 16), __uint_as_float(yv.x & 0xffff0000u), __uint_as_float(yv.y << 16), __uint_as_float(yv.y & 0xffff0000u),
	v_mfma_f32_32x32x16_bf16 v[98:113], v[150:153], v[138:141], v[98:113]
	ds_read_b128 v[138:141], v178 offset:32768
	v_mfma_f32_32x32x16_bf16 v[82:97], v[150:153], v[146:149], v[82:97]
	ds_read_b128 v[146:149], v178 offset:36864
	v_mfma_f32_32x32x16_bf16 v[50:65], v[150:153], v[158:161], v[50:65]
	v_mfma_f32_32x32x16_bf16 v[34:49], v[150:153], v[130:133], v[34:49]
	ds_read_b128 v[130:133], v179 offset:32768
	s_waitcnt lgkmcnt(2)
	v_mfma_f32_32x32x16_bf16 v[114:129], v[138:141], v[134:137], v[114:129]
	ds_read_b128 v[150:153], v179 offset:36864
	v_mfma_f32_32x32x16_bf16 v[66:81], v[138:141], v[154:157], v[66:81]
	ds_read_b128 v[158:161], v179 offset:40960
	v_mfma_f32_32x32x16_bf16 v[18:33], v[138:141], v[168:171], v[18:33]
	v_mfma_f32_32x32x16_bf16 v[2:17], v[138:141], v[142:145], v[2:17]
	ds_read_b128 v[138:141], v179 offset:45056
	s_waitcnt lgkmcnt(4)
	v_mfma_f32_32x32x16_bf16 v[98:113], v[146:149], v[134:137], v[98:113]
	ds_read_b128 v[134:137], v176 offset:32768
	v_mfma_f32_32x32x16_bf16 v[82:97], v[146:149], v[154:157], v[82:97]
	ds_read_b128 v[154:157], v176 offset:36864
	v_mfma_f32_32x32x16_bf16 v[50:65], v[146:149], v[168:171], v[50:65]
	v_mfma_f32_32x32x16_bf16 v[34:49], v[146:149], v[142:145], v[34:49]
	ds_read_b128 v[142:145], v174 offset:32768
	s_waitcnt lgkmcnt(2)
	v_mfma_f32_32x32x16_bf16 v[114:129], v[134:137], v[130:133], v[114:129]
	ds_read_b128 v[146:149], v174 offset:36864
	v_mfma_f32_32x32x16_bf16 v[66:81], v[134:137], v[150:153], v[66:81]
	ds_read_b128 v[168:171], v174 offset:40960
	v_mfma_f32_32x32x16_bf16 v[18:33], v[134:137], v[158:161], v[18:33]
	v_mfma_f32_32x32x16_bf16 v[2:17], v[134:137], v[138:141], v[2:17]
	ds_read_b128 v[134:137], v174 offset:45056
	s_waitcnt lgkmcnt(4)
	v_mfma_f32_32x32x16_bf16 v[98:113], v[154:157], v[130:133], v[98:113]
	ds_read_b128 v[130:133], v175 offset:32768
	v_mfma_f32_32x32x16_bf16 v[82:97], v[154:157], v[150:153], v[82:97]
	ds_read_b128 v[150:153], v175 offset:36864
	v_mfma_f32_32x32x16_bf16 v[50:65], v[154:157], v[158:161], v[50:65]
	v_mfma_f32_32x32x16_bf16 v[34:49], v[154:157], v[138:141], v[34:49]
	s_waitcnt lgkmcnt(1)
	v_mfma_f32_32x32x16_bf16 v[114:129], v[130:133], v[142:145], v[114:129]
	v_mfma_f32_32x32x16_bf16 v[66:81], v[130:133], v[146:149], v[66:81]
	v_mfma_f32_32x32x16_bf16 v[18:33], v[130:133], v[168:171], v[18:33]
	v_mfma_f32_32x32x16_bf16 v[2:17], v[130:133], v[134:137], v[2:17]
	s_waitcnt lgkmcnt(0)
	v_mfma_f32_32x32x16_bf16 v[98:113], v[150:153], v[142:145], v[98:113]
	v_mfma_f32_32x32x16_bf16 v[82:97], v[150:153], v[146:149], v[82:97]
	v_mfma_f32_32x32x16_bf16 v[50:65], v[150:153], v[168:171], v[50:65]
	v_mfma_f32_32x32x16_bf16 v[34:49], v[150:153], v[134:137], v[34:49]
	s_lshl_b32 s10, s9, 2
	s_or_b32 s10, s10, s8
	s_mulk_i32 s10, 0x2400
	v_lshl_or_b32 v0, v166, 3, s10
	v_lshlrev_b32_e32 v130, 3, v165
	v_and_b32_e32 v132, 56, v130
	v_mad_u32_u24 v130, v165, s78, v0
	v_cvt_pk_bf16_f32 v66, v66, v67
	v_cvt_pk_bf16_f32 v67, v68, v69
	v_cvt_pk_bf16_f32 v68, v70, v71
	v_cvt_pk_bf16_f32 v69, v72, v73
	v_add_u32_e32 v70, 0x1000, v130
	s_barrier
	ds_write2_b64 v70, v[66:67], v[68:69] offset0:64 offset1:66
	v_cvt_pk_bf16_f32 v66, v74, v75
	v_cvt_pk_bf16_f32 v67, v76, v77
	v_cvt_pk_bf16_f32 v68, v78, v79
	v_cvt_pk_bf16_f32 v69, v80, v81
	s_lshl_b32 s9, s9, 7
	ds_write2_b64 v70, v[66:67], v[68:69] offset0:68 offset1:70
	v_cvt_pk_bf16_f32 v66, v82, v83
	v_cvt_pk_bf16_f32 v67, v84, v85
	v_cvt_pk_bf16_f32 v68, v86, v87
	v_cvt_pk_bf16_f32 v69, v88, v89
	s_lshl_b32 s3, s3, 8
	v_bfe_u32 v131, v164, 3, 3
	s_lshl_b32 s8, s8, 6
	ds_write2_b64 v70, v[66:67], v[68:69] offset0:72 offset1:74
	v_cvt_pk_bf16_f32 v66, v90, v91
	v_cvt_pk_bf16_f32 v67, v92, v93
	v_cvt_pk_bf16_f32 v68, v94, v95
	v_cvt_pk_bf16_f32 v69, v96, v97
	s_add_i32 s2, s9, s2
	ds_write2_b64 v70, v[66:67], v[68:69] offset0:76 offset1:78
	v_or_b32_e32 v66, s2, v131
	s_or_b32 s3, s8, s3
	v_cvt_pk_bf16_f32 v114, v114, v115
	v_cvt_pk_bf16_f32 v115, v116, v117
	v_cvt_pk_bf16_f32 v116, v118, v119
	v_cvt_pk_bf16_f32 v117, v120, v121
	v_cvt_pk_bf16_f32 v98, v98, v99
	v_cvt_pk_bf16_f32 v99, v100, v101
	v_cvt_pk_bf16_f32 v100, v102, v103
	v_cvt_pk_bf16_f32 v101, v104, v105
	v_or_b32_e32 v68, s3, v132
	v_ashrrev_i32_e32 v67, 31, v66
	ds_write2_b64 v130, v[114:115], v[116:117] offset1:2
	v_cvt_pk_bf16_f32 v114, v122, v123
	v_cvt_pk_bf16_f32 v115, v124, v125
	v_cvt_pk_bf16_f32 v116, v126, v127
	v_cvt_pk_bf16_f32 v117, v128, v129
	ds_write2_b64 v130, v[98:99], v[100:101] offset0:8 offset1:10
	v_cvt_pk_bf16_f32 v98, v106, v107
	v_cvt_pk_bf16_f32 v99, v108, v109
	v_cvt_pk_bf16_f32 v100, v110, v111
	v_cvt_pk_bf16_f32 v101, v112, v113
	v_min_i32_e32 v0, 0x8000, v66
	v_ashrrev_i32_e32 v69, 31, v68
	v_lshlrev_b64 v[66:67], 11, v[66:67]
	ds_write2_b64 v130, v[114:115], v[116:117] offset0:4 offset1:6
	ds_write2_b64 v130, v[98:99], v[100:101] offset0:12 offset1:14
	v_lshl_add_u64 v[72:73], s[46:47], 0, v[66:67]
	v_lshlrev_b64 v[66:67], 1, v[68:69]
	s_waitcnt lgkmcnt(0)
	v_lshl_add_u64 v[96:97], v[72:73], 0, v[66:67]
	global_load_dwordx4 v[72:75], v[96:97], off
	v_ashrrev_i32_e32 v0, 11, v0
	v_readlane_b32 s8, v234, 10
	v_mul_hi_i32_i24_e32 v77, 0x6000, v0
	v_mul_i32_i24_e32 v76, 0x6000, v0
	v_readlane_b32 s9, v234, 11
	v_lshlrev_b64 v[68:69], 2, v[68:69]
	v_or_b32_e32 v71, 8, v131
	v_lshl_add_u64 v[76:77], s[8:9], 0, v[76:77]
	v_lshl_add_u64 v[80:81], v[76:77], 0, v[68:69]
	global_load_dwordx4 v[76:79], v[80:81], off
	v_or_b32_e32 v98, s2, v71
	global_load_dwordx4 v[80:83], v[80:81], off offset:16
	v_ashrrev_i32_e32 v99, 31, v98
	v_lshl_or_b32 v0, v132, 1, s10
	v_lshlrev_b64 v[84:85], 11, v[98:99]
	v_mad_u32_u24 v0, v131, s78, v0
	v_lshl_add_u64 v[84:85], s[46:47], 0, v[84:85]
	v_lshl_add_u64 v[100:101], v[84:85], 0, v[66:67]
	ds_read_b128 v[84:87], v0
	global_load_dwordx4 v[92:95], v[100:101], off
	ds_read_b128 v[88:91], v0 offset:1152
	v_cvt_pk_bf16_f32 v2, v2, v3
	v_cvt_pk_bf16_f32 v3, v4, v5
	s_waitcnt lgkmcnt(1)
; DI unsigned pack2(float a, float b) { f2 v = {a, b}; bf2 r = __builtin_convertvector(v, bf2); return __builtin_bit_cast(unsigned, r); }
;   DI void operator()(f32x16 (&acc)[2][MB], int wm, int wn, int r, int h) {
;     ...
;     for (int mb = 0; mb < MB; ++mb) {
;       const int tokl = (mb & 1) * 32 + r;
; #pragma unroll
;       for (int nb = 0; nb < 2; ++nb)
; #pragma unroll
;         for (int ig = 0; ig < 4; ++ig) {
;           u32x2 o;
;           o.x = pack2(acc[nb][mb][ig * 4 + 0], acc[nb][mb][ig * 4 + 1]);
;           o.y = pack2(acc[nb][mb][ig * 4 + 2], acc[nb][mb][ig * 4 + 3]);
;           *(u32x2*)(slab + tokl * 72 + nb * 32 + ig * 8 + h * 4) = o;
;         }
;       if ((mb & 1) || mb == MB - 1) {
;         asm volatile("s_waitcnt lgkmcnt(0)" ::: "memory");
;         const int ntok = (mb & 1) ? 64 : 32;
;         const int R0 = row0 + wm * (32 * MB) + (mb >> 1) * 64;
; #pragma unroll
;         for (int j = 0; j < 8; ++j) {
;           const int rowl = (lane >> 3) + 8 * j, ch = lane & 7;
;           if (rowl < ntok) {
;             const u32x4 yv = *(const u32x4*)(slab + rowl * 72 + ch * 8);
;             const int R = R0 + rowl;
;             const int mi = (R < NLAT) ? (R >> 11) : 16;
;             const int col = n0 + wn * 64 + ch * 8;
;             const float* g = gate + (size_t)mi * 6144 + col;
;             const f32x4n g0 = *(const f32x4n*)(g), g1 = *(const f32x4n*)(g + 4);
;             _Float16* xp = X + (size_t)R * 1024 + col;
;             const h8 xv = *(const h8*)xp;
;             const float y[8] = {__uint_as_float(yv.x << 16), __uint_as_float(yv.x & 0xffff0000u), __uint_as_float(yv.y << 16), __uint_as_float(yv.y & 0xffff0000u),
;                                 __uint_as_float(yv.z << 16), __uint_as_float(yv.z & 0xffff0000u), __uint_as_float(yv.w << 16), __uint_as_float(yv.w & 0xffff0000u)};
;             const float gg[8] = {g0.x, g0.y, g0.z, g0.w, g1.x, g1.y, g1.z, g1.w};
;             h8 o;
; #pragma unroll
;             for (int q = 0; q < 8; ++q) o[q] = (_Float16)(ALPHA * (float)xv[q] + gg[q] * y[q]);
;             *(h8*)xp = o;
	v_lshlrev_b32_e32 v104, 16, v84
	v_and_b32_e32 v105, 0xffff0000, v84
	v_cvt_pk_bf16_f32 v4, v6, v7
	v_cvt_pk_bf16_f32 v5, v8, v9
	v_cvt_pk_bf16_f32 v6, v10, v11
	v_cvt_pk_bf16_f32 v7, v12, v13
	v_cvt_pk_bf16_f32 v8, v14, v15
	v_cvt_pk_bf16_f32 v9, v16, v17
	v_cvt_pk_bf16_f32 v10, v34, v35
	v_cvt_pk_bf16_f32 v11, v36, v37
	v_cvt_pk_bf16_f32 v12, v38, v39
	v_cvt_pk_bf16_f32 v13, v40, v41
	v_cvt_pk_bf16_f32 v14, v42, v43
	v_cvt_pk_bf16_f32 v15, v44, v45
	v_cvt_pk_bf16_f32 v16, v46, v47
	v_cvt_pk_bf16_f32 v17, v48, v49
	v_cvt_pk_bf16_f32 v18, v18, v19
	v_cvt_pk_bf16_f32 v19, v20, v21
	v_cvt_pk_bf16_f32 v20, v22, v23
	v_cvt_pk_bf16_f32 v21, v24, v25
	v_cvt_pk_bf16_f32 v22, v26, v27
	v_cvt_pk_bf16_f32 v23, v28, v29
	v_cvt_pk_bf16_f32 v24, v30, v31
	v_cvt_pk_bf16_f32 v25, v32, v33
	v_cvt_pk_bf16_f32 v26, v50, v51
	v_cvt_pk_bf16_f32 v27, v52, v53
	v_cvt_pk_bf16_f32 v28, v54, v55
	v_cvt_pk_bf16_f32 v29, v56, v57
	v_cvt_pk_bf16_f32 v30, v58, v59
	v_cvt_pk_bf16_f32 v31, v60, v61
	v_cvt_pk_bf16_f32 v32, v62, v63
	v_cvt_pk_bf16_f32 v33, v64, v65
	s_mov_b32 s40, s76
	s_waitcnt vmcnt(3)
	v_cvt_f32_f16_e32 v102, v72
	v_cvt_f32_f16_sdwa v103, v72 dst_sel:DWORD dst_unused:UNUSED_PAD src0_sel:WORD_1
	v_cvt_f32_f16_e32 v106, v73
	v_cvt_f32_f16_sdwa v107, v73 dst_sel:DWORD dst_unused:UNUSED_PAD src0_sel:WORD_1
	v_pk_mul_f32 v[102:103], v[102:103], s[30:31] op_sel_hi:[1,0]
	s_waitcnt vmcnt(2)
	v_pk_fma_f32 v[76:77], v[76:77], v[104:105], v[102:103]
	s_nop 0
	v_cvt_pk_f16_f32 v72, v76, v77
	v_lshlrev_b32_e32 v76, 16, v85
	v_and_b32_e32 v77, 0xffff0000, v85
	v_pk_mul_f32 v[84:85], v[106:107], s[30:31] op_sel_hi:[1,0]
	s_waitcnt lgkmcnt(0)
	v_lshlrev_b32_e32 v102, 16, v90
	v_pk_fma_f32 v[76:77], v[78:79], v[76:77], v[84:85]
	v_cvt_f32_f16_e32 v78, v74
	v_cvt_f32_f16_sdwa v79, v74 dst_sel:DWORD dst_unused:UNUSED_PAD src0_sel:WORD_1
	v_cvt_pk_f16_f32 v73, v76, v77
	v_lshlrev_b32_e32 v76, 16, v86
	v_and_b32_e32 v77, 0xffff0000, v86
	v_pk_mul_f32 v[78:79], v[78:79], s[30:31] op_sel_hi:[1,0]
	s_waitcnt vmcnt(0)
	v_cvt_f32_f16_e32 v104, v92
	v_pk_fma_f32 v[76:77], v[80:81], v[76:77], v[78:79]
	v_cvt_f32_f16_e32 v78, v75
	v_cvt_f32_f16_sdwa v79, v75 dst_sel:DWORD dst_unused:UNUSED_PAD src0_sel:WORD_1
	v_cvt_pk_f16_f32 v74, v76, v77
	v_lshlrev_b32_e32 v76, 16, v87
	v_and_b32_e32 v77, 0xffff0000, v87
	v_pk_mul_f32 v[78:79], v[78:79], s[30:31] op_sel_hi:[1,0]
	v_cvt_f32_f16_sdwa v105, v92 dst_sel:DWORD dst_unused:UNUSED_PAD src0_sel:WORD_1
	v_pk_fma_f32 v[76:77], v[82:83], v[76:77], v[78:79]
	v_cvt_f32_f16_e32 v92, v93
	v_cvt_pk_f16_f32 v75, v76, v77
	global_store_dwordx4 v[96:97], v[72:75], off
	v_cvt_f32_f16_sdwa v93, v93 dst_sel:DWORD dst_unused:UNUSED_PAD src0_sel:WORD_1
	v_cvt_f32_f16_e32 v106, v94
	v_min_i32_e32 v72, 0x8000, v98
	v_ashrrev_i32_e32 v72, 11, v72
	v_mul_hi_i32_i24_e32 v73, 0x6000, v72
	v_mul_i32_i24_e32 v72, 0x6000, v72
	v_lshl_add_u64 v[72:73], s[8:9], 0, v[72:73]
	v_lshl_add_u64 v[72:73], v[72:73], 0, v[68:69]
	global_load_dwordx4 v[74:77], v[72:73], off
	global_load_dwordx4 v[78:81], v[72:73], off offset:16
	v_or_b32_e32 v72, 16, v131
	v_or_b32_e32 v82, s2, v72
	v_min_i32_e32 v73, 0x8000, v82
	v_ashrrev_i32_e32 v83, 31, v82
	v_ashrrev_i32_e32 v73, 11, v73
	v_lshlrev_b64 v[82:83], 11, v[82:83]
	v_cvt_f32_f16_sdwa v107, v94 dst_sel:DWORD dst_unused:UNUSED_PAD src0_sel:WORD_1
	v_cvt_f32_f16_e32 v94, v95
	v_cvt_f32_f16_sdwa v95, v95 dst_sel:DWORD dst_unused:UNUSED_PAD src0_sel:WORD_1
	v_mul_hi_i32_i24_e32 v85, 0x6000, v73
	v_mul_i32_i24_e32 v84, 0x6000, v73
	v_lshl_add_u64 v[82:83], s[46:47], 0, v[82:83]
	v_lshl_add_u64 v[84:85], s[8:9], 0, v[84:85]
	v_lshl_add_u64 v[98:99], v[82:83], 0, v[66:67]
	v_lshl_add_u64 v[86:87], v[84:85], 0, v[68:69]
	global_load_dwordx4 v[82:85], v[98:99], off
	v_lshlrev_b32_e32 v96, 16, v88
	v_and_b32_e32 v97, 0xffff0000, v88
	v_lshlrev_b32_e32 v88, 16, v89
	v_and_b32_e32 v89, 0xffff0000, v89
	v_and_b32_e32 v103, 0xffff0000, v90
	v_lshlrev_b32_e32 v90, 16, v91
	v_and_b32_e32 v91, 0xffff0000, v91
	v_pk_mul_f32 v[104:105], v[104:105], s[30:31] op_sel_hi:[1,0]
	v_pk_mul_f32 v[92:93], v[92:93], s[30:31] op_sel_hi:[1,0]
	v_pk_mul_f32 v[106:107], v[106:107], s[30:31] op_sel_hi:[1,0]
	v_pk_mul_f32 v[94:95], v[94:95], s[30:31] op_sel_hi:[1,0]
	v_or_b32_e32 v73, 24, v131
	s_waitcnt vmcnt(2)
	v_pk_fma_f32 v[74:75], v[74:75], v[96:97], v[104:105]
	v_pk_fma_f32 v[76:77], v[76:77], v[88:89], v[92:93]
	s_waitcnt vmcnt(1)
	v_pk_fma_f32 v[78:79], v[78:79], v[102:103], v[106:107]
	v_pk_fma_f32 v[80:81], v[80:81], v[90:91], v[94:95]
	v_cvt_pk_f16_f32 v74, v74, v75
	v_cvt_pk_f16_f32 v75, v76, v77
	v_cvt_pk_f16_f32 v76, v78, v79
	v_cvt_pk_f16_f32 v77, v80, v81
	global_store_dwordx4 v[100:101], v[74:77], off
	global_load_dwordx4 v[74:77], v[86:87], off
	s_waitcnt vmcnt(2)
	v_cvt_f32_f16_e32 v108, v82
	global_load_dwordx4 v[78:81], v[86:87], off offset:16
	v_or_b32_e32 v86, s2, v73
	v_min_i32_e32 v88, 0x8000, v86
	v_ashrrev_i32_e32 v87, 31, v86
	v_ashrrev_i32_e32 v88, 11, v88
	v_lshlrev_b64 v[86:87], 11, v[86:87]
	v_mul_hi_i32_i24_e32 v89, 0x6000, v88
	v_mul_i32_i24_e32 v88, 0x6000, v88
	v_lshl_add_u64 v[90:91], s[46:47], 0, v[86:87]
	v_lshl_add_u64 v[92:93], s[8:9], 0, v[88:89]
	ds_read_b128 v[86:89], v0 offset:2304
	v_cvt_f32_f16_sdwa v109, v82 dst_sel:DWORD dst_unused:UNUSED_PAD src0_sel:WORD_1
	v_cvt_f32_f16_e32 v82, v83
	v_cvt_f32_f16_sdwa v83, v83 dst_sel:DWORD dst_unused:UNUSED_PAD src0_sel:WORD_1
	v_cvt_f32_f16_e32 v110, v84
	v_cvt_f32_f16_sdwa v111, v84 dst_sel:DWORD dst_unused:UNUSED_PAD src0_sel:WORD_1
	v_cvt_f32_f16_e32 v84, v85
	v_cvt_f32_f16_sdwa v85, v85 dst_sel:DWORD dst_unused:UNUSED_PAD src0_sel:WORD_1
	v_lshl_add_u64 v[100:101], v[90:91], 0, v[66:67]
	global_load_dwordx4 v[94:97], v[100:101], off
	s_waitcnt lgkmcnt(0)
;   DI void operator()(f32x16 (&acc)[2][MB], int wm, int wn, int r, int h) {
;     ...
;         for (int j = 0; j < 8; ++j) {
;           const int rowl = (lane >> 3) + 8 * j, ch = lane & 7;
;           if (rowl < ntok) {
;             const u32x4 yv = *(const u32x4*)(slab + rowl * 72 + ch * 8);
;             const int R = R0 + rowl;
;             const int mi = (R < NLAT) ? (R >> 11) : 16;
;             const int col = n0 + wn * 64 + ch * 8;
;             const float* g = gate + (size_t)mi * 6144 + col;
;             const f32x4n g0 = *(const f32x4n*)(g), g1 = *(const f32x4n*)(g + 4);
;             _Float16* xp = X + (size_t)R * 1024 + col;
;             const h8 xv = *(const h8*)xp;
;             const float y[8] = {__uint_as_float(yv.x << 16), __uint_as_float(yv.x & 0xffff0000u), __uint_as_float(yv.y << 16), __uint_as_float(yv.y & 0xffff0000u),
;                                 __uint_as_float(yv.z << 16), __uint_as_float(yv.z & 0xffff0000u), __uint_as_float(yv.w << 16), __uint_as_float(yv.w & 0xffff0000u)};
;             const float gg[8] = {g0.x, g0.y, g0.z, g0.w, g1.x, g1.y, g1.z, g1.w};
;             h8 o;
; #pragma unroll
;             for (int q = 0; q < 8; ++q) o[q] = (_Float16)(ALPHA * (float)xv[q] + gg[q] * y[q]);
;             *(h8*)xp = o;
	v_lshlrev_b32_e32 v104, 16, v86
	v_and_b32_e32 v105, 0xffff0000, v86
	v_lshlrev_b32_e32 v86, 16, v87
	v_and_b32_e32 v87, 0xffff0000, v87
	v_lshlrev_b32_e32 v106, 16, v88
	v_and_b32_e32 v107, 0xffff0000, v88
	v_lshlrev_b32_e32 v88, 16, v89
	v_and_b32_e32 v89, 0xffff0000, v89
	v_pk_mul_f32 v[108:109], v[108:109], s[30:31] op_sel_hi:[1,0]
	v_pk_mul_f32 v[82:83], v[82:83], s[30:31] op_sel_hi:[1,0]
	v_pk_mul_f32 v[110:111], v[110:111], s[30:31] op_sel_hi:[1,0]
	v_pk_mul_f32 v[84:85], v[84:85], s[30:31] op_sel_hi:[1,0]
	v_lshl_add_u64 v[102:103], v[92:93], 0, v[68:69]
	ds_read_b128 v[90:93], v0 offset:3456
	s_waitcnt vmcnt(2)
	v_pk_fma_f32 v[74:75], v[74:75], v[104:105], v[108:109]
	v_pk_fma_f32 v[76:77], v[76:77], v[86:87], v[82:83]
	v_cvt_pk_f16_f32 v74, v74, v75
	v_cvt_pk_f16_f32 v75, v76, v77
	s_waitcnt lgkmcnt(0)
	v_lshlrev_b32_e32 v104, 16, v92
	v_and_b32_e32 v105, 0xffff0000, v92
	v_lshlrev_b32_e32 v92, 16, v93
	v_and_b32_e32 v93, 0xffff0000, v93
	s_waitcnt vmcnt(1)
	v_pk_fma_f32 v[78:79], v[78:79], v[106:107], v[110:111]
	v_pk_fma_f32 v[80:81], v[80:81], v[88:89], v[84:85]
	v_cvt_pk_f16_f32 v76, v78, v79
	v_cvt_pk_f16_f32 v77, v80, v81
	global_store_dwordx4 v[98:99], v[74:77], off
	global_load_dwordx4 v[76:79], v[102:103], off
	v_lshlrev_b32_e32 v98, 16, v90
	global_load_dwordx4 v[80:83], v[102:103], off offset:16
	v_or_b32_e32 v74, 32, v131
	v_or_b32_e32 v84, s2, v74
	v_min_i32_e32 v75, 0x8000, v84
	v_ashrrev_i32_e32 v85, 31, v84
	v_ashrrev_i32_e32 v75, 11, v75
	v_lshlrev_b64 v[84:85], 11, v[84:85]
	v_mul_hi_i32_i24_e32 v87, 0x6000, v75
	v_mul_i32_i24_e32 v86, 0x6000, v75
	v_lshl_add_u64 v[84:85], s[46:47], 0, v[84:85]
	v_lshl_add_u64 v[86:87], s[8:9], 0, v[86:87]
	v_lshl_add_u64 v[102:103], v[84:85], 0, v[66:67]
	s_waitcnt vmcnt(3)
	v_cvt_f32_f16_e32 v106, v94
	v_cvt_f32_f16_sdwa v107, v94 dst_sel:DWORD dst_unused:UNUSED_PAD src0_sel:WORD_1
	v_cvt_f32_f16_e32 v94, v95
	v_cvt_f32_f16_sdwa v95, v95 dst_sel:DWORD dst_unused:UNUSED_PAD src0_sel:WORD_1
	v_cvt_f32_f16_e32 v108, v96
	v_cvt_f32_f16_sdwa v109, v96 dst_sel:DWORD dst_unused:UNUSED_PAD src0_sel:WORD_1
	v_cvt_f32_f16_e32 v96, v97
	v_cvt_f32_f16_sdwa v97, v97 dst_sel:DWORD dst_unused:UNUSED_PAD src0_sel:WORD_1
	v_lshl_add_u64 v[88:89], v[86:87], 0, v[68:69]
	global_load_dwordx4 v[84:87], v[102:103], off
	v_and_b32_e32 v99, 0xffff0000, v90
	v_lshlrev_b32_e32 v90, 16, v91
	v_and_b32_e32 v91, 0xffff0000, v91
	v_pk_mul_f32 v[106:107], v[106:107], s[30:31] op_sel_hi:[1,0]
	v_pk_mul_f32 v[94:95], v[94:95], s[30:31] op_sel_hi:[1,0]
	v_pk_mul_f32 v[108:109], v[108:109], s[30:31] op_sel_hi:[1,0]
	v_pk_mul_f32 v[96:97], v[96:97], s[30:31] op_sel_hi:[1,0]
	v_or_b32_e32 v75, 40, v131
	s_waitcnt vmcnt(2)
	v_pk_fma_f32 v[76:77], v[76:77], v[98:99], v[106:107]
	v_pk_fma_f32 v[78:79], v[78:79], v[90:91], v[94:95]
	s_waitcnt vmcnt(1)
	v_pk_fma_f32 v[80:81], v[80:81], v[104:105], v[108:109]
	v_pk_fma_f32 v[82:83], v[82:83], v[92:93], v[96:97]
	v_cvt_pk_f16_f32 v76, v76, v77
	v_cvt_pk_f16_f32 v77, v78, v79
	v_cvt_pk_f16_f32 v78, v80, v81
	v_cvt_pk_f16_f32 v79, v82, v83
	global_store_dwordx4 v[100:101], v[76:79], off
	global_load_dwordx4 v[76:79], v[88:89], off
	s_waitcnt vmcnt(2)
	v_cvt_f32_f16_e32 v110, v84
	global_load_dwordx4 v[80:83], v[88:89], off offset:16
	v_or_b32_e32 v88, s2, v75
	v_min_i32_e32 v90, 0x8000, v88
	v_ashrrev_i32_e32 v89, 31, v88
	v_ashrrev_i32_e32 v90, 11, v90
	v_lshlrev_b64 v[88:89], 11, v[88:89]
	v_mul_hi_i32_i24_e32 v91, 0x6000, v90
	v_mul_i32_i24_e32 v90, 0x6000, v90
	v_lshl_add_u64 v[92:93], s[46:47], 0, v[88:89]
	v_lshl_add_u64 v[94:95], s[8:9], 0, v[90:91]
	ds_read_b128 v[88:91], v0 offset:4608
	v_cvt_f32_f16_sdwa v111, v84 dst_sel:DWORD dst_unused:UNUSED_PAD src0_sel:WORD_1
	v_cvt_f32_f16_e32 v84, v85
	v_cvt_f32_f16_sdwa v85, v85 dst_sel:DWORD dst_unused:UNUSED_PAD src0_sel:WORD_1
	v_cvt_f32_f16_e32 v112, v86
	v_cvt_f32_f16_sdwa v113, v86 dst_sel:DWORD dst_unused:UNUSED_PAD src0_sel:WORD_1
	v_cvt_f32_f16_e32 v86, v87
	v_cvt_f32_f16_sdwa v87, v87 dst_sel:DWORD dst_unused:UNUSED_PAD src0_sel:WORD_1
	v_lshl_add_u64 v[100:101], v[92:93], 0, v[66:67]
	global_load_dwordx4 v[96:99], v[100:101], off
	s_waitcnt lgkmcnt(0)
	v_lshlrev_b32_e32 v106, 16, v88
	v_and_b32_e32 v107, 0xffff0000, v88
	v_lshlrev_b32_e32 v88, 16, v89
	v_and_b32_e32 v89, 0xffff0000, v89
	v_lshlrev_b32_e32 v108, 16, v90
	v_and_b32_e32 v109, 0xffff0000, v90
	v_lshlrev_b32_e32 v90, 16, v91
	v_and_b32_e32 v91, 0xffff0000, v91
	v_pk_mul_f32 v[110:111], v[110:111], s[30:31] op_sel_hi:[1,0]
	v_pk_mul_f32 v[84:85], v[84:85], s[30:31] op_sel_hi:[1,0]
	v_pk_mul_f32 v[112:113], v[112:113], s[30:31] op_sel_hi:[1,0]
	v_pk_mul_f32 v[86:87], v[86:87], s[30:31] op_sel_hi:[1,0]
	v_lshl_add_u64 v[104:105], v[94:95], 0, v[68:69]
	ds_read_b128 v[92:95], v0 offset:5760
	s_waitcnt vmcnt(2)
	v_pk_fma_f32 v[76:77], v[76:77], v[106:107], v[110:111]
	v_pk_fma_f32 v[78:79], v[78:79], v[88:89], v[84:85]
	v_cvt_pk_f16_f32 v76, v76, v77
	v_cvt_pk_f16_f32 v77, v78, v79
	s_waitcnt lgkmcnt(0)
	v_lshlrev_b32_e32 v106, 16, v94
	v_and_b32_e32 v107, 0xffff0000, v94
	v_lshlrev_b32_e32 v94, 16, v95
	v_and_b32_e32 v95, 0xffff0000, v95
	s_waitcnt vmcnt(1)
	v_pk_fma_f32 v[80:81], v[80:81], v[108:109], v[112:113]
	v_pk_fma_f32 v[82:83], v[82:83], v[90:91], v[86:87]
	v_cvt_pk_f16_f32 v78, v80, v81
	v_cvt_pk_f16_f32 v79, v82, v83
	global_store_dwordx4 v[102:103], v[76:79], off
	global_load_dwordx4 v[78:81], v[104:105], off
	s_waitcnt vmcnt(2)
; DI unsigned pack2(float a, float b) { f2 v = {a, b}; bf2 r = __builtin_convertvector(v, bf2); return __builtin_bit_cast(unsigned, r); }
;   DI void operator()(f32x16 (&acc)[2][MB], int wm, int wn, int r, int h) {
;     ...
;     for (int mb = 0; mb < MB; ++mb) {
;       const int tokl = (mb & 1) * 32 + r;
; #pragma unroll
;       for (int nb = 0; nb < 2; ++nb)
; #pragma unroll
;         for (int ig = 0; ig < 4; ++ig) {
;           u32x2 o;
;           o.x = pack2(acc[nb][mb][ig * 4 + 0], acc[nb][mb][ig * 4 + 1]);
;           o.y = pack2(acc[nb][mb][ig * 4 + 2], acc[nb][mb][ig * 4 + 3]);
;           *(u32x2*)(slab + tokl * 72 + nb * 32 + ig * 8 + h * 4) = o;
;         }
;       if ((mb & 1) || mb == MB - 1) {
;         asm volatile("s_waitcnt lgkmcnt(0)" ::: "memory");
;         const int ntok = (mb & 1) ? 64 : 32;
;         const int R0 = row0 + wm * (32 * MB) + (mb >> 1) * 64;
; #pragma unroll
;         for (int j = 0; j < 8; ++j) {
;           const int rowl = (lane >> 3) + 8 * j, ch = lane & 7;
;           if (rowl < ntok) {
;             const u32x4 yv = *(const u32x4*)(slab + rowl * 72 + ch * 8);
;             const int R = R0 + rowl;
;             const int mi = (R < NLAT) ? (R >> 11) : 16;
;             const int col = n0 + wn * 64 + ch * 8;
;             const float* g = gate + (size_t)mi * 6144 + col;
;             const f32x4n g0 = *(const f32x4n*)(g), g1 = *(const f32x4n*)(g + 4);
;             _Float16* xp = X + (size_t)R * 1024 + col;
;             const h8 xv = *(const h8*)xp;
;             const float y[8] = {__uint_as_float(yv.x << 16), __uint_as_float(yv.x & 0xffff0000u), __uint_as_float(yv.y << 16), __uint_as_float(yv.y & 0xffff0000u),
;                                 __uint_as_float(yv.z << 16), __uint_as_float(yv.z & 0xffff0000u), __uint_as_float(yv.w << 16), __uint_as_float(yv.w & 0xffff0000u)};
;             const float gg[8] = {g0.x, g0.y, g0.z, g0.w, g1.x, g1.y, g1.z, g1.w};
;             h8 o;
; #pragma unroll
;             for (int q = 0; q < 8; ++q) o[q] = (_Float16)(ALPHA * (float)xv[q] + gg[q] * y[q]);
;             *(h8*)xp = o;
	v_cvt_f32_f16_e32 v108, v96
	global_load_dwordx4 v[82:85], v[104:105], off offset:16
	v_or_b32_e32 v76, 48, v131
	v_or_b32_e32 v86, s2, v76
	v_min_i32_e32 v77, 0x8000, v86
	v_ashrrev_i32_e32 v87, 31, v86
	v_ashrrev_i32_e32 v77, 11, v77
	v_lshlrev_b64 v[86:87], 11, v[86:87]
	v_cvt_f32_f16_sdwa v109, v96 dst_sel:DWORD dst_unused:UNUSED_PAD src0_sel:WORD_1
	v_cvt_f32_f16_e32 v96, v97
	v_cvt_f32_f16_sdwa v97, v97 dst_sel:DWORD dst_unused:UNUSED_PAD src0_sel:WORD_1
	v_cvt_f32_f16_e32 v110, v98
	v_cvt_f32_f16_sdwa v111, v98 dst_sel:DWORD dst_unused:UNUSED_PAD src0_sel:WORD_1
	v_cvt_f32_f16_e32 v98, v99
	v_cvt_f32_f16_sdwa v99, v99 dst_sel:DWORD dst_unused:UNUSED_PAD src0_sel:WORD_1
	v_mul_hi_i32_i24_e32 v89, 0x6000, v77
	v_mul_i32_i24_e32 v88, 0x6000, v77
	v_lshl_add_u64 v[86:87], s[46:47], 0, v[86:87]
	v_lshl_add_u64 v[88:89], s[8:9], 0, v[88:89]
	v_lshl_add_u64 v[102:103], v[86:87], 0, v[66:67]
	v_lshl_add_u64 v[90:91], v[88:89], 0, v[68:69]
	global_load_dwordx4 v[86:89], v[102:103], off
	v_lshlrev_b32_e32 v104, 16, v92
	v_and_b32_e32 v105, 0xffff0000, v92
	v_lshlrev_b32_e32 v92, 16, v93
	v_and_b32_e32 v93, 0xffff0000, v93
	v_pk_mul_f32 v[108:109], v[108:109], s[30:31] op_sel_hi:[1,0]
	v_pk_mul_f32 v[96:97], v[96:97], s[30:31] op_sel_hi:[1,0]
	v_pk_mul_f32 v[110:111], v[110:111], s[30:31] op_sel_hi:[1,0]
	v_pk_mul_f32 v[98:99], v[98:99], s[30:31] op_sel_hi:[1,0]
	v_or_b32_e32 v77, 56, v131
	s_waitcnt vmcnt(2)
	v_pk_fma_f32 v[78:79], v[78:79], v[104:105], v[108:109]
	v_pk_fma_f32 v[80:81], v[80:81], v[92:93], v[96:97]
	v_cvt_pk_f16_f32 v78, v78, v79
	v_cvt_pk_f16_f32 v79, v80, v81
	s_waitcnt vmcnt(1)
	v_pk_fma_f32 v[82:83], v[82:83], v[106:107], v[110:111]
	v_pk_fma_f32 v[84:85], v[84:85], v[94:95], v[98:99]
	v_cvt_pk_f16_f32 v80, v82, v83
	v_cvt_pk_f16_f32 v81, v84, v85
	global_store_dwordx4 v[100:101], v[78:81], off
	global_load_dwordx4 v[78:81], v[90:91], off
	s_waitcnt vmcnt(2)
	v_cvt_f32_f16_e32 v112, v86
	global_load_dwordx4 v[82:85], v[90:91], off offset:16
	v_or_b32_e32 v90, s2, v77
	v_min_i32_e32 v92, 0x8000, v90
	v_ashrrev_i32_e32 v91, 31, v90
	v_ashrrev_i32_e32 v92, 11, v92
	v_lshlrev_b64 v[90:91], 11, v[90:91]
	v_mul_hi_i32_i24_e32 v93, 0x6000, v92
	v_mul_i32_i24_e32 v92, 0x6000, v92
	v_lshl_add_u64 v[94:95], s[46:47], 0, v[90:91]
	v_lshl_add_u64 v[96:97], s[8:9], 0, v[92:93]
	ds_read_b128 v[90:93], v0 offset:6912
	v_cvt_f32_f16_sdwa v113, v86 dst_sel:DWORD dst_unused:UNUSED_PAD src0_sel:WORD_1
	v_cvt_f32_f16_e32 v86, v87
	v_cvt_f32_f16_sdwa v87, v87 dst_sel:DWORD dst_unused:UNUSED_PAD src0_sel:WORD_1
	v_cvt_f32_f16_e32 v114, v88
	v_cvt_f32_f16_sdwa v115, v88 dst_sel:DWORD dst_unused:UNUSED_PAD src0_sel:WORD_1
	v_cvt_f32_f16_e32 v88, v89
	v_cvt_f32_f16_sdwa v89, v89 dst_sel:DWORD dst_unused:UNUSED_PAD src0_sel:WORD_1
	v_lshl_add_u64 v[104:105], v[94:95], 0, v[66:67]
	global_load_dwordx4 v[98:101], v[104:105], off
	s_waitcnt lgkmcnt(0)
	v_lshlrev_b32_e32 v108, 16, v90
	v_and_b32_e32 v109, 0xffff0000, v90
	v_lshlrev_b32_e32 v90, 16, v91
	v_and_b32_e32 v91, 0xffff0000, v91
	v_lshlrev_b32_e32 v110, 16, v92
	v_and_b32_e32 v111, 0xffff0000, v92
	v_lshlrev_b32_e32 v92, 16, v93
	v_and_b32_e32 v93, 0xffff0000, v93
	v_pk_mul_f32 v[112:113], v[112:113], s[30:31] op_sel_hi:[1,0]
	v_pk_mul_f32 v[86:87], v[86:87], s[30:31] op_sel_hi:[1,0]
	v_pk_mul_f32 v[114:115], v[114:115], s[30:31] op_sel_hi:[1,0]
	v_pk_mul_f32 v[88:89], v[88:89], s[30:31] op_sel_hi:[1,0]
	v_lshl_add_u64 v[106:107], v[96:97], 0, v[68:69]
	ds_read_b128 v[94:97], v0 offset:8064
	ds_write2_b64 v70, v[10:11], v[12:13] offset0:72 offset1:74
	ds_write2_b64 v70, v[14:15], v[16:17] offset0:76 offset1:78
	s_add_i32 s2, s2, 64
	v_or_b32_e32 v34, s2, v131
	ds_write2_b64 v70, v[2:3], v[4:5] offset0:64 offset1:66
	ds_write2_b64 v70, v[6:7], v[8:9] offset0:68 offset1:70
	s_waitcnt lgkmcnt(4)
	v_lshlrev_b32_e32 v2, 16, v94
	v_and_b32_e32 v3, 0xffff0000, v94
	v_lshlrev_b32_e32 v4, 16, v95
	v_and_b32_e32 v5, 0xffff0000, v95
	v_lshlrev_b32_e32 v6, 16, v96
	v_and_b32_e32 v7, 0xffff0000, v96
	v_lshlrev_b32_e32 v8, 16, v97
	v_and_b32_e32 v9, 0xffff0000, v97
	v_ashrrev_i32_e32 v35, 31, v34
	v_lshlrev_b64 v[36:37], 11, v[34:35]
	v_lshl_add_u64 v[36:37], s[46:47], 0, v[36:37]
	ds_write2_b64 v130, v[18:19], v[20:21] offset1:2
	ds_write2_b64 v130, v[22:23], v[24:25] offset0:4 offset1:6
	ds_write2_b64 v130, v[26:27], v[28:29] offset0:8 offset1:10
	ds_write2_b64 v130, v[30:31], v[32:33] offset0:12 offset1:14
	v_lshl_add_u64 v[36:37], v[36:37], 0, v[66:67]
	s_waitcnt vmcnt(2)
	v_pk_fma_f32 v[78:79], v[78:79], v[108:109], v[112:113]
	v_pk_fma_f32 v[80:81], v[80:81], v[90:91], v[86:87]
	v_cvt_pk_f16_f32 v78, v78, v79
	v_cvt_pk_f16_f32 v79, v80, v81
	s_waitcnt vmcnt(1)
	v_pk_fma_f32 v[82:83], v[82:83], v[110:111], v[114:115]
	v_pk_fma_f32 v[84:85], v[84:85], v[92:93], v[88:89]
	v_cvt_pk_f16_f32 v80, v82, v83
	v_cvt_pk_f16_f32 v81, v84, v85
	global_store_dwordx4 v[102:103], v[78:81], off
	global_load_dwordx4 v[78:81], v[106:107], off
	s_waitcnt vmcnt(2)
	v_cvt_f32_f16_e32 v10, v98
	global_load_dwordx4 v[82:85], v[106:107], off offset:16
	v_cvt_f32_f16_sdwa v11, v98 dst_sel:DWORD dst_unused:UNUSED_PAD src0_sel:WORD_1
	v_cvt_f32_f16_e32 v12, v99
	v_cvt_f32_f16_sdwa v13, v99 dst_sel:DWORD dst_unused:UNUSED_PAD src0_sel:WORD_1
	v_cvt_f32_f16_e32 v14, v100
	v_cvt_f32_f16_sdwa v15, v100 dst_sel:DWORD dst_unused:UNUSED_PAD src0_sel:WORD_1
	v_cvt_f32_f16_e32 v16, v101
	v_cvt_f32_f16_sdwa v17, v101 dst_sel:DWORD dst_unused:UNUSED_PAD src0_sel:WORD_1
	v_pk_mul_f32 v[10:11], v[10:11], s[30:31] op_sel_hi:[1,0]
	v_pk_mul_f32 v[12:13], v[12:13], s[30:31] op_sel_hi:[1,0]
	v_pk_mul_f32 v[14:15], v[14:15], s[30:31] op_sel_hi:[1,0]
	v_pk_mul_f32 v[16:17], v[16:17], s[30:31] op_sel_hi:[1,0]
	s_waitcnt vmcnt(1)
;   DI void operator()(f32x16 (&acc)[2][MB], int wm, int wn, int r, int h) {
;     ...
;         for (int j = 0; j < 8; ++j) {
;           const int rowl = (lane >> 3) + 8 * j, ch = lane & 7;
;           if (rowl < ntok) {
;             const u32x4 yv = *(const u32x4*)(slab + rowl * 72 + ch * 8);
;             const int R = R0 + rowl;
;             const int mi = (R < NLAT) ? (R >> 11) : 16;
;             const int col = n0 + wn * 64 + ch * 8;
;             const float* g = gate + (size_t)mi * 6144 + col;
;             const f32x4n g0 = *(const f32x4n*)(g), g1 = *(const f32x4n*)(g + 4);
;             _Float16* xp = X + (size_t)R * 1024 + col;
;             const h8 xv = *(const h8*)xp;
;             const float y[8] = {__uint_as_float(yv.x << 16), __uint_as_float(yv.x & 0xffff0000u), __uint_as_float(yv.y << 16), __uint_as_float(yv.y & 0xffff0000u),
;                                 __uint_as_float(yv.z << 16), __uint_as_float(yv.z & 0xffff0000u), __uint_as_float(yv.w << 16), __uint_as_float(yv.w & 0xffff0000u)};
;             const float gg[8] = {g0.x, g0.y, g0.z, g0.w, g1.x, g1.y, g1.z, g1.w};
;             h8 o;
; #pragma unroll
;             for (int q = 0; q < 8; ++q) o[q] = (_Float16)(ALPHA * (float)xv[q] + gg[q] * y[q]);
;             *(h8*)xp = o;
	v_pk_fma_f32 v[2:3], v[78:79], v[2:3], v[10:11]
	v_pk_fma_f32 v[4:5], v[80:81], v[4:5], v[12:13]
	v_cvt_pk_f16_f32 v2, v2, v3
	v_cvt_pk_f16_f32 v3, v4, v5
	s_waitcnt vmcnt(0)
	v_pk_fma_f32 v[6:7], v[82:83], v[6:7], v[14:15]
	v_pk_fma_f32 v[8:9], v[84:85], v[8:9], v[16:17]
	v_cvt_pk_f16_f32 v4, v6, v7
	v_cvt_pk_f16_f32 v5, v8, v9
	global_store_dwordx4 v[104:105], v[2:5], off
	s_waitcnt lgkmcnt(0)
	global_load_dwordx4 v[2:5], v[36:37], off
	v_min_i32_e32 v6, 0x8000, v34
	v_ashrrev_i32_e32 v6, 11, v6
	v_mul_hi_i32_i24_e32 v7, 0x6000, v6
	v_mul_i32_i24_e32 v6, 0x6000, v6
	v_lshl_add_u64 v[6:7], s[8:9], 0, v[6:7]
	v_lshl_add_u64 v[10:11], v[6:7], 0, v[68:69]
	global_load_dwordx4 v[6:9], v[10:11], off
	v_or_b32_e32 v14, s2, v71
	global_load_dwordx4 v[10:13], v[10:11], off offset:16
	v_min_i32_e32 v16, 0x8000, v14
	v_ashrrev_i32_e32 v15, 31, v14
	v_ashrrev_i32_e32 v16, 11, v16
	v_lshlrev_b64 v[14:15], 11, v[14:15]
	v_mul_hi_i32_i24_e32 v17, 0x6000, v16
	v_mul_i32_i24_e32 v16, 0x6000, v16
	v_lshl_add_u64 v[18:19], s[46:47], 0, v[14:15]
	v_lshl_add_u64 v[20:21], s[8:9], 0, v[16:17]
	ds_read_b128 v[14:17], v0
	v_lshl_add_u64 v[26:27], v[18:19], 0, v[66:67]
	global_load_dwordx4 v[22:25], v[26:27], off
	v_lshl_add_u64 v[28:29], v[20:21], 0, v[68:69]
	ds_read_b128 v[18:21], v0 offset:1152
	s_waitcnt lgkmcnt(1)
	v_lshlrev_b32_e32 v30, 16, v14
	v_and_b32_e32 v31, 0xffff0000, v14
	v_lshlrev_b32_e32 v14, 16, v15
	v_and_b32_e32 v15, 0xffff0000, v15
	v_lshlrev_b32_e32 v32, 16, v16
	v_and_b32_e32 v33, 0xffff0000, v16
	v_lshlrev_b32_e32 v16, 16, v17
	v_and_b32_e32 v17, 0xffff0000, v17
	s_waitcnt vmcnt(3)
	v_cvt_f32_f16_e32 v34, v2
	v_cvt_f32_f16_sdwa v35, v2 dst_sel:DWORD dst_unused:UNUSED_PAD src0_sel:WORD_1
	v_cvt_f32_f16_e32 v2, v3
	v_cvt_f32_f16_sdwa v3, v3 dst_sel:DWORD dst_unused:UNUSED_PAD src0_sel:WORD_1
	v_cvt_f32_f16_e32 v38, v4
	v_cvt_f32_f16_sdwa v39, v4 dst_sel:DWORD dst_unused:UNUSED_PAD src0_sel:WORD_1
	v_cvt_f32_f16_e32 v4, v5
	v_cvt_f32_f16_sdwa v5, v5 dst_sel:DWORD dst_unused:UNUSED_PAD src0_sel:WORD_1
	v_pk_mul_f32 v[34:35], v[34:35], s[30:31] op_sel_hi:[1,0]
	v_pk_mul_f32 v[2:3], v[2:3], s[30:31] op_sel_hi:[1,0]
	v_pk_mul_f32 v[38:39], v[38:39], s[30:31] op_sel_hi:[1,0]
	v_pk_mul_f32 v[4:5], v[4:5], s[30:31] op_sel_hi:[1,0]
	s_waitcnt vmcnt(2)
	v_pk_fma_f32 v[6:7], v[6:7], v[30:31], v[34:35]
	v_pk_fma_f32 v[8:9], v[8:9], v[14:15], v[2:3]
	s_waitcnt vmcnt(1)
	v_pk_fma_f32 v[10:11], v[10:11], v[32:33], v[38:39]
	v_pk_fma_f32 v[12:13], v[12:13], v[16:17], v[4:5]
	v_cvt_pk_f16_f32 v2, v6, v7
	v_cvt_pk_f16_f32 v3, v8, v9
	v_cvt_pk_f16_f32 v4, v10, v11
	v_cvt_pk_f16_f32 v5, v12, v13
	global_store_dwordx4 v[36:37], v[2:5], off
	global_load_dwordx4 v[2:5], v[28:29], off
	v_or_b32_e32 v10, s2, v72
	global_load_dwordx4 v[6:9], v[28:29], off offset:16
	v_min_i32_e32 v12, 0x8000, v10
	v_ashrrev_i32_e32 v11, 31, v10
	v_ashrrev_i32_e32 v12, 11, v12
	v_lshlrev_b64 v[10:11], 11, v[10:11]
	s_waitcnt vmcnt(3)
	v_cvt_f32_f16_e32 v32, v22
	v_cvt_f32_f16_sdwa v33, v22 dst_sel:DWORD dst_unused:UNUSED_PAD src0_sel:WORD_1
	v_cvt_f32_f16_e32 v22, v23
	v_cvt_f32_f16_sdwa v23, v23 dst_sel:DWORD dst_unused:UNUSED_PAD src0_sel:WORD_1
	v_cvt_f32_f16_e32 v34, v24
	v_cvt_f32_f16_sdwa v35, v24 dst_sel:DWORD dst_unused:UNUSED_PAD src0_sel:WORD_1
	v_cvt_f32_f16_e32 v24, v25
	v_cvt_f32_f16_sdwa v25, v25 dst_sel:DWORD dst_unused:UNUSED_PAD src0_sel:WORD_1
	v_mul_hi_i32_i24_e32 v13, 0x6000, v12
	v_mul_i32_i24_e32 v12, 0x6000, v12
	v_lshl_add_u64 v[10:11], s[46:47], 0, v[10:11]
	v_lshl_add_u64 v[12:13], s[8:9], 0, v[12:13]
	v_lshl_add_u64 v[28:29], v[10:11], 0, v[66:67]
	v_lshl_add_u64 v[14:15], v[12:13], 0, v[68:69]
	global_load_dwordx4 v[10:13], v[28:29], off
	s_waitcnt lgkmcnt(0)
	v_lshlrev_b32_e32 v16, 16, v18
	v_and_b32_e32 v17, 0xffff0000, v18
	v_lshlrev_b32_e32 v18, 16, v19
	v_and_b32_e32 v19, 0xffff0000, v19
	v_lshlrev_b32_e32 v30, 16, v20
	v_and_b32_e32 v31, 0xffff0000, v20
	v_lshlrev_b32_e32 v20, 16, v21
	v_and_b32_e32 v21, 0xffff0000, v21
	v_pk_mul_f32 v[32:33], v[32:33], s[30:31] op_sel_hi:[1,0]
	v_pk_mul_f32 v[22:23], v[22:23], s[30:31] op_sel_hi:[1,0]
	v_pk_mul_f32 v[34:35], v[34:35], s[30:31] op_sel_hi:[1,0]
	v_pk_mul_f32 v[24:25], v[24:25], s[30:31] op_sel_hi:[1,0]
	s_waitcnt vmcnt(2)
	v_pk_fma_f32 v[2:3], v[2:3], v[16:17], v[32:33]
	v_pk_fma_f32 v[4:5], v[4:5], v[18:19], v[22:23]
	s_waitcnt vmcnt(1)
	v_pk_fma_f32 v[6:7], v[6:7], v[30:31], v[34:35]
	v_pk_fma_f32 v[8:9], v[8:9], v[20:21], v[24:25]
	v_cvt_pk_f16_f32 v2, v2, v3
	v_cvt_pk_f16_f32 v3, v4, v5
	v_cvt_pk_f16_f32 v4, v6, v7
	v_cvt_pk_f16_f32 v5, v8, v9
	global_store_dwordx4 v[26:27], v[2:5], off
	global_load_dwordx4 v[2:5], v[14:15], off
	s_waitcnt vmcnt(2)
	v_cvt_f32_f16_e32 v36, v10
	global_load_dwordx4 v[6:9], v[14:15], off offset:16
	v_or_b32_e32 v14, s2, v73
	v_min_i32_e32 v16, 0x8000, v14
	v_ashrrev_i32_e32 v15, 31, v14
	v_ashrrev_i32_e32 v16, 11, v16
	v_lshlrev_b64 v[14:15], 11, v[14:15]
	v_mul_hi_i32_i24_e32 v17, 0x6000, v16
	v_mul_i32_i24_e32 v16, 0x6000, v16
	v_lshl_add_u64 v[18:19], s[46:47], 0, v[14:15]
	v_lshl_add_u64 v[20:21], s[8:9], 0, v[16:17]
	ds_read_b128 v[14:17], v0 offset:2304
	v_cvt_f32_f16_sdwa v37, v10 dst_sel:DWORD dst_unused:UNUSED_PAD src0_sel:WORD_1
	v_cvt_f32_f16_e32 v10, v11
	v_cvt_f32_f16_sdwa v11, v11 dst_sel:DWORD dst_unused:UNUSED_PAD src0_sel:WORD_1
	v_cvt_f32_f16_e32 v38, v12
	v_cvt_f32_f16_sdwa v39, v12 dst_sel:DWORD dst_unused:UNUSED_PAD src0_sel:WORD_1
	v_cvt_f32_f16_e32 v12, v13
	v_cvt_f32_f16_sdwa v13, v13 dst_sel:DWORD dst_unused:UNUSED_PAD src0_sel:WORD_1
	v_lshl_add_u64 v[26:27], v[18:19], 0, v[66:67]
	global_load_dwordx4 v[22:25], v[26:27], off
	s_waitcnt lgkmcnt(0)
;   DI void operator()(f32x16 (&acc)[2][MB], int wm, int wn, int r, int h) {
;     ...
;         for (int j = 0; j < 8; ++j) {
;           const int rowl = (lane >> 3) + 8 * j, ch = lane & 7;
;           if (rowl < ntok) {
;             const u32x4 yv = *(const u32x4*)(slab + rowl * 72 + ch * 8);
;             const int R = R0 + rowl;
;             const int mi = (R < NLAT) ? (R >> 11) : 16;
;             const int col = n0 + wn * 64 + ch * 8;
;             const float* g = gate + (size_t)mi * 6144 + col;
;             const f32x4n g0 = *(const f32x4n*)(g), g1 = *(const f32x4n*)(g + 4);
;             _Float16* xp = X + (size_t)R * 1024 + col;
;             const h8 xv = *(const h8*)xp;
;             const float y[8] = {__uint_as_float(yv.x << 16), __uint_as_float(yv.x & 0xffff0000u), __uint_as_float(yv.y << 16), __uint_as_float(yv.y & 0xffff0000u),
;                                 __uint_as_float(yv.z << 16), __uint_as_float(yv.z & 0xffff0000u), __uint_as_float(yv.w << 16), __uint_as_float(yv.w & 0xffff0000u)};
;             const float gg[8] = {g0.x, g0.y, g0.z, g0.w, g1.x, g1.y, g1.z, g1.w};
;             h8 o;
; #pragma unroll
;             for (int q = 0; q < 8; ++q) o[q] = (_Float16)(ALPHA * (float)xv[q] + gg[q] * y[q]);
;             *(h8*)xp = o;
	v_lshlrev_b32_e32 v32, 16, v14
	v_and_b32_e32 v33, 0xffff0000, v14
	v_lshlrev_b32_e32 v14, 16, v15
	v_and_b32_e32 v15, 0xffff0000, v15
	v_lshlrev_b32_e32 v34, 16, v16
	v_and_b32_e32 v35, 0xffff0000, v16
	v_lshlrev_b32_e32 v16, 16, v17
	v_and_b32_e32 v17, 0xffff0000, v17
	v_pk_mul_f32 v[36:37], v[36:37], s[30:31] op_sel_hi:[1,0]
	v_pk_mul_f32 v[10:11], v[10:11], s[30:31] op_sel_hi:[1,0]
	v_pk_mul_f32 v[38:39], v[38:39], s[30:31] op_sel_hi:[1,0]
	v_pk_mul_f32 v[12:13], v[12:13], s[30:31] op_sel_hi:[1,0]
	v_lshl_add_u64 v[30:31], v[20:21], 0, v[68:69]
	ds_read_b128 v[18:21], v0 offset:3456
	s_waitcnt vmcnt(2)
	v_pk_fma_f32 v[2:3], v[2:3], v[32:33], v[36:37]
	v_pk_fma_f32 v[4:5], v[4:5], v[14:15], v[10:11]
	v_cvt_pk_f16_f32 v2, v2, v3
	v_cvt_pk_f16_f32 v3, v4, v5
	v_or_b32_e32 v10, s2, v74
	v_ashrrev_i32_e32 v11, 31, v10
	s_waitcnt vmcnt(1)
	v_pk_fma_f32 v[6:7], v[6:7], v[34:35], v[38:39]
	v_pk_fma_f32 v[8:9], v[8:9], v[16:17], v[12:13]
	v_cvt_pk_f16_f32 v4, v6, v7
	v_cvt_pk_f16_f32 v5, v8, v9
	global_store_dwordx4 v[28:29], v[2:5], off
	global_load_dwordx4 v[2:5], v[30:31], off
	v_min_i32_e32 v12, 0x8000, v10
	global_load_dwordx4 v[6:9], v[30:31], off offset:16
	v_ashrrev_i32_e32 v12, 11, v12
	v_lshlrev_b64 v[10:11], 11, v[10:11]
	v_mul_hi_i32_i24_e32 v13, 0x6000, v12
	v_mul_i32_i24_e32 v12, 0x6000, v12
	v_lshl_add_u64 v[10:11], s[46:47], 0, v[10:11]
	v_lshl_add_u64 v[12:13], s[8:9], 0, v[12:13]
	v_lshl_add_u64 v[28:29], v[10:11], 0, v[66:67]
	v_lshl_add_u64 v[14:15], v[12:13], 0, v[68:69]
	global_load_dwordx4 v[10:13], v[28:29], off
	s_waitcnt lgkmcnt(0)
	v_lshlrev_b32_e32 v16, 16, v18
	v_and_b32_e32 v17, 0xffff0000, v18
	s_waitcnt vmcnt(4)
	v_cvt_f32_f16_e32 v32, v22
	v_cvt_f32_f16_sdwa v33, v22 dst_sel:DWORD dst_unused:UNUSED_PAD src0_sel:WORD_1
	v_cvt_f32_f16_e32 v22, v23
	v_cvt_f32_f16_sdwa v23, v23 dst_sel:DWORD dst_unused:UNUSED_PAD src0_sel:WORD_1
	v_cvt_f32_f16_e32 v34, v24
	v_cvt_f32_f16_sdwa v35, v24 dst_sel:DWORD dst_unused:UNUSED_PAD src0_sel:WORD_1
	v_cvt_f32_f16_e32 v24, v25
	v_cvt_f32_f16_sdwa v25, v25 dst_sel:DWORD dst_unused:UNUSED_PAD src0_sel:WORD_1
	v_lshlrev_b32_e32 v18, 16, v19
	v_and_b32_e32 v19, 0xffff0000, v19
	v_lshlrev_b32_e32 v30, 16, v20
	v_and_b32_e32 v31, 0xffff0000, v20
	v_lshlrev_b32_e32 v20, 16, v21
	v_and_b32_e32 v21, 0xffff0000, v21
	v_pk_mul_f32 v[32:33], v[32:33], s[30:31] op_sel_hi:[1,0]
	v_pk_mul_f32 v[22:23], v[22:23], s[30:31] op_sel_hi:[1,0]
	v_pk_mul_f32 v[34:35], v[34:35], s[30:31] op_sel_hi:[1,0]
	v_pk_mul_f32 v[24:25], v[24:25], s[30:31] op_sel_hi:[1,0]
	s_waitcnt vmcnt(2)
	v_pk_fma_f32 v[2:3], v[2:3], v[16:17], v[32:33]
	v_pk_fma_f32 v[4:5], v[4:5], v[18:19], v[22:23]
	s_waitcnt vmcnt(1)
	v_pk_fma_f32 v[6:7], v[6:7], v[30:31], v[34:35]
	v_pk_fma_f32 v[8:9], v[8:9], v[20:21], v[24:25]
	v_cvt_pk_f16_f32 v2, v2, v3
	v_cvt_pk_f16_f32 v3, v4, v5
	v_cvt_pk_f16_f32 v4, v6, v7
	v_cvt_pk_f16_f32 v5, v8, v9
	global_store_dwordx4 v[26:27], v[2:5], off
	global_load_dwordx4 v[2:5], v[14:15], off
	s_waitcnt vmcnt(2)
	v_cvt_f32_f16_e32 v36, v10
	global_load_dwordx4 v[6:9], v[14:15], off offset:16
	v_or_b32_e32 v14, s2, v75
	v_min_i32_e32 v16, 0x8000, v14
	v_ashrrev_i32_e32 v15, 31, v14
	v_ashrrev_i32_e32 v16, 11, v16
	v_lshlrev_b64 v[14:15], 11, v[14:15]
	v_mul_hi_i32_i24_e32 v17, 0x6000, v16
	v_mul_i32_i24_e32 v16, 0x6000, v16
	v_lshl_add_u64 v[18:19], s[46:47], 0, v[14:15]
	v_lshl_add_u64 v[20:21], s[8:9], 0, v[16:17]
	ds_read_b128 v[14:17], v0 offset:4608
	v_cvt_f32_f16_sdwa v37, v10 dst_sel:DWORD dst_unused:UNUSED_PAD src0_sel:WORD_1
	v_cvt_f32_f16_e32 v10, v11
	v_cvt_f32_f16_sdwa v11, v11 dst_sel:DWORD dst_unused:UNUSED_PAD src0_sel:WORD_1
	v_cvt_f32_f16_e32 v38, v12
	v_cvt_f32_f16_sdwa v39, v12 dst_sel:DWORD dst_unused:UNUSED_PAD src0_sel:WORD_1
	v_cvt_f32_f16_e32 v12, v13
	v_cvt_f32_f16_sdwa v13, v13 dst_sel:DWORD dst_unused:UNUSED_PAD src0_sel:WORD_1
	v_lshl_add_u64 v[26:27], v[18:19], 0, v[66:67]
	global_load_dwordx4 v[22:25], v[26:27], off
	s_waitcnt lgkmcnt(0)
	v_lshlrev_b32_e32 v32, 16, v14
	v_and_b32_e32 v33, 0xffff0000, v14
	v_lshlrev_b32_e32 v14, 16, v15
	v_and_b32_e32 v15, 0xffff0000, v15
	v_lshlrev_b32_e32 v34, 16, v16
	v_and_b32_e32 v35, 0xffff0000, v16
	v_lshlrev_b32_e32 v16, 16, v17
	v_and_b32_e32 v17, 0xffff0000, v17
	v_pk_mul_f32 v[36:37], v[36:37], s[30:31] op_sel_hi:[1,0]
	v_pk_mul_f32 v[10:11], v[10:11], s[30:31] op_sel_hi:[1,0]
	v_pk_mul_f32 v[38:39], v[38:39], s[30:31] op_sel_hi:[1,0]
	v_pk_mul_f32 v[12:13], v[12:13], s[30:31] op_sel_hi:[1,0]
	v_lshl_add_u64 v[30:31], v[20:21], 0, v[68:69]
	ds_read_b128 v[18:21], v0 offset:5760
	s_waitcnt vmcnt(2)
	v_pk_fma_f32 v[2:3], v[2:3], v[32:33], v[36:37]
	v_pk_fma_f32 v[4:5], v[4:5], v[14:15], v[10:11]
	v_cvt_pk_f16_f32 v2, v2, v3
	s_waitcnt vmcnt(1)
	v_pk_fma_f32 v[6:7], v[6:7], v[34:35], v[38:39]
	v_pk_fma_f32 v[8:9], v[8:9], v[16:17], v[12:13]
	v_cvt_pk_f16_f32 v3, v4, v5
	v_cvt_pk_f16_f32 v4, v6, v7
	v_cvt_pk_f16_f32 v5, v8, v9
	global_store_dwordx4 v[28:29], v[2:5], off
	global_load_dwordx4 v[2:5], v[30:31], off
	v_or_b32_e32 v10, s2, v76
	global_load_dwordx4 v[6:9], v[30:31], off offset:16
	v_min_i32_e32 v12, 0x8000, v10
	v_ashrrev_i32_e32 v11, 31, v10
	v_ashrrev_i32_e32 v12, 11, v12
	v_lshlrev_b64 v[10:11], 11, v[10:11]
	v_mul_hi_i32_i24_e32 v13, 0x6000, v12
	v_mul_i32_i24_e32 v12, 0x6000, v12
	v_lshl_add_u64 v[10:11], s[46:47], 0, v[10:11]
	v_lshl_add_u64 v[12:13], s[8:9], 0, v[12:13]
	v_lshl_add_u64 v[28:29], v[10:11], 0, v[66:67]
	v_lshl_add_u64 v[14:15], v[12:13], 0, v[68:69]
	s_waitcnt vmcnt(3)
;   DI void operator()(f32x16 (&acc)[2][MB], int wm, int wn, int r, int h) {
;     ...
;         for (int j = 0; j < 8; ++j) {
;           const int rowl = (lane >> 3) + 8 * j, ch = lane & 7;
;           if (rowl < ntok) {
;             const u32x4 yv = *(const u32x4*)(slab + rowl * 72 + ch * 8);
;             const int R = R0 + rowl;
;             const int mi = (R < NLAT) ? (R >> 11) : 16;
;             const int col = n0 + wn * 64 + ch * 8;
;             const float* g = gate + (size_t)mi * 6144 + col;
;             const f32x4n g0 = *(const f32x4n*)(g), g1 = *(const f32x4n*)(g + 4);
;             _Float16* xp = X + (size_t)R * 1024 + col;
;             const h8 xv = *(const h8*)xp;
;             const float y[8] = {__uint_as_float(yv.x << 16), __uint_as_float(yv.x & 0xffff0000u), __uint_as_float(yv.y << 16), __uint_as_float(yv.y & 0xffff0000u),
;                                 __uint_as_float(yv.z << 16), __uint_as_float(yv.z & 0xffff0000u), __uint_as_float(yv.w << 16), __uint_as_float(yv.w & 0xffff0000u)};
;             const float gg[8] = {g0.x, g0.y, g0.z, g0.w, g1.x, g1.y, g1.z, g1.w};
;             h8 o;
; #pragma unroll
;             for (int q = 0; q < 8; ++q) o[q] = (_Float16)(ALPHA * (float)xv[q] + gg[q] * y[q]);
;             *(h8*)xp = o;
;           }
;         }
;       }
;     }
;     __syncthreads();
	v_cvt_f32_f16_e32 v32, v22
	v_cvt_f32_f16_sdwa v33, v22 dst_sel:DWORD dst_unused:UNUSED_PAD src0_sel:WORD_1
	v_cvt_f32_f16_e32 v22, v23
	v_cvt_f32_f16_sdwa v23, v23 dst_sel:DWORD dst_unused:UNUSED_PAD src0_sel:WORD_1
	v_cvt_f32_f16_e32 v34, v24
	v_cvt_f32_f16_sdwa v35, v24 dst_sel:DWORD dst_unused:UNUSED_PAD src0_sel:WORD_1
	v_cvt_f32_f16_e32 v24, v25
	v_cvt_f32_f16_sdwa v25, v25 dst_sel:DWORD dst_unused:UNUSED_PAD src0_sel:WORD_1
	global_load_dwordx4 v[10:13], v[28:29], off
	s_waitcnt lgkmcnt(0)
	v_lshlrev_b32_e32 v16, 16, v18
	v_and_b32_e32 v17, 0xffff0000, v18
	v_lshlrev_b32_e32 v18, 16, v19
	v_and_b32_e32 v19, 0xffff0000, v19
	v_lshlrev_b32_e32 v30, 16, v20
	v_and_b32_e32 v31, 0xffff0000, v20
	v_lshlrev_b32_e32 v20, 16, v21
	v_and_b32_e32 v21, 0xffff0000, v21
	v_pk_mul_f32 v[32:33], v[32:33], s[30:31] op_sel_hi:[1,0]
	v_pk_mul_f32 v[22:23], v[22:23], s[30:31] op_sel_hi:[1,0]
	v_pk_mul_f32 v[34:35], v[34:35], s[30:31] op_sel_hi:[1,0]
	v_pk_mul_f32 v[24:25], v[24:25], s[30:31] op_sel_hi:[1,0]
	s_waitcnt vmcnt(2)
	v_pk_fma_f32 v[2:3], v[2:3], v[16:17], v[32:33]
	v_pk_fma_f32 v[4:5], v[4:5], v[18:19], v[22:23]
	s_waitcnt vmcnt(1)
	v_pk_fma_f32 v[6:7], v[6:7], v[30:31], v[34:35]
	v_pk_fma_f32 v[8:9], v[8:9], v[20:21], v[24:25]
	v_cvt_pk_f16_f32 v2, v2, v3
	v_cvt_pk_f16_f32 v3, v4, v5
	v_cvt_pk_f16_f32 v4, v6, v7
	v_cvt_pk_f16_f32 v5, v8, v9
	global_store_dwordx4 v[26:27], v[2:5], off
	global_load_dwordx4 v[2:5], v[14:15], off
	s_waitcnt vmcnt(2)
	v_cvt_f32_f16_e32 v36, v10
	global_load_dwordx4 v[6:9], v[14:15], off offset:16
	v_or_b32_e32 v14, s2, v77
	v_min_i32_e32 v16, 0x8000, v14
	v_ashrrev_i32_e32 v15, 31, v14
	v_ashrrev_i32_e32 v16, 11, v16
	v_lshlrev_b64 v[14:15], 11, v[14:15]
	v_mul_hi_i32_i24_e32 v17, 0x6000, v16
	v_mul_i32_i24_e32 v16, 0x6000, v16
	v_lshl_add_u64 v[18:19], s[46:47], 0, v[14:15]
	v_lshl_add_u64 v[20:21], s[8:9], 0, v[16:17]
	ds_read_b128 v[14:17], v0 offset:6912
	v_cvt_f32_f16_sdwa v37, v10 dst_sel:DWORD dst_unused:UNUSED_PAD src0_sel:WORD_1
	v_cvt_f32_f16_e32 v10, v11
	v_cvt_f32_f16_sdwa v11, v11 dst_sel:DWORD dst_unused:UNUSED_PAD src0_sel:WORD_1
	v_cvt_f32_f16_e32 v38, v12
	v_cvt_f32_f16_sdwa v39, v12 dst_sel:DWORD dst_unused:UNUSED_PAD src0_sel:WORD_1
	v_cvt_f32_f16_e32 v12, v13
	v_cvt_f32_f16_sdwa v13, v13 dst_sel:DWORD dst_unused:UNUSED_PAD src0_sel:WORD_1
	v_lshl_add_u64 v[26:27], v[18:19], 0, v[66:67]
	global_load_dwordx4 v[22:25], v[26:27], off
	s_waitcnt lgkmcnt(0)
	v_lshlrev_b32_e32 v32, 16, v14
	v_and_b32_e32 v33, 0xffff0000, v14
	v_lshlrev_b32_e32 v14, 16, v15
	v_and_b32_e32 v15, 0xffff0000, v15
	v_lshlrev_b32_e32 v34, 16, v16
	v_and_b32_e32 v35, 0xffff0000, v16
	v_lshlrev_b32_e32 v16, 16, v17
	v_and_b32_e32 v17, 0xffff0000, v17
	v_pk_mul_f32 v[36:37], v[36:37], s[30:31] op_sel_hi:[1,0]
	v_pk_mul_f32 v[10:11], v[10:11], s[30:31] op_sel_hi:[1,0]
	v_pk_mul_f32 v[38:39], v[38:39], s[30:31] op_sel_hi:[1,0]
	v_pk_mul_f32 v[12:13], v[12:13], s[30:31] op_sel_hi:[1,0]
	v_lshl_add_u64 v[30:31], v[20:21], 0, v[68:69]
	ds_read_b128 v[18:21], v0 offset:8064
	s_waitcnt vmcnt(2)
	v_pk_fma_f32 v[2:3], v[2:3], v[32:33], v[36:37]
	v_pk_fma_f32 v[4:5], v[4:5], v[14:15], v[10:11]
	v_cvt_pk_f16_f32 v2, v2, v3
	v_cvt_pk_f16_f32 v3, v4, v5
	s_waitcnt lgkmcnt(0)
	v_lshlrev_b32_e32 v10, 16, v18
	v_and_b32_e32 v11, 0xffff0000, v18
	v_lshlrev_b32_e32 v14, 16, v20
	v_and_b32_e32 v15, 0xffff0000, v20
	s_waitcnt vmcnt(1)
	v_pk_fma_f32 v[6:7], v[6:7], v[34:35], v[38:39]
	v_pk_fma_f32 v[8:9], v[8:9], v[16:17], v[12:13]
	v_cvt_pk_f16_f32 v4, v6, v7
	v_cvt_pk_f16_f32 v5, v8, v9
	global_store_dwordx4 v[28:29], v[2:5], off
	global_load_dwordx4 v[2:5], v[30:31], off
	v_lshlrev_b32_e32 v12, 16, v19
	global_load_dwordx4 v[6:9], v[30:31], off offset:16
	v_and_b32_e32 v13, 0xffff0000, v19
	v_lshlrev_b32_e32 v16, 16, v21
	v_and_b32_e32 v17, 0xffff0000, v21
	s_waitcnt vmcnt(3)
	v_cvt_f32_f16_e32 v18, v22
	v_cvt_f32_f16_sdwa v19, v22 dst_sel:DWORD dst_unused:UNUSED_PAD src0_sel:WORD_1
	v_cvt_f32_f16_e32 v20, v23
	v_cvt_f32_f16_sdwa v21, v23 dst_sel:DWORD dst_unused:UNUSED_PAD src0_sel:WORD_1
	v_cvt_f32_f16_e32 v22, v24
	v_cvt_f32_f16_sdwa v23, v24 dst_sel:DWORD dst_unused:UNUSED_PAD src0_sel:WORD_1
	v_cvt_f32_f16_e32 v24, v25
	v_cvt_f32_f16_sdwa v25, v25 dst_sel:DWORD dst_unused:UNUSED_PAD src0_sel:WORD_1
	v_pk_mul_f32 v[18:19], v[18:19], s[30:31] op_sel_hi:[1,0]
	v_pk_mul_f32 v[20:21], v[20:21], s[30:31] op_sel_hi:[1,0]
	v_pk_mul_f32 v[22:23], v[22:23], s[30:31] op_sel_hi:[1,0]
	v_pk_mul_f32 v[24:25], v[24:25], s[30:31] op_sel_hi:[1,0]
	s_waitcnt vmcnt(1)
	v_pk_fma_f32 v[2:3], v[2:3], v[10:11], v[18:19]
	v_pk_fma_f32 v[4:5], v[4:5], v[12:13], v[20:21]
	s_waitcnt vmcnt(0)
	v_pk_fma_f32 v[6:7], v[6:7], v[14:15], v[22:23]
	v_pk_fma_f32 v[8:9], v[8:9], v[16:17], v[24:25]
	v_cvt_pk_f16_f32 v2, v2, v3
	v_cvt_pk_f16_f32 v3, v4, v5
	v_cvt_pk_f16_f32 v4, v6, v7
	v_cvt_pk_f16_f32 v5, v8, v9
	global_store_dwordx4 v[26:27], v[2:5], off
	s_barrier
	s_branch .LBB0_861

; __global__ void __launch_bounds__(512, 2) fwd_megakernel(Params p, int ph_lo, int ph_hi) {
;   __shared__ __attribute__((aligned(16))) char smem[SMEM_BYTES];
;   __shared__ __attribute__((aligned(16))) unsigned xb_words[4];
	.amdhsa_kernel _Z14fwd_megakernel6Paramsii
		.amdhsa_group_segment_fixed_size 135184
		.amdhsa_private_segment_fixed_size 0
		.amdhsa_kernarg_size 440
		.amdhsa_user_sgpr_count 2
		.amdhsa_user_sgpr_dispatch_ptr 0
		.amdhsa_user_sgpr_queue_ptr 0
		.amdhsa_user_sgpr_kernarg_segment_ptr 1
		.amdhsa_user_sgpr_dispatch_id 0
		.amdhsa_user_sgpr_kernarg_preload_length 0
		.amdhsa_user_sgpr_kernarg_preload_offset 0
		.amdhsa_user_sgpr_private_segment_size 0
		.amdhsa_uses_dynamic_stack 0
		.amdhsa_enable_private_segment 0
		.amdhsa_system_sgpr_workgroup_id_x 1
		.amdhsa_system_sgpr_workgroup_id_y 0
		.amdhsa_system_sgpr_workgroup_id_z 0
		.amdhsa_system_sgpr_workgroup_info 0
		.amdhsa_system_vgpr_workitem_id 2
		.amdhsa_next_free_vgpr 256
		.amdhsa_next_free_sgpr 102
		.amdhsa_accum_offset 256
		.amdhsa_reserve_vcc 1
		.amdhsa_float_round_mode_32 0
		.amdhsa_float_round_mode_16_64 0
		.amdhsa_float_denorm_mode_32 3
		.amdhsa_float_denorm_mode_16_64 3
		.amdhsa_dx10_clamp 1
		.amdhsa_ieee_mode 1
		.amdhsa_fp16_overflow 0
		.amdhsa_tg_split 0
		.amdhsa_exception_fp_ieee_invalid_op 0
		.amdhsa_exception_fp_denorm_src 0
		.amdhsa_exception_fp_ieee_div_zero 0
		.amdhsa_exception_fp_ieee_overflow 0
		.amdhsa_exception_fp_ieee_underflow 0
		.amdhsa_exception_fp_ieee_inexact 0
		.amdhsa_exception_int_div_zero 0
	.end_amdhsa_kernel

; __global__ void __launch_bounds__(512, 2) fwd_megakernel(Params p, int ph_lo, int ph_hi) {
;   __shared__ __attribute__((aligned(16))) char smem[SMEM_BYTES];
;   __shared__ __attribute__((aligned(16))) unsigned xb_words[4];
amdhsa.kernels:
  - .agpr_count:     0
    .args:
      - .offset:         0
        .size:           176
        .value_kind:     by_value
      - .offset:         176
        .size:           4
        .value_kind:     by_value
      - .offset:         180
        .size:           4
        .value_kind:     by_value
      - .offset:         184
        .size:           4
        .value_kind:     hidden_block_count_x
      - .offset:         188
        .size:           4
        .value_kind:     hidden_block_count_y
      - .offset:         192
        .size:           4
        .value_kind:     hidden_block_count_z
      - .offset:         196
        .size:           2
        .value_kind:     hidden_group_size_x
      - .offset:         198
        .size:           2
        .value_kind:     hidden_group_size_y
      - .offset:         200
        .size:           2
        .value_kind:     hidden_group_size_z
      - .offset:         202
        .size:           2
        .value_kind:     hidden_remainder_x
      - .offset:         204
        .size:           2
        .value_kind:     hidden_remainder_y
      - .offset:         206
        .size:           2
        .value_kind:     hidden_remainder_z
      - .offset:         224
        .size:           8
        .value_kind:     hidden_global_offset_x
      - .offset:         232
        .size:           8
        .value_kind:     hidden_global_offset_y
      - .offset:         240
        .size:           8
        .value_kind:     hidden_global_offset_z
      - .offset:         248
        .size:           2
        .value_kind:     hidden_grid_dims
      - .offset:         272
        .size:           8
        .value_kind:     hidden_multigrid_sync_arg
    .group_segment_fixed_size: 135184
    .kernarg_segment_align: 8
    .kernarg_segment_size: 440
    .language:       OpenCL C
    .language_version:
      - 2
      - 0
    .max_flat_workgroup_size: 512
    .name:           _Z14fwd_megakernel6Paramsii
    .private_segment_fixed_size: 0
    .sgpr_count:     108
    .sgpr_spill_count: 179
    .symbol:         _Z14fwd_megakernel6Paramsii.kd
    .uniform_work_group_size: 1
    .uses_dynamic_stack: false
    .vgpr_count:     256
    .vgpr_spill_count: 0
    .wavefront_size: 64
